# P4 K-loops regenerated by hand: deep 2-tile register prefetch (dead VGPRs + SGPR-base loads), loads/ds_writes interleaved in MFMA chain
# speedup vs baseline: 1.0888x; 1.0185x over previous
; #define GEMM_GLOAD(P, kt_) { GEMM_GL1(P, 0, kt_) GEMM_GL1(P, 1, kt_) GEMM_GL1(P, 2, kt_) GEMM_GL1(P, 3, kt_) }
; #define GEMM_LSTORE(P, buf_) { GEMM_LS1(P, 0, buf_) GEMM_LS1(P, 1, buf_) GEMM_LS1(P, 2, buf_) GEMM_LS1(P, 3, buf_) }
; template <bool DEEP>
; DI void gemm_mainloop_t(const u16* __restrict__ Ag, int lda, const u16* __restrict__ Bg, int ldb, int K, char* ldsraw,
;                         f32x16 (&acc)[2][2], int akstep) {
;     ...
;   } else {
;     GEMM_GLOAD(x, 0);
;     GEMM_LSTORE(x, 0);
;     __syncthreads();
;     for (int kt = 0; kt < nk; kt += 2) {
;       GEMM_GLOAD(x, kt + 1);
;       GEMM_COMPUTE(0);
;       GEMM_LSTORE(x, 1);
;       __syncthreads();
;       if (kt + 2 < nk) GEMM_GLOAD(x, kt + 2);
;       GEMM_COMPUTE(1);
;       if (kt + 2 < nk) GEMM_LSTORE(x, 0);
;       __syncthreads();
;     }
.LBB0_1054:
	s_lshl_b64 s[8:9], s[8:9], 1
	s_add_u32 s8, s20, s8
	s_addc_u32 s9, s21, s9
	v_lshrrev_b32_e32 v244, 3, v209
	v_and_b32_e32 v245, 7, v209
	v_lshlrev_b32_e32 v245, 4, v245
	v_mov_b32_e32 v246, v244
	v_mul_u32_u24_e32 v206, 0x3300, v246
	v_add_u32_e32 v206, v206, v245
	v_mul_u32_u24_e32 v248, 0x400, v246
	v_add_u32_e32 v248, v248, v245
	v_add_u32_e32 v246, 32, v244
	v_mul_u32_u24_e32 v207, 0x3300, v246
	v_add_u32_e32 v207, v207, v245
	v_mul_u32_u24_e32 v249, 0x400, v246
	v_add_u32_e32 v249, v249, v245
	v_add_u32_e32 v246, 64, v244
	v_mul_u32_u24_e32 v208, 0x3300, v246
	v_add_u32_e32 v208, v208, v245
	v_mul_u32_u24_e32 v250, 0x400, v246
	v_add_u32_e32 v250, v250, v245
	v_add_u32_e32 v246, 96, v244
	v_mul_u32_u24_e32 v226, 0x3300, v246
	v_add_u32_e32 v226, v226, v245
	v_mul_u32_u24_e32 v169, 0x400, v246
	v_add_u32_e32 v169, v169, v245
	v_mul_u32_u24_e32 v150, 0x90, v244
	v_add_u32_e32 v150, v150, v245
	v_add_u32_e32 v151, 0x1200, v150
	v_and_b32_e32 v244, 31, v209
	v_bfe_u32 v245, v209, 5, 1
	v_lshlrev_b32_e32 v245, 4, v245
	v_bfe_u32 v246, v209, 7, 1
	v_lshl_add_u32 v246, v246, 6, v244
	v_mul_u32_u24_e32 v148, 0x90, v246
	v_add_u32_e32 v148, v148, v245
	v_bfe_u32 v246, v209, 6, 1
	v_lshl_add_u32 v246, v246, 6, v244
	v_mul_u32_u24_e32 v0, 0x90, v246
	v_add_u32_e32 v0, v0, v245
	global_load_dwordx4 v[170:173], v206, s[8:9]
	global_load_dwordx4 v[174:177], v248, s[0:1]
	global_load_dwordx4 v[178:181], v207, s[8:9]
	global_load_dwordx4 v[182:185], v249, s[0:1]
	global_load_dwordx4 v[186:189], v208, s[8:9]
	global_load_dwordx4 v[190:193], v250, s[0:1]
	global_load_dwordx4 v[194:197], v226, s[8:9]
	global_load_dwordx4 v[198:201], v169, s[0:1]
	global_load_dwordx4 v[152:155], v206, s[8:9] offset:128
	global_load_dwordx4 v[228:231], v248, s[0:1] offset:128
	global_load_dwordx4 v[156:159], v207, s[8:9] offset:128
	global_load_dwordx4 v[232:235], v249, s[0:1] offset:128
	global_load_dwordx4 v[160:163], v208, s[8:9] offset:128
	global_load_dwordx4 v[236:239], v250, s[0:1] offset:128
	global_load_dwordx4 v[164:167], v226, s[8:9] offset:128
	global_load_dwordx4 v[240:243], v169, s[0:1] offset:128
	s_waitcnt vmcnt(15)
	ds_write_b128 v150, v[170:173]
	s_waitcnt vmcnt(14)
	ds_write_b128 v150, v[174:177] offset:36864
	s_waitcnt vmcnt(13)
	ds_write_b128 v150, v[178:181] offset:4608
	s_waitcnt vmcnt(12)
	ds_write_b128 v150, v[182:185] offset:41472
	s_waitcnt vmcnt(11)
	ds_write_b128 v150, v[186:189] offset:9216
	s_waitcnt vmcnt(10)
	ds_write_b128 v150, v[190:193] offset:46080
	s_waitcnt vmcnt(9)
	ds_write_b128 v150, v[194:197] offset:13824
	s_waitcnt vmcnt(8)
	ds_write_b128 v150, v[198:201] offset:50688
	s_waitcnt lgkmcnt(0)
	s_barrier
	s_setprio 1
	ds_read_b128 v[212:215], v0 offset:36864
	ds_read_b128 v[216:219], v148
	ds_read_b128 v[202:205], v0 offset:41472
	ds_read_b128 v[244:247], v148 offset:4608
	s_waitcnt lgkmcnt(2)
	v_mfma_f32_32x32x16_f16 v[50:65], v[212:215], v[216:219], 0
	global_load_dwordx4 v[170:173], v206, s[8:9] offset:256
	s_waitcnt lgkmcnt(1)
	v_mfma_f32_32x32x16_f16 v[34:49], v[202:205], v[216:219], 0
	ds_read_b128 v[216:219], v148 offset:32
	s_waitcnt vmcnt(8)
	ds_write_b128 v150, v[152:155] offset:18432
	s_waitcnt lgkmcnt(2)
	v_mfma_f32_32x32x16_f16 v[18:33], v[212:215], v[244:247], 0
	ds_read_b128 v[212:215], v0 offset:36896
	global_load_dwordx4 v[174:177], v248, s[0:1] offset:256
	v_mfma_f32_32x32x16_f16 v[2:17], v[202:205], v[244:247], 0
	ds_read_b128 v[202:205], v0 offset:41504
	ds_read_b128 v[244:247], v148 offset:4640
	s_waitcnt vmcnt(8)
	ds_write_b128 v150, v[228:231] offset:55296
	s_waitcnt lgkmcnt(3)
	v_mfma_f32_32x32x16_f16 v[50:65], v[212:215], v[216:219], v[50:65]
	global_load_dwordx4 v[178:181], v207, s[8:9] offset:256
	s_waitcnt lgkmcnt(2)
	v_mfma_f32_32x32x16_f16 v[34:49], v[202:205], v[216:219], v[34:49]
	ds_read_b128 v[216:219], v148 offset:64
	s_waitcnt vmcnt(8)
	ds_write_b128 v150, v[156:159] offset:23040
	s_waitcnt lgkmcnt(3)
	v_mfma_f32_32x32x16_f16 v[18:33], v[212:215], v[244:247], v[18:33]
	ds_read_b128 v[212:215], v0 offset:36928
	global_load_dwordx4 v[182:185], v249, s[0:1] offset:256
	v_mfma_f32_32x32x16_f16 v[2:17], v[202:205], v[244:247], v[2:17]
	ds_read_b128 v[202:205], v0 offset:41536
	ds_read_b128 v[244:247], v148 offset:4672
	s_waitcnt vmcnt(8)
	ds_write_b128 v150, v[232:235] offset:59904
	s_waitcnt lgkmcnt(3)
	v_mfma_f32_32x32x16_f16 v[50:65], v[212:215], v[216:219], v[50:65]
	global_load_dwordx4 v[186:189], v208, s[8:9] offset:256
	s_waitcnt lgkmcnt(2)
	v_mfma_f32_32x32x16_f16 v[34:49], v[202:205], v[216:219], v[34:49]
	ds_read_b128 v[216:219], v148 offset:96
	s_waitcnt vmcnt(8)
	ds_write_b128 v150, v[160:163] offset:27648
	s_waitcnt lgkmcnt(3)
	v_mfma_f32_32x32x16_f16 v[18:33], v[212:215], v[244:247], v[18:33]
	ds_read_b128 v[212:215], v0 offset:36960
	global_load_dwordx4 v[190:193], v250, s[0:1] offset:256
	v_mfma_f32_32x32x16_f16 v[2:17], v[202:205], v[244:247], v[2:17]
	ds_read_b128 v[202:205], v0 offset:41568
	ds_read_b128 v[244:247], v148 offset:4704
	s_waitcnt vmcnt(8)
	ds_write_b128 v150, v[236:239] offset:64512
	s_waitcnt lgkmcnt(3)
	v_mfma_f32_32x32x16_f16 v[50:65], v[212:215], v[216:219], v[50:65]
	global_load_dwordx4 v[194:197], v226, s[8:9] offset:256
	s_waitcnt lgkmcnt(2)
	v_mfma_f32_32x32x16_f16 v[34:49], v[202:205], v[216:219], v[34:49]
	s_waitcnt vmcnt(8)
	ds_write_b128 v150, v[164:167] offset:32256
	s_waitcnt lgkmcnt(2)
	v_mfma_f32_32x32x16_f16 v[18:33], v[212:215], v[244:247], v[18:33]
	global_load_dwordx4 v[198:201], v169, s[0:1] offset:256
	v_mfma_f32_32x32x16_f16 v[2:17], v[202:205], v[244:247], v[2:17]
	s_waitcnt vmcnt(8)
	ds_write_b128 v151, v[240:243] offset:64512
	s_setprio 0
	s_waitcnt lgkmcnt(0)
	s_barrier
; #define GEMM_GLOAD(P, kt_) { GEMM_GL1(P, 0, kt_) GEMM_GL1(P, 1, kt_) GEMM_GL1(P, 2, kt_) GEMM_GL1(P, 3, kt_) }
; #define GEMM_LSTORE(P, buf_) { GEMM_LS1(P, 0, buf_) GEMM_LS1(P, 1, buf_) GEMM_LS1(P, 2, buf_) GEMM_LS1(P, 3, buf_) }
; template <bool DEEP>
; DI void gemm_mainloop_t(const u16* __restrict__ Ag, int lda, const u16* __restrict__ Bg, int ldb, int K, char* ldsraw,
;                         f32x16 (&acc)[2][2], int akstep) {
;     ...
;     for (int kt = 0; kt < nk; kt += 2) {
;       if (kt + 2 < nk) GEMM_GLOAD(x, kt + 2);
;       GEMM_COMPUTE(0);
;       GEMM_LSTORE(y, 1);
;       __syncthreads();
;       if (kt + 3 < nk) GEMM_GLOAD(y, kt + 3);
;       GEMM_COMPUTE(1);
;       if (kt + 2 < nk) GEMM_LSTORE(x, 0);
;       __syncthreads();
;     }
	s_setprio 1
	ds_read_b128 v[212:215], v0 offset:55296
	ds_read_b128 v[216:219], v148 offset:18432
	ds_read_b128 v[202:205], v0 offset:59904
	ds_read_b128 v[244:247], v148 offset:23040
	s_waitcnt lgkmcnt(2)
	v_mfma_f32_32x32x16_f16 v[50:65], v[212:215], v[216:219], v[50:65]
	global_load_dwordx4 v[152:155], v206, s[8:9] offset:384
	s_waitcnt lgkmcnt(1)
	v_mfma_f32_32x32x16_f16 v[34:49], v[202:205], v[216:219], v[34:49]
	ds_read_b128 v[216:219], v148 offset:18464
	s_waitcnt vmcnt(8)
	ds_write_b128 v150, v[170:173]
	s_waitcnt lgkmcnt(2)
	v_mfma_f32_32x32x16_f16 v[18:33], v[212:215], v[244:247], v[18:33]
	ds_read_b128 v[212:215], v0 offset:55328
	global_load_dwordx4 v[228:231], v248, s[0:1] offset:384
	v_mfma_f32_32x32x16_f16 v[2:17], v[202:205], v[244:247], v[2:17]
	ds_read_b128 v[202:205], v0 offset:59936
	ds_read_b128 v[244:247], v148 offset:23072
	s_waitcnt vmcnt(8)
	ds_write_b128 v150, v[174:177] offset:36864
	s_waitcnt lgkmcnt(3)
	v_mfma_f32_32x32x16_f16 v[50:65], v[212:215], v[216:219], v[50:65]
	global_load_dwordx4 v[156:159], v207, s[8:9] offset:384
	s_waitcnt lgkmcnt(2)
	v_mfma_f32_32x32x16_f16 v[34:49], v[202:205], v[216:219], v[34:49]
	ds_read_b128 v[216:219], v148 offset:18496
	s_waitcnt vmcnt(8)
	ds_write_b128 v150, v[178:181] offset:4608
	s_waitcnt lgkmcnt(3)
	v_mfma_f32_32x32x16_f16 v[18:33], v[212:215], v[244:247], v[18:33]
	ds_read_b128 v[212:215], v0 offset:55360
	global_load_dwordx4 v[232:235], v249, s[0:1] offset:384
	v_mfma_f32_32x32x16_f16 v[2:17], v[202:205], v[244:247], v[2:17]
	ds_read_b128 v[202:205], v0 offset:59968
	ds_read_b128 v[244:247], v148 offset:23104
	s_waitcnt vmcnt(8)
	ds_write_b128 v150, v[182:185] offset:41472
	s_waitcnt lgkmcnt(3)
	v_mfma_f32_32x32x16_f16 v[50:65], v[212:215], v[216:219], v[50:65]
	global_load_dwordx4 v[160:163], v208, s[8:9] offset:384
	s_waitcnt lgkmcnt(2)
	v_mfma_f32_32x32x16_f16 v[34:49], v[202:205], v[216:219], v[34:49]
	ds_read_b128 v[216:219], v148 offset:18528
	s_waitcnt vmcnt(8)
	ds_write_b128 v150, v[186:189] offset:9216
	s_waitcnt lgkmcnt(3)
	v_mfma_f32_32x32x16_f16 v[18:33], v[212:215], v[244:247], v[18:33]
	ds_read_b128 v[212:215], v0 offset:55392
	global_load_dwordx4 v[236:239], v250, s[0:1] offset:384
	v_mfma_f32_32x32x16_f16 v[2:17], v[202:205], v[244:247], v[2:17]
	ds_read_b128 v[202:205], v0 offset:60000
	ds_read_b128 v[244:247], v148 offset:23136
	s_waitcnt vmcnt(8)
	ds_write_b128 v150, v[190:193] offset:46080
	s_waitcnt lgkmcnt(3)
	v_mfma_f32_32x32x16_f16 v[50:65], v[212:215], v[216:219], v[50:65]
	global_load_dwordx4 v[164:167], v226, s[8:9] offset:384
	s_waitcnt lgkmcnt(2)
	v_mfma_f32_32x32x16_f16 v[34:49], v[202:205], v[216:219], v[34:49]
	s_waitcnt vmcnt(8)
	ds_write_b128 v150, v[194:197] offset:13824
	s_waitcnt lgkmcnt(2)
	v_mfma_f32_32x32x16_f16 v[18:33], v[212:215], v[244:247], v[18:33]
	global_load_dwordx4 v[240:243], v169, s[0:1] offset:384
	v_mfma_f32_32x32x16_f16 v[2:17], v[202:205], v[244:247], v[2:17]
	s_waitcnt vmcnt(8)
	ds_write_b128 v150, v[198:201] offset:50688
	s_setprio 0
	s_waitcnt lgkmcnt(0)
	s_barrier
	s_setprio 1
	ds_read_b128 v[212:215], v0 offset:36864
	ds_read_b128 v[216:219], v148
	ds_read_b128 v[202:205], v0 offset:41472
	ds_read_b128 v[244:247], v148 offset:4608
	s_waitcnt lgkmcnt(2)
	v_mfma_f32_32x32x16_f16 v[50:65], v[212:215], v[216:219], v[50:65]
	global_load_dwordx4 v[170:173], v206, s[8:9] offset:512
	s_waitcnt lgkmcnt(1)
	v_mfma_f32_32x32x16_f16 v[34:49], v[202:205], v[216:219], v[34:49]
	ds_read_b128 v[216:219], v148 offset:32
	s_waitcnt vmcnt(8)
	ds_write_b128 v150, v[152:155] offset:18432
	s_waitcnt lgkmcnt(2)
	v_mfma_f32_32x32x16_f16 v[18:33], v[212:215], v[244:247], v[18:33]
	ds_read_b128 v[212:215], v0 offset:36896
	global_load_dwordx4 v[174:177], v248, s[0:1] offset:512
	v_mfma_f32_32x32x16_f16 v[2:17], v[202:205], v[244:247], v[2:17]
	ds_read_b128 v[202:205], v0 offset:41504
	ds_read_b128 v[244:247], v148 offset:4640
	s_waitcnt vmcnt(8)
	ds_write_b128 v150, v[228:231] offset:55296
	s_waitcnt lgkmcnt(3)
	v_mfma_f32_32x32x16_f16 v[50:65], v[212:215], v[216:219], v[50:65]
	global_load_dwordx4 v[178:181], v207, s[8:9] offset:512
	s_waitcnt lgkmcnt(2)
	v_mfma_f32_32x32x16_f16 v[34:49], v[202:205], v[216:219], v[34:49]
	ds_read_b128 v[216:219], v148 offset:64
	s_waitcnt vmcnt(8)
	ds_write_b128 v150, v[156:159] offset:23040
	s_waitcnt lgkmcnt(3)
	v_mfma_f32_32x32x16_f16 v[18:33], v[212:215], v[244:247], v[18:33]
	ds_read_b128 v[212:215], v0 offset:36928
	global_load_dwordx4 v[182:185], v249, s[0:1] offset:512
	v_mfma_f32_32x32x16_f16 v[2:17], v[202:205], v[244:247], v[2:17]
	ds_read_b128 v[202:205], v0 offset:41536
	ds_read_b128 v[244:247], v148 offset:4672
	s_waitcnt vmcnt(8)
	ds_write_b128 v150, v[232:235] offset:59904
	s_waitcnt lgkmcnt(3)
	v_mfma_f32_32x32x16_f16 v[50:65], v[212:215], v[216:219], v[50:65]
	global_load_dwordx4 v[186:189], v208, s[8:9] offset:512
	s_waitcnt lgkmcnt(2)
	v_mfma_f32_32x32x16_f16 v[34:49], v[202:205], v[216:219], v[34:49]
	ds_read_b128 v[216:219], v148 offset:96
	s_waitcnt vmcnt(8)
	ds_write_b128 v150, v[160:163] offset:27648
	s_waitcnt lgkmcnt(3)
	v_mfma_f32_32x32x16_f16 v[18:33], v[212:215], v[244:247], v[18:33]
	ds_read_b128 v[212:215], v0 offset:36960
	global_load_dwordx4 v[190:193], v250, s[0:1] offset:512
	v_mfma_f32_32x32x16_f16 v[2:17], v[202:205], v[244:247], v[2:17]
	ds_read_b128 v[202:205], v0 offset:41568
	ds_read_b128 v[244:247], v148 offset:4704
	s_waitcnt vmcnt(8)
	ds_write_b128 v150, v[236:239] offset:64512
	s_waitcnt lgkmcnt(3)
	v_mfma_f32_32x32x16_f16 v[50:65], v[212:215], v[216:219], v[50:65]
	global_load_dwordx4 v[194:197], v226, s[8:9] offset:512
	s_waitcnt lgkmcnt(2)
	v_mfma_f32_32x32x16_f16 v[34:49], v[202:205], v[216:219], v[34:49]
	s_waitcnt vmcnt(8)
	ds_write_b128 v150, v[164:167] offset:32256
	s_waitcnt lgkmcnt(2)
	v_mfma_f32_32x32x16_f16 v[18:33], v[212:215], v[244:247], v[18:33]
	global_load_dwordx4 v[198:201], v169, s[0:1] offset:512
	v_mfma_f32_32x32x16_f16 v[2:17], v[202:205], v[244:247], v[2:17]
	s_waitcnt vmcnt(8)
	ds_write_b128 v151, v[240:243] offset:64512
	s_setprio 0
	s_waitcnt lgkmcnt(0)
	s_barrier
; #define GEMM_GLOAD(P, kt_) { GEMM_GL1(P, 0, kt_) GEMM_GL1(P, 1, kt_) GEMM_GL1(P, 2, kt_) GEMM_GL1(P, 3, kt_) }
; #define GEMM_LSTORE(P, buf_) { GEMM_LS1(P, 0, buf_) GEMM_LS1(P, 1, buf_) GEMM_LS1(P, 2, buf_) GEMM_LS1(P, 3, buf_) }
; template <bool DEEP>
; DI void gemm_mainloop_t(const u16* __restrict__ Ag, int lda, const u16* __restrict__ Bg, int ldb, int K, char* ldsraw,
;                         f32x16 (&acc)[2][2], int akstep) {
;     ...
;     for (int kt = 0; kt < nk; kt += 2) {
;       if (kt + 2 < nk) GEMM_GLOAD(x, kt + 2);
;       GEMM_COMPUTE(0);
;       GEMM_LSTORE(y, 1);
;       __syncthreads();
;       if (kt + 3 < nk) GEMM_GLOAD(y, kt + 3);
;       GEMM_COMPUTE(1);
;       if (kt + 2 < nk) GEMM_LSTORE(x, 0);
;       __syncthreads();
;     }
	s_setprio 1
	ds_read_b128 v[212:215], v0 offset:55296
	ds_read_b128 v[216:219], v148 offset:18432
	ds_read_b128 v[202:205], v0 offset:59904
	ds_read_b128 v[244:247], v148 offset:23040
	s_waitcnt lgkmcnt(2)
	v_mfma_f32_32x32x16_f16 v[50:65], v[212:215], v[216:219], v[50:65]
	global_load_dwordx4 v[152:155], v206, s[8:9] offset:640
	s_waitcnt lgkmcnt(1)
	v_mfma_f32_32x32x16_f16 v[34:49], v[202:205], v[216:219], v[34:49]
	ds_read_b128 v[216:219], v148 offset:18464
	s_waitcnt vmcnt(8)
	ds_write_b128 v150, v[170:173]
	s_waitcnt lgkmcnt(2)
	v_mfma_f32_32x32x16_f16 v[18:33], v[212:215], v[244:247], v[18:33]
	ds_read_b128 v[212:215], v0 offset:55328
	global_load_dwordx4 v[228:231], v248, s[0:1] offset:640
	v_mfma_f32_32x32x16_f16 v[2:17], v[202:205], v[244:247], v[2:17]
	ds_read_b128 v[202:205], v0 offset:59936
	ds_read_b128 v[244:247], v148 offset:23072
	s_waitcnt vmcnt(8)
	ds_write_b128 v150, v[174:177] offset:36864
	s_waitcnt lgkmcnt(3)
	v_mfma_f32_32x32x16_f16 v[50:65], v[212:215], v[216:219], v[50:65]
	global_load_dwordx4 v[156:159], v207, s[8:9] offset:640
	s_waitcnt lgkmcnt(2)
	v_mfma_f32_32x32x16_f16 v[34:49], v[202:205], v[216:219], v[34:49]
	ds_read_b128 v[216:219], v148 offset:18496
	s_waitcnt vmcnt(8)
	ds_write_b128 v150, v[178:181] offset:4608
	s_waitcnt lgkmcnt(3)
	v_mfma_f32_32x32x16_f16 v[18:33], v[212:215], v[244:247], v[18:33]
	ds_read_b128 v[212:215], v0 offset:55360
	global_load_dwordx4 v[232:235], v249, s[0:1] offset:640
	v_mfma_f32_32x32x16_f16 v[2:17], v[202:205], v[244:247], v[2:17]
	ds_read_b128 v[202:205], v0 offset:59968
	ds_read_b128 v[244:247], v148 offset:23104
	s_waitcnt vmcnt(8)
	ds_write_b128 v150, v[182:185] offset:41472
	s_waitcnt lgkmcnt(3)
	v_mfma_f32_32x32x16_f16 v[50:65], v[212:215], v[216:219], v[50:65]
	global_load_dwordx4 v[160:163], v208, s[8:9] offset:640
	s_waitcnt lgkmcnt(2)
	v_mfma_f32_32x32x16_f16 v[34:49], v[202:205], v[216:219], v[34:49]
	ds_read_b128 v[216:219], v148 offset:18528
	s_waitcnt vmcnt(8)
	ds_write_b128 v150, v[186:189] offset:9216
	s_waitcnt lgkmcnt(3)
	v_mfma_f32_32x32x16_f16 v[18:33], v[212:215], v[244:247], v[18:33]
	ds_read_b128 v[212:215], v0 offset:55392
	global_load_dwordx4 v[236:239], v250, s[0:1] offset:640
	v_mfma_f32_32x32x16_f16 v[2:17], v[202:205], v[244:247], v[2:17]
	ds_read_b128 v[202:205], v0 offset:60000
	ds_read_b128 v[244:247], v148 offset:23136
	s_waitcnt vmcnt(8)
	ds_write_b128 v150, v[190:193] offset:46080
	s_waitcnt lgkmcnt(3)
	v_mfma_f32_32x32x16_f16 v[50:65], v[212:215], v[216:219], v[50:65]
	global_load_dwordx4 v[164:167], v226, s[8:9] offset:640
	s_waitcnt lgkmcnt(2)
	v_mfma_f32_32x32x16_f16 v[34:49], v[202:205], v[216:219], v[34:49]
	s_waitcnt vmcnt(8)
	ds_write_b128 v150, v[194:197] offset:13824
	s_waitcnt lgkmcnt(2)
	v_mfma_f32_32x32x16_f16 v[18:33], v[212:215], v[244:247], v[18:33]
	global_load_dwordx4 v[240:243], v169, s[0:1] offset:640
	v_mfma_f32_32x32x16_f16 v[2:17], v[202:205], v[244:247], v[2:17]
	s_waitcnt vmcnt(8)
	ds_write_b128 v150, v[198:201] offset:50688
	s_setprio 0
	s_waitcnt lgkmcnt(0)
	s_barrier
	s_setprio 1
	ds_read_b128 v[212:215], v0 offset:36864
	ds_read_b128 v[216:219], v148
	ds_read_b128 v[202:205], v0 offset:41472
	ds_read_b128 v[244:247], v148 offset:4608
	s_waitcnt lgkmcnt(2)
	v_mfma_f32_32x32x16_f16 v[50:65], v[212:215], v[216:219], v[50:65]
	global_load_dwordx4 v[170:173], v206, s[8:9] offset:768
	s_waitcnt lgkmcnt(1)
	v_mfma_f32_32x32x16_f16 v[34:49], v[202:205], v[216:219], v[34:49]
	ds_read_b128 v[216:219], v148 offset:32
	s_waitcnt vmcnt(8)
	ds_write_b128 v150, v[152:155] offset:18432
	s_waitcnt lgkmcnt(2)
	v_mfma_f32_32x32x16_f16 v[18:33], v[212:215], v[244:247], v[18:33]
	ds_read_b128 v[212:215], v0 offset:36896
	global_load_dwordx4 v[174:177], v248, s[0:1] offset:768
	v_mfma_f32_32x32x16_f16 v[2:17], v[202:205], v[244:247], v[2:17]
	ds_read_b128 v[202:205], v0 offset:41504
	ds_read_b128 v[244:247], v148 offset:4640
	s_waitcnt vmcnt(8)
	ds_write_b128 v150, v[228:231] offset:55296
	s_waitcnt lgkmcnt(3)
	v_mfma_f32_32x32x16_f16 v[50:65], v[212:215], v[216:219], v[50:65]
	global_load_dwordx4 v[178:181], v207, s[8:9] offset:768
	s_waitcnt lgkmcnt(2)
	v_mfma_f32_32x32x16_f16 v[34:49], v[202:205], v[216:219], v[34:49]
	ds_read_b128 v[216:219], v148 offset:64
	s_waitcnt vmcnt(8)
	ds_write_b128 v150, v[156:159] offset:23040
	s_waitcnt lgkmcnt(3)
	v_mfma_f32_32x32x16_f16 v[18:33], v[212:215], v[244:247], v[18:33]
	ds_read_b128 v[212:215], v0 offset:36928
	global_load_dwordx4 v[182:185], v249, s[0:1] offset:768
	v_mfma_f32_32x32x16_f16 v[2:17], v[202:205], v[244:247], v[2:17]
	ds_read_b128 v[202:205], v0 offset:41536
	ds_read_b128 v[244:247], v148 offset:4672
	s_waitcnt vmcnt(8)
	ds_write_b128 v150, v[232:235] offset:59904
	s_waitcnt lgkmcnt(3)
	v_mfma_f32_32x32x16_f16 v[50:65], v[212:215], v[216:219], v[50:65]
	global_load_dwordx4 v[186:189], v208, s[8:9] offset:768
	s_waitcnt lgkmcnt(2)
	v_mfma_f32_32x32x16_f16 v[34:49], v[202:205], v[216:219], v[34:49]
	ds_read_b128 v[216:219], v148 offset:96
	s_waitcnt vmcnt(8)
	ds_write_b128 v150, v[160:163] offset:27648
	s_waitcnt lgkmcnt(3)
	v_mfma_f32_32x32x16_f16 v[18:33], v[212:215], v[244:247], v[18:33]
	ds_read_b128 v[212:215], v0 offset:36960
	global_load_dwordx4 v[190:193], v250, s[0:1] offset:768
	v_mfma_f32_32x32x16_f16 v[2:17], v[202:205], v[244:247], v[2:17]
	ds_read_b128 v[202:205], v0 offset:41568
	ds_read_b128 v[244:247], v148 offset:4704
	s_waitcnt vmcnt(8)
	ds_write_b128 v150, v[236:239] offset:64512
	s_waitcnt lgkmcnt(3)
	v_mfma_f32_32x32x16_f16 v[50:65], v[212:215], v[216:219], v[50:65]
	global_load_dwordx4 v[194:197], v226, s[8:9] offset:768
	s_waitcnt lgkmcnt(2)
	v_mfma_f32_32x32x16_f16 v[34:49], v[202:205], v[216:219], v[34:49]
	s_waitcnt vmcnt(8)
	ds_write_b128 v150, v[164:167] offset:32256
	s_waitcnt lgkmcnt(2)
	v_mfma_f32_32x32x16_f16 v[18:33], v[212:215], v[244:247], v[18:33]
	global_load_dwordx4 v[198:201], v169, s[0:1] offset:768
	v_mfma_f32_32x32x16_f16 v[2:17], v[202:205], v[244:247], v[2:17]
	s_waitcnt vmcnt(8)
	ds_write_b128 v151, v[240:243] offset:64512
	s_setprio 0
	s_waitcnt lgkmcnt(0)
	s_barrier
; #define GEMM_GLOAD(P, kt_) { GEMM_GL1(P, 0, kt_) GEMM_GL1(P, 1, kt_) GEMM_GL1(P, 2, kt_) GEMM_GL1(P, 3, kt_) }
; #define GEMM_LSTORE(P, buf_) { GEMM_LS1(P, 0, buf_) GEMM_LS1(P, 1, buf_) GEMM_LS1(P, 2, buf_) GEMM_LS1(P, 3, buf_) }
; template <bool DEEP>
; DI void gemm_mainloop_t(const u16* __restrict__ Ag, int lda, const u16* __restrict__ Bg, int ldb, int K, char* ldsraw,
;                         f32x16 (&acc)[2][2], int akstep) {
;     ...
;     for (int kt = 0; kt < nk; kt += 2) {
;       if (kt + 2 < nk) GEMM_GLOAD(x, kt + 2);
;       GEMM_COMPUTE(0);
;       GEMM_LSTORE(y, 1);
;       __syncthreads();
;       if (kt + 3 < nk) GEMM_GLOAD(y, kt + 3);
;       GEMM_COMPUTE(1);
;       if (kt + 2 < nk) GEMM_LSTORE(x, 0);
;       __syncthreads();
;     }
	s_setprio 1
	ds_read_b128 v[212:215], v0 offset:55296
	ds_read_b128 v[216:219], v148 offset:18432
	ds_read_b128 v[202:205], v0 offset:59904
	ds_read_b128 v[244:247], v148 offset:23040
	s_waitcnt lgkmcnt(2)
	v_mfma_f32_32x32x16_f16 v[50:65], v[212:215], v[216:219], v[50:65]
	global_load_dwordx4 v[152:155], v206, s[8:9] offset:896
	s_waitcnt lgkmcnt(1)
	v_mfma_f32_32x32x16_f16 v[34:49], v[202:205], v[216:219], v[34:49]
	ds_read_b128 v[216:219], v148 offset:18464
	s_waitcnt vmcnt(8)
	ds_write_b128 v150, v[170:173]
	s_waitcnt lgkmcnt(2)
	v_mfma_f32_32x32x16_f16 v[18:33], v[212:215], v[244:247], v[18:33]
	ds_read_b128 v[212:215], v0 offset:55328
	global_load_dwordx4 v[228:231], v248, s[0:1] offset:896
	v_mfma_f32_32x32x16_f16 v[2:17], v[202:205], v[244:247], v[2:17]
	ds_read_b128 v[202:205], v0 offset:59936
	ds_read_b128 v[244:247], v148 offset:23072
	s_waitcnt vmcnt(8)
	ds_write_b128 v150, v[174:177] offset:36864
	s_waitcnt lgkmcnt(3)
	v_mfma_f32_32x32x16_f16 v[50:65], v[212:215], v[216:219], v[50:65]
	global_load_dwordx4 v[156:159], v207, s[8:9] offset:896
	s_waitcnt lgkmcnt(2)
	v_mfma_f32_32x32x16_f16 v[34:49], v[202:205], v[216:219], v[34:49]
	ds_read_b128 v[216:219], v148 offset:18496
	s_waitcnt vmcnt(8)
	ds_write_b128 v150, v[178:181] offset:4608
	s_waitcnt lgkmcnt(3)
	v_mfma_f32_32x32x16_f16 v[18:33], v[212:215], v[244:247], v[18:33]
	ds_read_b128 v[212:215], v0 offset:55360
	global_load_dwordx4 v[232:235], v249, s[0:1] offset:896
	v_mfma_f32_32x32x16_f16 v[2:17], v[202:205], v[244:247], v[2:17]
	ds_read_b128 v[202:205], v0 offset:59968
	ds_read_b128 v[244:247], v148 offset:23104
	s_waitcnt vmcnt(8)
	ds_write_b128 v150, v[182:185] offset:41472
	s_waitcnt lgkmcnt(3)
	v_mfma_f32_32x32x16_f16 v[50:65], v[212:215], v[216:219], v[50:65]
	global_load_dwordx4 v[160:163], v208, s[8:9] offset:896
	s_waitcnt lgkmcnt(2)
	v_mfma_f32_32x32x16_f16 v[34:49], v[202:205], v[216:219], v[34:49]
	ds_read_b128 v[216:219], v148 offset:18528
	s_waitcnt vmcnt(8)
	ds_write_b128 v150, v[186:189] offset:9216
	s_waitcnt lgkmcnt(3)
	v_mfma_f32_32x32x16_f16 v[18:33], v[212:215], v[244:247], v[18:33]
	ds_read_b128 v[212:215], v0 offset:55392
	global_load_dwordx4 v[236:239], v250, s[0:1] offset:896
	v_mfma_f32_32x32x16_f16 v[2:17], v[202:205], v[244:247], v[2:17]
	ds_read_b128 v[202:205], v0 offset:60000
	ds_read_b128 v[244:247], v148 offset:23136
	s_waitcnt vmcnt(8)
	ds_write_b128 v150, v[190:193] offset:46080
	s_waitcnt lgkmcnt(3)
	v_mfma_f32_32x32x16_f16 v[50:65], v[212:215], v[216:219], v[50:65]
	global_load_dwordx4 v[164:167], v226, s[8:9] offset:896
	s_waitcnt lgkmcnt(2)
	v_mfma_f32_32x32x16_f16 v[34:49], v[202:205], v[216:219], v[34:49]
	s_waitcnt vmcnt(8)
	ds_write_b128 v150, v[194:197] offset:13824
	s_waitcnt lgkmcnt(2)
	v_mfma_f32_32x32x16_f16 v[18:33], v[212:215], v[244:247], v[18:33]
	global_load_dwordx4 v[240:243], v169, s[0:1] offset:896
	v_mfma_f32_32x32x16_f16 v[2:17], v[202:205], v[244:247], v[2:17]
	s_waitcnt vmcnt(8)
	ds_write_b128 v150, v[198:201] offset:50688
	s_setprio 0
	s_waitcnt lgkmcnt(0)
	s_barrier
	s_setprio 1
	ds_read_b128 v[212:215], v0 offset:36864
	ds_read_b128 v[216:219], v148
	ds_read_b128 v[202:205], v0 offset:41472
	ds_read_b128 v[244:247], v148 offset:4608
	s_waitcnt lgkmcnt(2)
	v_mfma_f32_32x32x16_f16 v[50:65], v[212:215], v[216:219], v[50:65]
	s_waitcnt lgkmcnt(1)
	v_mfma_f32_32x32x16_f16 v[34:49], v[202:205], v[216:219], v[34:49]
	ds_read_b128 v[216:219], v148 offset:32
	s_waitcnt vmcnt(7)
	ds_write_b128 v150, v[152:155] offset:18432
	s_waitcnt lgkmcnt(2)
	v_mfma_f32_32x32x16_f16 v[18:33], v[212:215], v[244:247], v[18:33]
	ds_read_b128 v[212:215], v0 offset:36896
	v_mfma_f32_32x32x16_f16 v[2:17], v[202:205], v[244:247], v[2:17]
	ds_read_b128 v[202:205], v0 offset:41504
	ds_read_b128 v[244:247], v148 offset:4640
	s_waitcnt vmcnt(6)
	ds_write_b128 v150, v[228:231] offset:55296
	s_waitcnt lgkmcnt(3)
	v_mfma_f32_32x32x16_f16 v[50:65], v[212:215], v[216:219], v[50:65]
	s_waitcnt lgkmcnt(2)
	v_mfma_f32_32x32x16_f16 v[34:49], v[202:205], v[216:219], v[34:49]
	ds_read_b128 v[216:219], v148 offset:64
	s_waitcnt vmcnt(5)
	ds_write_b128 v150, v[156:159] offset:23040
	s_waitcnt lgkmcnt(3)
	v_mfma_f32_32x32x16_f16 v[18:33], v[212:215], v[244:247], v[18:33]
	ds_read_b128 v[212:215], v0 offset:36928
	v_mfma_f32_32x32x16_f16 v[2:17], v[202:205], v[244:247], v[2:17]
	ds_read_b128 v[202:205], v0 offset:41536
	ds_read_b128 v[244:247], v148 offset:4672
	s_waitcnt vmcnt(4)
	ds_write_b128 v150, v[232:235] offset:59904
	s_waitcnt lgkmcnt(3)
	v_mfma_f32_32x32x16_f16 v[50:65], v[212:215], v[216:219], v[50:65]
	s_waitcnt lgkmcnt(2)
	v_mfma_f32_32x32x16_f16 v[34:49], v[202:205], v[216:219], v[34:49]
	ds_read_b128 v[216:219], v148 offset:96
	s_waitcnt vmcnt(3)
	ds_write_b128 v150, v[160:163] offset:27648
	s_waitcnt lgkmcnt(3)
	v_mfma_f32_32x32x16_f16 v[18:33], v[212:215], v[244:247], v[18:33]
	ds_read_b128 v[212:215], v0 offset:36960
	v_mfma_f32_32x32x16_f16 v[2:17], v[202:205], v[244:247], v[2:17]
	ds_read_b128 v[202:205], v0 offset:41568
	ds_read_b128 v[244:247], v148 offset:4704
	s_waitcnt vmcnt(2)
	ds_write_b128 v150, v[236:239] offset:64512
	s_waitcnt lgkmcnt(3)
	v_mfma_f32_32x32x16_f16 v[50:65], v[212:215], v[216:219], v[50:65]
	s_waitcnt lgkmcnt(2)
	v_mfma_f32_32x32x16_f16 v[34:49], v[202:205], v[216:219], v[34:49]
	s_waitcnt vmcnt(1)
	ds_write_b128 v150, v[164:167] offset:32256
	s_waitcnt lgkmcnt(2)
	v_mfma_f32_32x32x16_f16 v[18:33], v[212:215], v[244:247], v[18:33]
	v_mfma_f32_32x32x16_f16 v[2:17], v[202:205], v[244:247], v[2:17]
	s_waitcnt vmcnt(0)
	ds_write_b128 v151, v[240:243] offset:64512
	s_setprio 0
	s_waitcnt lgkmcnt(0)
	s_barrier
; DI float bflo(unsigned u) { return (float)__builtin_bit_cast(bf2_t, u)[0]; }
; DI float bfhi(unsigned u) { return (float)__builtin_bit_cast(bf2_t, u)[1]; }
; DI void phase4(const Params& p, int l, char* lds) {
;     ...
; #pragma unroll
;       for (int a = 0; a < 2; ++a)
; #pragma unroll
;         for (int b = 0; b < 2; ++b)
; #pragma unroll
;           for (int i = 0; i < 2; ++i) {
;             const uint4 o = scr[((a * 2 + b) * 2 + i) * 256];
;             mg[a][b][8 * i] += bflo(o.x) * acc[a][b][8 * i];
;             mg[a][b][8 * i + 1] += bfhi(o.x) * acc[a][b][8 * i + 1];
;             mg[a][b][8 * i + 2] += bflo(o.y) * acc[a][b][8 * i + 2];
;             mg[a][b][8 * i + 3] += bfhi(o.y) * acc[a][b][8 * i + 3];
;             mg[a][b][8 * i + 4] += bflo(o.z) * acc[a][b][8 * i + 4];
;             mg[a][b][8 * i + 5] += bfhi(o.z) * acc[a][b][8 * i + 5];
;             mg[a][b][8 * i + 6] += bflo(o.w) * acc[a][b][8 * i + 6];
;             mg[a][b][8 * i + 7] += bfhi(o.w) * acc[a][b][8 * i + 7];
;           }
	s_setprio 1
	ds_read_b128 v[212:215], v0 offset:55296
	ds_read_b128 v[216:219], v148 offset:18432
	ds_read_b128 v[202:205], v0 offset:59904
	ds_read_b128 v[244:247], v148 offset:23040
	s_waitcnt lgkmcnt(2)
	v_mfma_f32_32x32x16_f16 v[50:65], v[212:215], v[216:219], v[50:65]
	s_waitcnt lgkmcnt(1)
	v_mfma_f32_32x32x16_f16 v[34:49], v[202:205], v[216:219], v[34:49]
	ds_read_b128 v[216:219], v148 offset:18464
	s_waitcnt lgkmcnt(1)
	v_mfma_f32_32x32x16_f16 v[18:33], v[212:215], v[244:247], v[18:33]
	ds_read_b128 v[212:215], v0 offset:55328
	v_mfma_f32_32x32x16_f16 v[2:17], v[202:205], v[244:247], v[2:17]
	ds_read_b128 v[202:205], v0 offset:59936
	ds_read_b128 v[244:247], v148 offset:23072
	s_waitcnt lgkmcnt(2)
	v_mfma_f32_32x32x16_f16 v[50:65], v[212:215], v[216:219], v[50:65]
	s_waitcnt lgkmcnt(1)
	v_mfma_f32_32x32x16_f16 v[34:49], v[202:205], v[216:219], v[34:49]
	ds_read_b128 v[216:219], v148 offset:18496
	s_waitcnt lgkmcnt(1)
	v_mfma_f32_32x32x16_f16 v[18:33], v[212:215], v[244:247], v[18:33]
	ds_read_b128 v[212:215], v0 offset:55360
	v_mfma_f32_32x32x16_f16 v[2:17], v[202:205], v[244:247], v[2:17]
	ds_read_b128 v[202:205], v0 offset:59968
	ds_read_b128 v[244:247], v148 offset:23104
	s_waitcnt lgkmcnt(2)
	v_mfma_f32_32x32x16_f16 v[50:65], v[212:215], v[216:219], v[50:65]
	s_waitcnt lgkmcnt(1)
	v_mfma_f32_32x32x16_f16 v[34:49], v[202:205], v[216:219], v[34:49]
	ds_read_b128 v[216:219], v148 offset:18528
	s_waitcnt lgkmcnt(1)
	v_mfma_f32_32x32x16_f16 v[18:33], v[212:215], v[244:247], v[18:33]
	ds_read_b128 v[212:215], v0 offset:55392
	v_mfma_f32_32x32x16_f16 v[2:17], v[202:205], v[244:247], v[2:17]
	ds_read_b128 v[202:205], v0 offset:60000
	ds_read_b128 v[244:247], v148 offset:23136
	s_waitcnt lgkmcnt(2)
	v_mfma_f32_32x32x16_f16 v[50:65], v[212:215], v[216:219], v[50:65]
	s_waitcnt lgkmcnt(1)
	v_mfma_f32_32x32x16_f16 v[34:49], v[202:205], v[216:219], v[34:49]
	s_waitcnt lgkmcnt(0)
	v_mfma_f32_32x32x16_f16 v[18:33], v[212:215], v[244:247], v[18:33]
	v_mfma_f32_32x32x16_f16 v[2:17], v[202:205], v[244:247], v[2:17]
	s_setprio 0
	s_nop 1
	s_barrier
	global_load_dwordx4 v[170:173], v[68:69], off
	global_load_dwordx4 v[174:177], v[70:71], off
	global_load_dwordx4 v[178:181], v[72:73], off
	global_load_dwordx4 v[182:185], v[74:75], off
	global_load_dwordx4 v[186:189], v[76:77], off
	global_load_dwordx4 v[190:193], v[78:79], off
	global_load_dwordx4 v[194:197], v[80:81], off
	global_load_dwordx4 v[198:201], v[82:83], off
	s_add_i32 s22, s22, 1
	s_add_u32 s6, s6, 0x200000
	s_addc_u32 s7, s7, 0
	s_add_u32 s0, s0, 0x100000
	s_addc_u32 s1, s1, 0
	s_cmp_eq_u32 s6, 0x800000
	s_waitcnt vmcnt(7)
	v_cvt_f32_f16_sdwa v153, v170 dst_sel:DWORD dst_unused:UNUSED_PAD src0_sel:WORD_1
	v_cvt_f32_f16_e32 v152, v170
	v_pk_fma_f32 v[144:145], v[50:51], v[152:153], v[144:145]
	v_cvt_f32_f16_sdwa v51, v171 dst_sel:DWORD dst_unused:UNUSED_PAD src0_sel:WORD_1
	v_cvt_f32_f16_e32 v50, v171
	v_pk_fma_f32 v[146:147], v[52:53], v[50:51], v[146:147]
	v_cvt_f32_f16_sdwa v51, v172 dst_sel:DWORD dst_unused:UNUSED_PAD src0_sel:WORD_1
	v_cvt_f32_f16_e32 v50, v172
	v_pk_fma_f32 v[140:141], v[54:55], v[50:51], v[140:141]
	v_cvt_f32_f16_sdwa v51, v173 dst_sel:DWORD dst_unused:UNUSED_PAD src0_sel:WORD_1
	v_cvt_f32_f16_e32 v50, v173
	v_pk_fma_f32 v[142:143], v[56:57], v[50:51], v[142:143]
	s_waitcnt vmcnt(6)
	v_cvt_f32_f16_sdwa v55, v174 dst_sel:DWORD dst_unused:UNUSED_PAD src0_sel:WORD_1
	v_cvt_f32_f16_e32 v54, v174
	v_cvt_f32_f16_e32 v50, v176
	v_pk_fma_f32 v[136:137], v[58:59], v[54:55], v[136:137]
	v_cvt_f32_f16_sdwa v55, v175 dst_sel:DWORD dst_unused:UNUSED_PAD src0_sel:WORD_1
	v_cvt_f32_f16_e32 v54, v175
	v_cvt_f32_f16_sdwa v51, v176 dst_sel:DWORD dst_unused:UNUSED_PAD src0_sel:WORD_1
	v_pk_fma_f32 v[138:139], v[60:61], v[54:55], v[138:139]
	v_pk_fma_f32 v[134:135], v[62:63], v[50:51], v[134:135]
	v_cvt_f32_f16_sdwa v51, v177 dst_sel:DWORD dst_unused:UNUSED_PAD src0_sel:WORD_1
	v_cvt_f32_f16_e32 v50, v177
	v_pk_fma_f32 v[132:133], v[64:65], v[50:51], v[132:133]
	s_waitcnt vmcnt(5)
	v_cvt_f32_f16_sdwa v55, v178 dst_sel:DWORD dst_unused:UNUSED_PAD src0_sel:WORD_1
	v_cvt_f32_f16_e32 v54, v178
	v_pk_fma_f32 v[128:129], v[34:35], v[54:55], v[128:129]
	v_cvt_f32_f16_sdwa v35, v179 dst_sel:DWORD dst_unused:UNUSED_PAD src0_sel:WORD_1
	v_cvt_f32_f16_e32 v34, v179
	v_pk_fma_f32 v[130:131], v[36:37], v[34:35], v[130:131]
	v_cvt_f32_f16_sdwa v35, v180 dst_sel:DWORD dst_unused:UNUSED_PAD src0_sel:WORD_1
	v_cvt_f32_f16_e32 v34, v180
	v_pk_fma_f32 v[124:125], v[38:39], v[34:35], v[124:125]
	v_cvt_f32_f16_sdwa v35, v181 dst_sel:DWORD dst_unused:UNUSED_PAD src0_sel:WORD_1
	v_cvt_f32_f16_e32 v34, v181
	v_pk_fma_f32 v[126:127], v[40:41], v[34:35], v[126:127]
	s_waitcnt vmcnt(4)
	v_cvt_f32_f16_sdwa v39, v182 dst_sel:DWORD dst_unused:UNUSED_PAD src0_sel:WORD_1
	v_cvt_f32_f16_e32 v38, v182
	v_cvt_f32_f16_e32 v34, v184
	v_pk_fma_f32 v[120:121], v[42:43], v[38:39], v[120:121]
	v_cvt_f32_f16_sdwa v39, v183 dst_sel:DWORD dst_unused:UNUSED_PAD src0_sel:WORD_1
	v_cvt_f32_f16_e32 v38, v183
	v_cvt_f32_f16_sdwa v35, v184 dst_sel:DWORD dst_unused:UNUSED_PAD src0_sel:WORD_1
	v_pk_fma_f32 v[122:123], v[44:45], v[38:39], v[122:123]
	v_pk_fma_f32 v[118:119], v[46:47], v[34:35], v[118:119]
	v_cvt_f32_f16_sdwa v35, v185 dst_sel:DWORD dst_unused:UNUSED_PAD src0_sel:WORD_1
	v_cvt_f32_f16_e32 v34, v185
	v_pk_fma_f32 v[116:117], v[48:49], v[34:35], v[116:117]
	s_waitcnt vmcnt(3)
; DI float bflo(unsigned u) { return (float)__builtin_bit_cast(bf2_t, u)[0]; }
; DI float bfhi(unsigned u) { return (float)__builtin_bit_cast(bf2_t, u)[1]; }
; DI int TID() { int t = threadIdx.x; asm volatile("" : "+v"(t)); return t; }
; #define GEMM_GLOAD(P, kt_) { GEMM_GL1(P, 0, kt_) GEMM_GL1(P, 1, kt_) GEMM_GL1(P, 2, kt_) GEMM_GL1(P, 3, kt_) }
; #define GEMM_LSTORE(P, buf_) { GEMM_LS1(P, 0, buf_) GEMM_LS1(P, 1, buf_) GEMM_LS1(P, 2, buf_) GEMM_LS1(P, 3, buf_) }
; template <bool DEEP>
; DI void gemm_mainloop_t(const u16* __restrict__ Ag, int lda, const u16* __restrict__ Bg, int ldb, int K, char* ldsraw,
;                         f32x16 (&acc)[2][2], int akstep) {
;   const int tid = TID(), lane = tid & 63, w = tid >> 6, wm = w >> 1, wn = w & 1, r = lane & 31, h = lane >> 5;
;   u16* As = (u16*)ldsraw;
;   u16* Bs = As + 2 * 128 * LDT;
;   uint4 xa0, xa1, xa2, xa3, xb0, xb1, xb2, xb3;
;   const int nk = K >> 6;
;   const int row0 = tid >> 3, cc = tid & 7;
;   if (DEEP) {
;     uint4 ya0, ya1, ya2, ya3, yb0, yb1, yb2, yb3;
;     GEMM_GLOAD(x, 0);
;     GEMM_GLOAD(y, 1);
;     GEMM_LSTORE(x, 0);
;     __syncthreads();
; DI void phase4(const Params& p, int l, char* lds) {
;     ...
; #pragma unroll
;       for (int a = 0; a < 2; ++a)
; #pragma unroll
;         for (int b = 0; b < 2; ++b)
; #pragma unroll
;           for (int i = 0; i < 2; ++i) {
;             const uint4 o = scr[((a * 2 + b) * 2 + i) * 256];
;             mg[a][b][8 * i] += bflo(o.x) * acc[a][b][8 * i];
;             mg[a][b][8 * i + 1] += bfhi(o.x) * acc[a][b][8 * i + 1];
;             mg[a][b][8 * i + 2] += bflo(o.y) * acc[a][b][8 * i + 2];
;             mg[a][b][8 * i + 3] += bfhi(o.y) * acc[a][b][8 * i + 3];
;             mg[a][b][8 * i + 4] += bflo(o.z) * acc[a][b][8 * i + 4];
;             mg[a][b][8 * i + 5] += bfhi(o.z) * acc[a][b][8 * i + 5];
;             mg[a][b][8 * i + 6] += bflo(o.w) * acc[a][b][8 * i + 6];
;             mg[a][b][8 * i + 7] += bfhi(o.w) * acc[a][b][8 * i + 7];
;           }
	v_cvt_f32_f16_sdwa v39, v186 dst_sel:DWORD dst_unused:UNUSED_PAD src0_sel:WORD_1
	v_cvt_f32_f16_e32 v38, v186
	v_pk_fma_f32 v[112:113], v[18:19], v[38:39], v[112:113]
	v_cvt_f32_f16_sdwa v19, v187 dst_sel:DWORD dst_unused:UNUSED_PAD src0_sel:WORD_1
	v_cvt_f32_f16_e32 v18, v187
	v_pk_fma_f32 v[114:115], v[20:21], v[18:19], v[114:115]
	v_cvt_f32_f16_sdwa v19, v188 dst_sel:DWORD dst_unused:UNUSED_PAD src0_sel:WORD_1
	v_cvt_f32_f16_e32 v18, v188
	v_pk_fma_f32 v[108:109], v[22:23], v[18:19], v[108:109]
	v_cvt_f32_f16_sdwa v19, v189 dst_sel:DWORD dst_unused:UNUSED_PAD src0_sel:WORD_1
	v_cvt_f32_f16_e32 v18, v189
	v_pk_fma_f32 v[110:111], v[24:25], v[18:19], v[110:111]
	s_waitcnt vmcnt(2)
	v_cvt_f32_f16_sdwa v23, v190 dst_sel:DWORD dst_unused:UNUSED_PAD src0_sel:WORD_1
	v_cvt_f32_f16_e32 v22, v190
	v_cvt_f32_f16_e32 v18, v192
	v_pk_fma_f32 v[104:105], v[26:27], v[22:23], v[104:105]
	v_cvt_f32_f16_sdwa v23, v191 dst_sel:DWORD dst_unused:UNUSED_PAD src0_sel:WORD_1
	v_cvt_f32_f16_e32 v22, v191
	v_cvt_f32_f16_sdwa v19, v192 dst_sel:DWORD dst_unused:UNUSED_PAD src0_sel:WORD_1
	v_pk_fma_f32 v[106:107], v[28:29], v[22:23], v[106:107]
	v_pk_fma_f32 v[102:103], v[30:31], v[18:19], v[102:103]
	v_cvt_f32_f16_sdwa v19, v193 dst_sel:DWORD dst_unused:UNUSED_PAD src0_sel:WORD_1
	v_cvt_f32_f16_e32 v18, v193
	v_pk_fma_f32 v[100:101], v[32:33], v[18:19], v[100:101]
	s_waitcnt vmcnt(1)
	v_cvt_f32_f16_sdwa v23, v194 dst_sel:DWORD dst_unused:UNUSED_PAD src0_sel:WORD_1
	v_cvt_f32_f16_e32 v22, v194
	v_pk_fma_f32 v[96:97], v[2:3], v[22:23], v[96:97]
	v_cvt_f32_f16_sdwa v3, v195 dst_sel:DWORD dst_unused:UNUSED_PAD src0_sel:WORD_1
	v_cvt_f32_f16_e32 v2, v195
	v_pk_fma_f32 v[98:99], v[4:5], v[2:3], v[98:99]
	v_cvt_f32_f16_sdwa v3, v196 dst_sel:DWORD dst_unused:UNUSED_PAD src0_sel:WORD_1
	v_cvt_f32_f16_e32 v2, v196
	v_pk_fma_f32 v[92:93], v[6:7], v[2:3], v[92:93]
	v_cvt_f32_f16_sdwa v3, v197 dst_sel:DWORD dst_unused:UNUSED_PAD src0_sel:WORD_1
	v_cvt_f32_f16_e32 v2, v197
	v_pk_fma_f32 v[94:95], v[8:9], v[2:3], v[94:95]
	s_waitcnt vmcnt(0)
	v_cvt_f32_f16_sdwa v7, v198 dst_sel:DWORD dst_unused:UNUSED_PAD src0_sel:WORD_1
	v_cvt_f32_f16_e32 v6, v198
	v_cvt_f32_f16_e32 v2, v200
	v_pk_fma_f32 v[88:89], v[10:11], v[6:7], v[88:89]
	v_cvt_f32_f16_sdwa v7, v199 dst_sel:DWORD dst_unused:UNUSED_PAD src0_sel:WORD_1
	v_cvt_f32_f16_e32 v6, v199
	v_cvt_f32_f16_sdwa v3, v200 dst_sel:DWORD dst_unused:UNUSED_PAD src0_sel:WORD_1
	v_pk_fma_f32 v[90:91], v[12:13], v[6:7], v[90:91]
	v_pk_fma_f32 v[86:87], v[14:15], v[2:3], v[86:87]
	v_cvt_f32_f16_sdwa v3, v201 dst_sel:DWORD dst_unused:UNUSED_PAD src0_sel:WORD_1
	v_cvt_f32_f16_e32 v2, v201
	v_pk_fma_f32 v[84:85], v[16:17], v[2:3], v[84:85]
	s_cbranch_scc1 .LBB0_1052
.LBB0_1055:
	s_waitcnt vmcnt(31)
	s_add_u32 s8, s18, s6
	s_addc_u32 s9, s19, s7
	v_lshrrev_b32_e32 v244, 3, v209
	v_and_b32_e32 v245, 7, v209
	v_lshlrev_b32_e32 v245, 4, v245
	v_mov_b32_e32 v246, v244
	v_mul_u32_u24_e32 v206, 0x800, v246
	v_add_u32_e32 v206, v206, v245
	v_mul_u32_u24_e32 v248, 0x800, v246
	v_add_u32_e32 v248, v248, v245
	v_add_u32_e32 v246, 32, v244
	v_mul_u32_u24_e32 v207, 0x800, v246
	v_add_u32_e32 v207, v207, v245
	v_mul_u32_u24_e32 v249, 0x800, v246
	v_add_u32_e32 v249, v249, v245
	v_add_u32_e32 v246, 64, v244
	v_mul_u32_u24_e32 v208, 0x800, v246
	v_add_u32_e32 v208, v208, v245
	v_mul_u32_u24_e32 v250, 0x800, v246
	v_add_u32_e32 v250, v250, v245
	v_add_u32_e32 v246, 96, v244
	v_mul_u32_u24_e32 v226, 0x800, v246
	v_add_u32_e32 v226, v226, v245
	v_mul_u32_u24_e32 v169, 0x800, v246
	v_add_u32_e32 v169, v169, v245
	v_mul_u32_u24_e32 v150, 0x90, v244
	v_add_u32_e32 v150, v150, v245
	v_add_u32_e32 v151, 0x1200, v150
	v_and_b32_e32 v244, 31, v209
	v_bfe_u32 v245, v209, 5, 1
	v_lshlrev_b32_e32 v245, 4, v245
	v_bfe_u32 v246, v209, 7, 1
	v_lshl_add_u32 v246, v246, 6, v244
	v_mul_u32_u24_e32 v148, 0x90, v246
	v_add_u32_e32 v148, v148, v245
	v_bfe_u32 v246, v209, 6, 1
	v_lshl_add_u32 v246, v246, 6, v244
	v_mul_u32_u24_e32 v0, 0x90, v246
	v_add_u32_e32 v0, v0, v245
	global_load_dwordx4 v[170:173], v206, s[4:5]
	global_load_dwordx4 v[174:177], v248, s[8:9]
	global_load_dwordx4 v[178:181], v207, s[4:5]
	global_load_dwordx4 v[182:185], v249, s[8:9]
	global_load_dwordx4 v[186:189], v208, s[4:5]
	global_load_dwordx4 v[190:193], v250, s[8:9]
	global_load_dwordx4 v[194:197], v226, s[4:5]
	global_load_dwordx4 v[198:201], v169, s[8:9]
	global_load_dwordx4 v[152:155], v206, s[4:5] offset:128
	global_load_dwordx4 v[228:231], v248, s[8:9] offset:128
	global_load_dwordx4 v[156:159], v207, s[4:5] offset:128
	global_load_dwordx4 v[232:235], v249, s[8:9] offset:128
	global_load_dwordx4 v[160:163], v208, s[4:5] offset:128
	global_load_dwordx4 v[236:239], v250, s[8:9] offset:128
	global_load_dwordx4 v[164:167], v226, s[4:5] offset:128
	global_load_dwordx4 v[240:243], v169, s[8:9] offset:128
	s_waitcnt vmcnt(15)
	ds_write_b128 v150, v[170:173]
	s_waitcnt vmcnt(14)
	ds_write_b128 v150, v[174:177] offset:36864
	s_waitcnt vmcnt(13)
	ds_write_b128 v150, v[178:181] offset:4608
	s_waitcnt vmcnt(12)
	ds_write_b128 v150, v[182:185] offset:41472
	s_waitcnt vmcnt(11)
	ds_write_b128 v150, v[186:189] offset:9216
	s_waitcnt vmcnt(10)
	ds_write_b128 v150, v[190:193] offset:46080
	s_waitcnt vmcnt(9)
	ds_write_b128 v150, v[194:197] offset:13824
	s_waitcnt vmcnt(8)
	ds_write_b128 v150, v[198:201] offset:50688
	s_waitcnt lgkmcnt(0)
	s_barrier
; #define GEMM_GLOAD(P, kt_) { GEMM_GL1(P, 0, kt_) GEMM_GL1(P, 1, kt_) GEMM_GL1(P, 2, kt_) GEMM_GL1(P, 3, kt_) }
; #define GEMM_LSTORE(P, buf_) { GEMM_LS1(P, 0, buf_) GEMM_LS1(P, 1, buf_) GEMM_LS1(P, 2, buf_) GEMM_LS1(P, 3, buf_) }
; template <bool DEEP>
; DI void gemm_mainloop_t(const u16* __restrict__ Ag, int lda, const u16* __restrict__ Bg, int ldb, int K, char* ldsraw,
;                         f32x16 (&acc)[2][2], int akstep) {
;     ...
;     for (int kt = 0; kt < nk; kt += 2) {
;       if (kt + 2 < nk) GEMM_GLOAD(x, kt + 2);
;       GEMM_COMPUTE(0);
;       GEMM_LSTORE(y, 1);
;       __syncthreads();
;       if (kt + 3 < nk) GEMM_GLOAD(y, kt + 3);
;       GEMM_COMPUTE(1);
;       if (kt + 2 < nk) GEMM_LSTORE(x, 0);
;       __syncthreads();
;     }
	s_setprio 1
	ds_read_b128 v[212:215], v0 offset:36864
	ds_read_b128 v[216:219], v148
	ds_read_b128 v[202:205], v0 offset:41472
	ds_read_b128 v[244:247], v148 offset:4608
	s_waitcnt lgkmcnt(2)
	v_mfma_f32_32x32x16_f16 v[50:65], v[212:215], v[216:219], 0
	global_load_dwordx4 v[170:173], v206, s[4:5] offset:256
	s_waitcnt lgkmcnt(1)
	v_mfma_f32_32x32x16_f16 v[34:49], v[202:205], v[216:219], 0
	ds_read_b128 v[216:219], v148 offset:32
	s_waitcnt vmcnt(8)
	ds_write_b128 v150, v[152:155] offset:18432
	s_waitcnt lgkmcnt(2)
	v_mfma_f32_32x32x16_f16 v[18:33], v[212:215], v[244:247], 0
	ds_read_b128 v[212:215], v0 offset:36896
	global_load_dwordx4 v[174:177], v248, s[8:9] offset:256
	v_mfma_f32_32x32x16_f16 v[2:17], v[202:205], v[244:247], 0
	ds_read_b128 v[202:205], v0 offset:41504
	ds_read_b128 v[244:247], v148 offset:4640
	s_waitcnt vmcnt(8)
	ds_write_b128 v150, v[228:231] offset:55296
	s_waitcnt lgkmcnt(3)
	v_mfma_f32_32x32x16_f16 v[50:65], v[212:215], v[216:219], v[50:65]
	global_load_dwordx4 v[178:181], v207, s[4:5] offset:256
	s_waitcnt lgkmcnt(2)
	v_mfma_f32_32x32x16_f16 v[34:49], v[202:205], v[216:219], v[34:49]
	ds_read_b128 v[216:219], v148 offset:64
	s_waitcnt vmcnt(8)
	ds_write_b128 v150, v[156:159] offset:23040
	s_waitcnt lgkmcnt(3)
	v_mfma_f32_32x32x16_f16 v[18:33], v[212:215], v[244:247], v[18:33]
	ds_read_b128 v[212:215], v0 offset:36928
	global_load_dwordx4 v[182:185], v249, s[8:9] offset:256
	v_mfma_f32_32x32x16_f16 v[2:17], v[202:205], v[244:247], v[2:17]
	ds_read_b128 v[202:205], v0 offset:41536
	ds_read_b128 v[244:247], v148 offset:4672
	s_waitcnt vmcnt(8)
	ds_write_b128 v150, v[232:235] offset:59904
	s_waitcnt lgkmcnt(3)
	v_mfma_f32_32x32x16_f16 v[50:65], v[212:215], v[216:219], v[50:65]
	global_load_dwordx4 v[186:189], v208, s[4:5] offset:256
	s_waitcnt lgkmcnt(2)
	v_mfma_f32_32x32x16_f16 v[34:49], v[202:205], v[216:219], v[34:49]
	ds_read_b128 v[216:219], v148 offset:96
	s_waitcnt vmcnt(8)
	ds_write_b128 v150, v[160:163] offset:27648
	s_waitcnt lgkmcnt(3)
	v_mfma_f32_32x32x16_f16 v[18:33], v[212:215], v[244:247], v[18:33]
	ds_read_b128 v[212:215], v0 offset:36960
	global_load_dwordx4 v[190:193], v250, s[8:9] offset:256
	v_mfma_f32_32x32x16_f16 v[2:17], v[202:205], v[244:247], v[2:17]
	ds_read_b128 v[202:205], v0 offset:41568
	ds_read_b128 v[244:247], v148 offset:4704
	s_waitcnt vmcnt(8)
	ds_write_b128 v150, v[236:239] offset:64512
	s_waitcnt lgkmcnt(3)
	v_mfma_f32_32x32x16_f16 v[50:65], v[212:215], v[216:219], v[50:65]
	global_load_dwordx4 v[194:197], v226, s[4:5] offset:256
	s_waitcnt lgkmcnt(2)
	v_mfma_f32_32x32x16_f16 v[34:49], v[202:205], v[216:219], v[34:49]
	s_waitcnt vmcnt(8)
	ds_write_b128 v150, v[164:167] offset:32256
	s_waitcnt lgkmcnt(2)
	v_mfma_f32_32x32x16_f16 v[18:33], v[212:215], v[244:247], v[18:33]
	global_load_dwordx4 v[198:201], v169, s[8:9] offset:256
	v_mfma_f32_32x32x16_f16 v[2:17], v[202:205], v[244:247], v[2:17]
	s_waitcnt vmcnt(8)
	ds_write_b128 v151, v[240:243] offset:64512
	s_setprio 0
	s_waitcnt lgkmcnt(0)
	s_barrier
	s_setprio 1
	ds_read_b128 v[212:215], v0 offset:55296
	ds_read_b128 v[216:219], v148 offset:18432
	ds_read_b128 v[202:205], v0 offset:59904
	ds_read_b128 v[244:247], v148 offset:23040
	s_waitcnt lgkmcnt(2)
	v_mfma_f32_32x32x16_f16 v[50:65], v[212:215], v[216:219], v[50:65]
	global_load_dwordx4 v[152:155], v206, s[4:5] offset:384
	s_waitcnt lgkmcnt(1)
	v_mfma_f32_32x32x16_f16 v[34:49], v[202:205], v[216:219], v[34:49]
	ds_read_b128 v[216:219], v148 offset:18464
	s_waitcnt vmcnt(8)
	ds_write_b128 v150, v[170:173]
	s_waitcnt lgkmcnt(2)
	v_mfma_f32_32x32x16_f16 v[18:33], v[212:215], v[244:247], v[18:33]
	ds_read_b128 v[212:215], v0 offset:55328
	global_load_dwordx4 v[228:231], v248, s[8:9] offset:384
	v_mfma_f32_32x32x16_f16 v[2:17], v[202:205], v[244:247], v[2:17]
	ds_read_b128 v[202:205], v0 offset:59936
	ds_read_b128 v[244:247], v148 offset:23072
	s_waitcnt vmcnt(8)
	ds_write_b128 v150, v[174:177] offset:36864
	s_waitcnt lgkmcnt(3)
	v_mfma_f32_32x32x16_f16 v[50:65], v[212:215], v[216:219], v[50:65]
	global_load_dwordx4 v[156:159], v207, s[4:5] offset:384
	s_waitcnt lgkmcnt(2)
	v_mfma_f32_32x32x16_f16 v[34:49], v[202:205], v[216:219], v[34:49]
	ds_read_b128 v[216:219], v148 offset:18496
	s_waitcnt vmcnt(8)
	ds_write_b128 v150, v[178:181] offset:4608
	s_waitcnt lgkmcnt(3)
	v_mfma_f32_32x32x16_f16 v[18:33], v[212:215], v[244:247], v[18:33]
	ds_read_b128 v[212:215], v0 offset:55360
	global_load_dwordx4 v[232:235], v249, s[8:9] offset:384
	v_mfma_f32_32x32x16_f16 v[2:17], v[202:205], v[244:247], v[2:17]
	ds_read_b128 v[202:205], v0 offset:59968
	ds_read_b128 v[244:247], v148 offset:23104
	s_waitcnt vmcnt(8)
	ds_write_b128 v150, v[182:185] offset:41472
	s_waitcnt lgkmcnt(3)
	v_mfma_f32_32x32x16_f16 v[50:65], v[212:215], v[216:219], v[50:65]
	global_load_dwordx4 v[160:163], v208, s[4:5] offset:384
	s_waitcnt lgkmcnt(2)
	v_mfma_f32_32x32x16_f16 v[34:49], v[202:205], v[216:219], v[34:49]
	ds_read_b128 v[216:219], v148 offset:18528
	s_waitcnt vmcnt(8)
	ds_write_b128 v150, v[186:189] offset:9216
	s_waitcnt lgkmcnt(3)
	v_mfma_f32_32x32x16_f16 v[18:33], v[212:215], v[244:247], v[18:33]
	ds_read_b128 v[212:215], v0 offset:55392
	global_load_dwordx4 v[236:239], v250, s[8:9] offset:384
	v_mfma_f32_32x32x16_f16 v[2:17], v[202:205], v[244:247], v[2:17]
	ds_read_b128 v[202:205], v0 offset:60000
	ds_read_b128 v[244:247], v148 offset:23136
	s_waitcnt vmcnt(8)
	ds_write_b128 v150, v[190:193] offset:46080
	s_waitcnt lgkmcnt(3)
	v_mfma_f32_32x32x16_f16 v[50:65], v[212:215], v[216:219], v[50:65]
	global_load_dwordx4 v[164:167], v226, s[4:5] offset:384
	s_waitcnt lgkmcnt(2)
	v_mfma_f32_32x32x16_f16 v[34:49], v[202:205], v[216:219], v[34:49]
	s_waitcnt vmcnt(8)
	ds_write_b128 v150, v[194:197] offset:13824
	s_waitcnt lgkmcnt(2)
	v_mfma_f32_32x32x16_f16 v[18:33], v[212:215], v[244:247], v[18:33]
	global_load_dwordx4 v[240:243], v169, s[8:9] offset:384
	v_mfma_f32_32x32x16_f16 v[2:17], v[202:205], v[244:247], v[2:17]
	s_waitcnt vmcnt(8)
	ds_write_b128 v150, v[198:201] offset:50688
	s_setprio 0
	s_waitcnt lgkmcnt(0)
	s_barrier
; #define GEMM_GLOAD(P, kt_) { GEMM_GL1(P, 0, kt_) GEMM_GL1(P, 1, kt_) GEMM_GL1(P, 2, kt_) GEMM_GL1(P, 3, kt_) }
; #define GEMM_LSTORE(P, buf_) { GEMM_LS1(P, 0, buf_) GEMM_LS1(P, 1, buf_) GEMM_LS1(P, 2, buf_) GEMM_LS1(P, 3, buf_) }
; template <bool DEEP>
; DI void gemm_mainloop_t(const u16* __restrict__ Ag, int lda, const u16* __restrict__ Bg, int ldb, int K, char* ldsraw,
;                         f32x16 (&acc)[2][2], int akstep) {
;     ...
;     for (int kt = 0; kt < nk; kt += 2) {
;       if (kt + 2 < nk) GEMM_GLOAD(x, kt + 2);
;       GEMM_COMPUTE(0);
;       GEMM_LSTORE(y, 1);
;       __syncthreads();
;       if (kt + 3 < nk) GEMM_GLOAD(y, kt + 3);
;       GEMM_COMPUTE(1);
;       if (kt + 2 < nk) GEMM_LSTORE(x, 0);
;       __syncthreads();
;     }
	s_setprio 1
	ds_read_b128 v[212:215], v0 offset:36864
	ds_read_b128 v[216:219], v148
	ds_read_b128 v[202:205], v0 offset:41472
	ds_read_b128 v[244:247], v148 offset:4608
	s_waitcnt lgkmcnt(2)
	v_mfma_f32_32x32x16_f16 v[50:65], v[212:215], v[216:219], v[50:65]
	global_load_dwordx4 v[170:173], v206, s[4:5] offset:512
	s_waitcnt lgkmcnt(1)
	v_mfma_f32_32x32x16_f16 v[34:49], v[202:205], v[216:219], v[34:49]
	ds_read_b128 v[216:219], v148 offset:32
	s_waitcnt vmcnt(8)
	ds_write_b128 v150, v[152:155] offset:18432
	s_waitcnt lgkmcnt(2)
	v_mfma_f32_32x32x16_f16 v[18:33], v[212:215], v[244:247], v[18:33]
	ds_read_b128 v[212:215], v0 offset:36896
	global_load_dwordx4 v[174:177], v248, s[8:9] offset:512
	v_mfma_f32_32x32x16_f16 v[2:17], v[202:205], v[244:247], v[2:17]
	ds_read_b128 v[202:205], v0 offset:41504
	ds_read_b128 v[244:247], v148 offset:4640
	s_waitcnt vmcnt(8)
	ds_write_b128 v150, v[228:231] offset:55296
	s_waitcnt lgkmcnt(3)
	v_mfma_f32_32x32x16_f16 v[50:65], v[212:215], v[216:219], v[50:65]
	global_load_dwordx4 v[178:181], v207, s[4:5] offset:512
	s_waitcnt lgkmcnt(2)
	v_mfma_f32_32x32x16_f16 v[34:49], v[202:205], v[216:219], v[34:49]
	ds_read_b128 v[216:219], v148 offset:64
	s_waitcnt vmcnt(8)
	ds_write_b128 v150, v[156:159] offset:23040
	s_waitcnt lgkmcnt(3)
	v_mfma_f32_32x32x16_f16 v[18:33], v[212:215], v[244:247], v[18:33]
	ds_read_b128 v[212:215], v0 offset:36928
	global_load_dwordx4 v[182:185], v249, s[8:9] offset:512
	v_mfma_f32_32x32x16_f16 v[2:17], v[202:205], v[244:247], v[2:17]
	ds_read_b128 v[202:205], v0 offset:41536
	ds_read_b128 v[244:247], v148 offset:4672
	s_waitcnt vmcnt(8)
	ds_write_b128 v150, v[232:235] offset:59904
	s_waitcnt lgkmcnt(3)
	v_mfma_f32_32x32x16_f16 v[50:65], v[212:215], v[216:219], v[50:65]
	global_load_dwordx4 v[186:189], v208, s[4:5] offset:512
	s_waitcnt lgkmcnt(2)
	v_mfma_f32_32x32x16_f16 v[34:49], v[202:205], v[216:219], v[34:49]
	ds_read_b128 v[216:219], v148 offset:96
	s_waitcnt vmcnt(8)
	ds_write_b128 v150, v[160:163] offset:27648
	s_waitcnt lgkmcnt(3)
	v_mfma_f32_32x32x16_f16 v[18:33], v[212:215], v[244:247], v[18:33]
	ds_read_b128 v[212:215], v0 offset:36960
	global_load_dwordx4 v[190:193], v250, s[8:9] offset:512
	v_mfma_f32_32x32x16_f16 v[2:17], v[202:205], v[244:247], v[2:17]
	ds_read_b128 v[202:205], v0 offset:41568
	ds_read_b128 v[244:247], v148 offset:4704
	s_waitcnt vmcnt(8)
	ds_write_b128 v150, v[236:239] offset:64512
	s_waitcnt lgkmcnt(3)
	v_mfma_f32_32x32x16_f16 v[50:65], v[212:215], v[216:219], v[50:65]
	global_load_dwordx4 v[194:197], v226, s[4:5] offset:512
	s_waitcnt lgkmcnt(2)
	v_mfma_f32_32x32x16_f16 v[34:49], v[202:205], v[216:219], v[34:49]
	s_waitcnt vmcnt(8)
	ds_write_b128 v150, v[164:167] offset:32256
	s_waitcnt lgkmcnt(2)
	v_mfma_f32_32x32x16_f16 v[18:33], v[212:215], v[244:247], v[18:33]
	global_load_dwordx4 v[198:201], v169, s[8:9] offset:512
	v_mfma_f32_32x32x16_f16 v[2:17], v[202:205], v[244:247], v[2:17]
	s_waitcnt vmcnt(8)
	ds_write_b128 v151, v[240:243] offset:64512
	s_setprio 0
	s_waitcnt lgkmcnt(0)
	s_barrier
	s_setprio 1
	ds_read_b128 v[212:215], v0 offset:55296
	ds_read_b128 v[216:219], v148 offset:18432
	ds_read_b128 v[202:205], v0 offset:59904
	ds_read_b128 v[244:247], v148 offset:23040
	s_waitcnt lgkmcnt(2)
	v_mfma_f32_32x32x16_f16 v[50:65], v[212:215], v[216:219], v[50:65]
	global_load_dwordx4 v[152:155], v206, s[4:5] offset:640
	s_waitcnt lgkmcnt(1)
	v_mfma_f32_32x32x16_f16 v[34:49], v[202:205], v[216:219], v[34:49]
	ds_read_b128 v[216:219], v148 offset:18464
	s_waitcnt vmcnt(8)
	ds_write_b128 v150, v[170:173]
	s_waitcnt lgkmcnt(2)
	v_mfma_f32_32x32x16_f16 v[18:33], v[212:215], v[244:247], v[18:33]
	ds_read_b128 v[212:215], v0 offset:55328
	global_load_dwordx4 v[228:231], v248, s[8:9] offset:640
	v_mfma_f32_32x32x16_f16 v[2:17], v[202:205], v[244:247], v[2:17]
	ds_read_b128 v[202:205], v0 offset:59936
	ds_read_b128 v[244:247], v148 offset:23072
	s_waitcnt vmcnt(8)
	ds_write_b128 v150, v[174:177] offset:36864
	s_waitcnt lgkmcnt(3)
	v_mfma_f32_32x32x16_f16 v[50:65], v[212:215], v[216:219], v[50:65]
	global_load_dwordx4 v[156:159], v207, s[4:5] offset:640
	s_waitcnt lgkmcnt(2)
	v_mfma_f32_32x32x16_f16 v[34:49], v[202:205], v[216:219], v[34:49]
	ds_read_b128 v[216:219], v148 offset:18496
	s_waitcnt vmcnt(8)
	ds_write_b128 v150, v[178:181] offset:4608
	s_waitcnt lgkmcnt(3)
	v_mfma_f32_32x32x16_f16 v[18:33], v[212:215], v[244:247], v[18:33]
	ds_read_b128 v[212:215], v0 offset:55360
	global_load_dwordx4 v[232:235], v249, s[8:9] offset:640
	v_mfma_f32_32x32x16_f16 v[2:17], v[202:205], v[244:247], v[2:17]
	ds_read_b128 v[202:205], v0 offset:59968
	ds_read_b128 v[244:247], v148 offset:23104
	s_waitcnt vmcnt(8)
	ds_write_b128 v150, v[182:185] offset:41472
	s_waitcnt lgkmcnt(3)
	v_mfma_f32_32x32x16_f16 v[50:65], v[212:215], v[216:219], v[50:65]
	global_load_dwordx4 v[160:163], v208, s[4:5] offset:640
	s_waitcnt lgkmcnt(2)
	v_mfma_f32_32x32x16_f16 v[34:49], v[202:205], v[216:219], v[34:49]
	ds_read_b128 v[216:219], v148 offset:18528
	s_waitcnt vmcnt(8)
	ds_write_b128 v150, v[186:189] offset:9216
	s_waitcnt lgkmcnt(3)
	v_mfma_f32_32x32x16_f16 v[18:33], v[212:215], v[244:247], v[18:33]
	ds_read_b128 v[212:215], v0 offset:55392
	global_load_dwordx4 v[236:239], v250, s[8:9] offset:640
	v_mfma_f32_32x32x16_f16 v[2:17], v[202:205], v[244:247], v[2:17]
	ds_read_b128 v[202:205], v0 offset:60000
	ds_read_b128 v[244:247], v148 offset:23136
	s_waitcnt vmcnt(8)
	ds_write_b128 v150, v[190:193] offset:46080
	s_waitcnt lgkmcnt(3)
	v_mfma_f32_32x32x16_f16 v[50:65], v[212:215], v[216:219], v[50:65]
	global_load_dwordx4 v[164:167], v226, s[4:5] offset:640
	s_waitcnt lgkmcnt(2)
	v_mfma_f32_32x32x16_f16 v[34:49], v[202:205], v[216:219], v[34:49]
	s_waitcnt vmcnt(8)
	ds_write_b128 v150, v[194:197] offset:13824
	s_waitcnt lgkmcnt(2)
	v_mfma_f32_32x32x16_f16 v[18:33], v[212:215], v[244:247], v[18:33]
	global_load_dwordx4 v[240:243], v169, s[8:9] offset:640
	v_mfma_f32_32x32x16_f16 v[2:17], v[202:205], v[244:247], v[2:17]
	s_waitcnt vmcnt(8)
	ds_write_b128 v150, v[198:201] offset:50688
	s_setprio 0
	s_waitcnt lgkmcnt(0)
	s_barrier
; #define GEMM_GLOAD(P, kt_) { GEMM_GL1(P, 0, kt_) GEMM_GL1(P, 1, kt_) GEMM_GL1(P, 2, kt_) GEMM_GL1(P, 3, kt_) }
; #define GEMM_LSTORE(P, buf_) { GEMM_LS1(P, 0, buf_) GEMM_LS1(P, 1, buf_) GEMM_LS1(P, 2, buf_) GEMM_LS1(P, 3, buf_) }
; template <bool DEEP>
; DI void gemm_mainloop_t(const u16* __restrict__ Ag, int lda, const u16* __restrict__ Bg, int ldb, int K, char* ldsraw,
;                         f32x16 (&acc)[2][2], int akstep) {
;     ...
;     for (int kt = 0; kt < nk; kt += 2) {
;       if (kt + 2 < nk) GEMM_GLOAD(x, kt + 2);
;       GEMM_COMPUTE(0);
;       GEMM_LSTORE(y, 1);
;       __syncthreads();
;       if (kt + 3 < nk) GEMM_GLOAD(y, kt + 3);
;       GEMM_COMPUTE(1);
;       if (kt + 2 < nk) GEMM_LSTORE(x, 0);
;       __syncthreads();
;     }
	s_setprio 1
	ds_read_b128 v[212:215], v0 offset:36864
	ds_read_b128 v[216:219], v148
	ds_read_b128 v[202:205], v0 offset:41472
	ds_read_b128 v[244:247], v148 offset:4608
	s_waitcnt lgkmcnt(2)
	v_mfma_f32_32x32x16_f16 v[50:65], v[212:215], v[216:219], v[50:65]
	global_load_dwordx4 v[170:173], v206, s[4:5] offset:768
	s_waitcnt lgkmcnt(1)
	v_mfma_f32_32x32x16_f16 v[34:49], v[202:205], v[216:219], v[34:49]
	ds_read_b128 v[216:219], v148 offset:32
	s_waitcnt vmcnt(8)
	ds_write_b128 v150, v[152:155] offset:18432
	s_waitcnt lgkmcnt(2)
	v_mfma_f32_32x32x16_f16 v[18:33], v[212:215], v[244:247], v[18:33]
	ds_read_b128 v[212:215], v0 offset:36896
	global_load_dwordx4 v[174:177], v248, s[8:9] offset:768
	v_mfma_f32_32x32x16_f16 v[2:17], v[202:205], v[244:247], v[2:17]
	ds_read_b128 v[202:205], v0 offset:41504
	ds_read_b128 v[244:247], v148 offset:4640
	s_waitcnt vmcnt(8)
	ds_write_b128 v150, v[228:231] offset:55296
	s_waitcnt lgkmcnt(3)
	v_mfma_f32_32x32x16_f16 v[50:65], v[212:215], v[216:219], v[50:65]
	global_load_dwordx4 v[178:181], v207, s[4:5] offset:768
	s_waitcnt lgkmcnt(2)
	v_mfma_f32_32x32x16_f16 v[34:49], v[202:205], v[216:219], v[34:49]
	ds_read_b128 v[216:219], v148 offset:64
	s_waitcnt vmcnt(8)
	ds_write_b128 v150, v[156:159] offset:23040
	s_waitcnt lgkmcnt(3)
	v_mfma_f32_32x32x16_f16 v[18:33], v[212:215], v[244:247], v[18:33]
	ds_read_b128 v[212:215], v0 offset:36928
	global_load_dwordx4 v[182:185], v249, s[8:9] offset:768
	v_mfma_f32_32x32x16_f16 v[2:17], v[202:205], v[244:247], v[2:17]
	ds_read_b128 v[202:205], v0 offset:41536
	ds_read_b128 v[244:247], v148 offset:4672
	s_waitcnt vmcnt(8)
	ds_write_b128 v150, v[232:235] offset:59904
	s_waitcnt lgkmcnt(3)
	v_mfma_f32_32x32x16_f16 v[50:65], v[212:215], v[216:219], v[50:65]
	global_load_dwordx4 v[186:189], v208, s[4:5] offset:768
	s_waitcnt lgkmcnt(2)
	v_mfma_f32_32x32x16_f16 v[34:49], v[202:205], v[216:219], v[34:49]
	ds_read_b128 v[216:219], v148 offset:96
	s_waitcnt vmcnt(8)
	ds_write_b128 v150, v[160:163] offset:27648
	s_waitcnt lgkmcnt(3)
	v_mfma_f32_32x32x16_f16 v[18:33], v[212:215], v[244:247], v[18:33]
	ds_read_b128 v[212:215], v0 offset:36960
	global_load_dwordx4 v[190:193], v250, s[8:9] offset:768
	v_mfma_f32_32x32x16_f16 v[2:17], v[202:205], v[244:247], v[2:17]
	ds_read_b128 v[202:205], v0 offset:41568
	ds_read_b128 v[244:247], v148 offset:4704
	s_waitcnt vmcnt(8)
	ds_write_b128 v150, v[236:239] offset:64512
	s_waitcnt lgkmcnt(3)
	v_mfma_f32_32x32x16_f16 v[50:65], v[212:215], v[216:219], v[50:65]
	global_load_dwordx4 v[194:197], v226, s[4:5] offset:768
	s_waitcnt lgkmcnt(2)
	v_mfma_f32_32x32x16_f16 v[34:49], v[202:205], v[216:219], v[34:49]
	s_waitcnt vmcnt(8)
	ds_write_b128 v150, v[164:167] offset:32256
	s_waitcnt lgkmcnt(2)
	v_mfma_f32_32x32x16_f16 v[18:33], v[212:215], v[244:247], v[18:33]
	global_load_dwordx4 v[198:201], v169, s[8:9] offset:768
	v_mfma_f32_32x32x16_f16 v[2:17], v[202:205], v[244:247], v[2:17]
	s_waitcnt vmcnt(8)
	ds_write_b128 v151, v[240:243] offset:64512
	s_setprio 0
	s_waitcnt lgkmcnt(0)
	s_barrier
	s_setprio 1
	ds_read_b128 v[212:215], v0 offset:55296
	ds_read_b128 v[216:219], v148 offset:18432
	ds_read_b128 v[202:205], v0 offset:59904
	ds_read_b128 v[244:247], v148 offset:23040
	s_waitcnt lgkmcnt(2)
	v_mfma_f32_32x32x16_f16 v[50:65], v[212:215], v[216:219], v[50:65]
	global_load_dwordx4 v[152:155], v206, s[4:5] offset:896
	s_waitcnt lgkmcnt(1)
	v_mfma_f32_32x32x16_f16 v[34:49], v[202:205], v[216:219], v[34:49]
	ds_read_b128 v[216:219], v148 offset:18464
	s_waitcnt vmcnt(8)
	ds_write_b128 v150, v[170:173]
	s_waitcnt lgkmcnt(2)
	v_mfma_f32_32x32x16_f16 v[18:33], v[212:215], v[244:247], v[18:33]
	ds_read_b128 v[212:215], v0 offset:55328
	global_load_dwordx4 v[228:231], v248, s[8:9] offset:896
	v_mfma_f32_32x32x16_f16 v[2:17], v[202:205], v[244:247], v[2:17]
	ds_read_b128 v[202:205], v0 offset:59936
	ds_read_b128 v[244:247], v148 offset:23072
	s_waitcnt vmcnt(8)
	ds_write_b128 v150, v[174:177] offset:36864
	s_waitcnt lgkmcnt(3)
	v_mfma_f32_32x32x16_f16 v[50:65], v[212:215], v[216:219], v[50:65]
	global_load_dwordx4 v[156:159], v207, s[4:5] offset:896
	s_waitcnt lgkmcnt(2)
	v_mfma_f32_32x32x16_f16 v[34:49], v[202:205], v[216:219], v[34:49]
	ds_read_b128 v[216:219], v148 offset:18496
	s_waitcnt vmcnt(8)
	ds_write_b128 v150, v[178:181] offset:4608
	s_waitcnt lgkmcnt(3)
	v_mfma_f32_32x32x16_f16 v[18:33], v[212:215], v[244:247], v[18:33]
	ds_read_b128 v[212:215], v0 offset:55360
	global_load_dwordx4 v[232:235], v249, s[8:9] offset:896
	v_mfma_f32_32x32x16_f16 v[2:17], v[202:205], v[244:247], v[2:17]
	ds_read_b128 v[202:205], v0 offset:59968
	ds_read_b128 v[244:247], v148 offset:23104
	s_waitcnt vmcnt(8)
	ds_write_b128 v150, v[182:185] offset:41472
	s_waitcnt lgkmcnt(3)
	v_mfma_f32_32x32x16_f16 v[50:65], v[212:215], v[216:219], v[50:65]
	global_load_dwordx4 v[160:163], v208, s[4:5] offset:896
	s_waitcnt lgkmcnt(2)
	v_mfma_f32_32x32x16_f16 v[34:49], v[202:205], v[216:219], v[34:49]
	ds_read_b128 v[216:219], v148 offset:18528
	s_waitcnt vmcnt(8)
	ds_write_b128 v150, v[186:189] offset:9216
	s_waitcnt lgkmcnt(3)
	v_mfma_f32_32x32x16_f16 v[18:33], v[212:215], v[244:247], v[18:33]
	ds_read_b128 v[212:215], v0 offset:55392
	global_load_dwordx4 v[236:239], v250, s[8:9] offset:896
	v_mfma_f32_32x32x16_f16 v[2:17], v[202:205], v[244:247], v[2:17]
	ds_read_b128 v[202:205], v0 offset:60000
	ds_read_b128 v[244:247], v148 offset:23136
	s_waitcnt vmcnt(8)
	ds_write_b128 v150, v[190:193] offset:46080
	s_waitcnt lgkmcnt(3)
	v_mfma_f32_32x32x16_f16 v[50:65], v[212:215], v[216:219], v[50:65]
	global_load_dwordx4 v[164:167], v226, s[4:5] offset:896
	s_waitcnt lgkmcnt(2)
	v_mfma_f32_32x32x16_f16 v[34:49], v[202:205], v[216:219], v[34:49]
	s_waitcnt vmcnt(8)
	ds_write_b128 v150, v[194:197] offset:13824
	s_waitcnt lgkmcnt(2)
	v_mfma_f32_32x32x16_f16 v[18:33], v[212:215], v[244:247], v[18:33]
	global_load_dwordx4 v[240:243], v169, s[8:9] offset:896
	v_mfma_f32_32x32x16_f16 v[2:17], v[202:205], v[244:247], v[2:17]
	s_waitcnt vmcnt(8)
	ds_write_b128 v150, v[198:201] offset:50688
	s_setprio 0
	s_waitcnt lgkmcnt(0)
	s_barrier
; #define GEMM_GLOAD(P, kt_) { GEMM_GL1(P, 0, kt_) GEMM_GL1(P, 1, kt_) GEMM_GL1(P, 2, kt_) GEMM_GL1(P, 3, kt_) }
; #define GEMM_LSTORE(P, buf_) { GEMM_LS1(P, 0, buf_) GEMM_LS1(P, 1, buf_) GEMM_LS1(P, 2, buf_) GEMM_LS1(P, 3, buf_) }
; template <bool DEEP>
; DI void gemm_mainloop_t(const u16* __restrict__ Ag, int lda, const u16* __restrict__ Bg, int ldb, int K, char* ldsraw,
;                         f32x16 (&acc)[2][2], int akstep) {
;     ...
;     for (int kt = 0; kt < nk; kt += 2) {
;       if (kt + 2 < nk) GEMM_GLOAD(x, kt + 2);
;       GEMM_COMPUTE(0);
;       GEMM_LSTORE(y, 1);
;       __syncthreads();
;       if (kt + 3 < nk) GEMM_GLOAD(y, kt + 3);
;       GEMM_COMPUTE(1);
;       if (kt + 2 < nk) GEMM_LSTORE(x, 0);
;       __syncthreads();
;     }
	s_setprio 1
	ds_read_b128 v[212:215], v0 offset:36864
	ds_read_b128 v[216:219], v148
	ds_read_b128 v[202:205], v0 offset:41472
	ds_read_b128 v[244:247], v148 offset:4608
	s_waitcnt lgkmcnt(2)
	v_mfma_f32_32x32x16_f16 v[50:65], v[212:215], v[216:219], v[50:65]
	global_load_dwordx4 v[170:173], v206, s[4:5] offset:1024
	s_waitcnt lgkmcnt(1)
	v_mfma_f32_32x32x16_f16 v[34:49], v[202:205], v[216:219], v[34:49]
	ds_read_b128 v[216:219], v148 offset:32
	s_waitcnt vmcnt(8)
	ds_write_b128 v150, v[152:155] offset:18432
	s_waitcnt lgkmcnt(2)
	v_mfma_f32_32x32x16_f16 v[18:33], v[212:215], v[244:247], v[18:33]
	ds_read_b128 v[212:215], v0 offset:36896
	global_load_dwordx4 v[174:177], v248, s[8:9] offset:1024
	v_mfma_f32_32x32x16_f16 v[2:17], v[202:205], v[244:247], v[2:17]
	ds_read_b128 v[202:205], v0 offset:41504
	ds_read_b128 v[244:247], v148 offset:4640
	s_waitcnt vmcnt(8)
	ds_write_b128 v150, v[228:231] offset:55296
	s_waitcnt lgkmcnt(3)
	v_mfma_f32_32x32x16_f16 v[50:65], v[212:215], v[216:219], v[50:65]
	global_load_dwordx4 v[178:181], v207, s[4:5] offset:1024
	s_waitcnt lgkmcnt(2)
	v_mfma_f32_32x32x16_f16 v[34:49], v[202:205], v[216:219], v[34:49]
	ds_read_b128 v[216:219], v148 offset:64
	s_waitcnt vmcnt(8)
	ds_write_b128 v150, v[156:159] offset:23040
	s_waitcnt lgkmcnt(3)
	v_mfma_f32_32x32x16_f16 v[18:33], v[212:215], v[244:247], v[18:33]
	ds_read_b128 v[212:215], v0 offset:36928
	global_load_dwordx4 v[182:185], v249, s[8:9] offset:1024
	v_mfma_f32_32x32x16_f16 v[2:17], v[202:205], v[244:247], v[2:17]
	ds_read_b128 v[202:205], v0 offset:41536
	ds_read_b128 v[244:247], v148 offset:4672
	s_waitcnt vmcnt(8)
	ds_write_b128 v150, v[232:235] offset:59904
	s_waitcnt lgkmcnt(3)
	v_mfma_f32_32x32x16_f16 v[50:65], v[212:215], v[216:219], v[50:65]
	global_load_dwordx4 v[186:189], v208, s[4:5] offset:1024
	s_waitcnt lgkmcnt(2)
	v_mfma_f32_32x32x16_f16 v[34:49], v[202:205], v[216:219], v[34:49]
	ds_read_b128 v[216:219], v148 offset:96
	s_waitcnt vmcnt(8)
	ds_write_b128 v150, v[160:163] offset:27648
	s_waitcnt lgkmcnt(3)
	v_mfma_f32_32x32x16_f16 v[18:33], v[212:215], v[244:247], v[18:33]
	ds_read_b128 v[212:215], v0 offset:36960
	global_load_dwordx4 v[190:193], v250, s[8:9] offset:1024
	v_mfma_f32_32x32x16_f16 v[2:17], v[202:205], v[244:247], v[2:17]
	ds_read_b128 v[202:205], v0 offset:41568
	ds_read_b128 v[244:247], v148 offset:4704
	s_waitcnt vmcnt(8)
	ds_write_b128 v150, v[236:239] offset:64512
	s_waitcnt lgkmcnt(3)
	v_mfma_f32_32x32x16_f16 v[50:65], v[212:215], v[216:219], v[50:65]
	global_load_dwordx4 v[194:197], v226, s[4:5] offset:1024
	s_waitcnt lgkmcnt(2)
	v_mfma_f32_32x32x16_f16 v[34:49], v[202:205], v[216:219], v[34:49]
	s_waitcnt vmcnt(8)
	ds_write_b128 v150, v[164:167] offset:32256
	s_waitcnt lgkmcnt(2)
	v_mfma_f32_32x32x16_f16 v[18:33], v[212:215], v[244:247], v[18:33]
	global_load_dwordx4 v[198:201], v169, s[8:9] offset:1024
	v_mfma_f32_32x32x16_f16 v[2:17], v[202:205], v[244:247], v[2:17]
	s_waitcnt vmcnt(8)
	ds_write_b128 v151, v[240:243] offset:64512
	s_setprio 0
	s_waitcnt lgkmcnt(0)
	s_barrier
	s_setprio 1
	ds_read_b128 v[212:215], v0 offset:55296
	ds_read_b128 v[216:219], v148 offset:18432
	ds_read_b128 v[202:205], v0 offset:59904
	ds_read_b128 v[244:247], v148 offset:23040
	s_waitcnt lgkmcnt(2)
	v_mfma_f32_32x32x16_f16 v[50:65], v[212:215], v[216:219], v[50:65]
	global_load_dwordx4 v[152:155], v206, s[4:5] offset:1152
	s_waitcnt lgkmcnt(1)
	v_mfma_f32_32x32x16_f16 v[34:49], v[202:205], v[216:219], v[34:49]
	ds_read_b128 v[216:219], v148 offset:18464
	s_waitcnt vmcnt(8)
	ds_write_b128 v150, v[170:173]
	s_waitcnt lgkmcnt(2)
	v_mfma_f32_32x32x16_f16 v[18:33], v[212:215], v[244:247], v[18:33]
	ds_read_b128 v[212:215], v0 offset:55328
	global_load_dwordx4 v[228:231], v248, s[8:9] offset:1152
	v_mfma_f32_32x32x16_f16 v[2:17], v[202:205], v[244:247], v[2:17]
	ds_read_b128 v[202:205], v0 offset:59936
	ds_read_b128 v[244:247], v148 offset:23072
	s_waitcnt vmcnt(8)
	ds_write_b128 v150, v[174:177] offset:36864
	s_waitcnt lgkmcnt(3)
	v_mfma_f32_32x32x16_f16 v[50:65], v[212:215], v[216:219], v[50:65]
	global_load_dwordx4 v[156:159], v207, s[4:5] offset:1152
	s_waitcnt lgkmcnt(2)
	v_mfma_f32_32x32x16_f16 v[34:49], v[202:205], v[216:219], v[34:49]
	ds_read_b128 v[216:219], v148 offset:18496
	s_waitcnt vmcnt(8)
	ds_write_b128 v150, v[178:181] offset:4608
	s_waitcnt lgkmcnt(3)
	v_mfma_f32_32x32x16_f16 v[18:33], v[212:215], v[244:247], v[18:33]
	ds_read_b128 v[212:215], v0 offset:55360
	global_load_dwordx4 v[232:235], v249, s[8:9] offset:1152
	v_mfma_f32_32x32x16_f16 v[2:17], v[202:205], v[244:247], v[2:17]
	ds_read_b128 v[202:205], v0 offset:59968
	ds_read_b128 v[244:247], v148 offset:23104
	s_waitcnt vmcnt(8)
	ds_write_b128 v150, v[182:185] offset:41472
	s_waitcnt lgkmcnt(3)
	v_mfma_f32_32x32x16_f16 v[50:65], v[212:215], v[216:219], v[50:65]
	global_load_dwordx4 v[160:163], v208, s[4:5] offset:1152
	s_waitcnt lgkmcnt(2)
	v_mfma_f32_32x32x16_f16 v[34:49], v[202:205], v[216:219], v[34:49]
	ds_read_b128 v[216:219], v148 offset:18528
	s_waitcnt vmcnt(8)
	ds_write_b128 v150, v[186:189] offset:9216
	s_waitcnt lgkmcnt(3)
	v_mfma_f32_32x32x16_f16 v[18:33], v[212:215], v[244:247], v[18:33]
	ds_read_b128 v[212:215], v0 offset:55392
	global_load_dwordx4 v[236:239], v250, s[8:9] offset:1152
	v_mfma_f32_32x32x16_f16 v[2:17], v[202:205], v[244:247], v[2:17]
	ds_read_b128 v[202:205], v0 offset:60000
	ds_read_b128 v[244:247], v148 offset:23136
	s_waitcnt vmcnt(8)
	ds_write_b128 v150, v[190:193] offset:46080
	s_waitcnt lgkmcnt(3)
	v_mfma_f32_32x32x16_f16 v[50:65], v[212:215], v[216:219], v[50:65]
	global_load_dwordx4 v[164:167], v226, s[4:5] offset:1152
	s_waitcnt lgkmcnt(2)
	v_mfma_f32_32x32x16_f16 v[34:49], v[202:205], v[216:219], v[34:49]
	s_waitcnt vmcnt(8)
	ds_write_b128 v150, v[194:197] offset:13824
	s_waitcnt lgkmcnt(2)
	v_mfma_f32_32x32x16_f16 v[18:33], v[212:215], v[244:247], v[18:33]
	global_load_dwordx4 v[240:243], v169, s[8:9] offset:1152
	v_mfma_f32_32x32x16_f16 v[2:17], v[202:205], v[244:247], v[2:17]
	s_waitcnt vmcnt(8)
	ds_write_b128 v150, v[198:201] offset:50688
	s_setprio 0
	s_waitcnt lgkmcnt(0)
	s_barrier
; #define GEMM_GLOAD(P, kt_) { GEMM_GL1(P, 0, kt_) GEMM_GL1(P, 1, kt_) GEMM_GL1(P, 2, kt_) GEMM_GL1(P, 3, kt_) }
; #define GEMM_LSTORE(P, buf_) { GEMM_LS1(P, 0, buf_) GEMM_LS1(P, 1, buf_) GEMM_LS1(P, 2, buf_) GEMM_LS1(P, 3, buf_) }
; template <bool DEEP>
; DI void gemm_mainloop_t(const u16* __restrict__ Ag, int lda, const u16* __restrict__ Bg, int ldb, int K, char* ldsraw,
;                         f32x16 (&acc)[2][2], int akstep) {
;     ...
;     for (int kt = 0; kt < nk; kt += 2) {
;       if (kt + 2 < nk) GEMM_GLOAD(x, kt + 2);
;       GEMM_COMPUTE(0);
;       GEMM_LSTORE(y, 1);
;       __syncthreads();
;       if (kt + 3 < nk) GEMM_GLOAD(y, kt + 3);
;       GEMM_COMPUTE(1);
;       if (kt + 2 < nk) GEMM_LSTORE(x, 0);
;       __syncthreads();
;     }
	s_setprio 1
	ds_read_b128 v[212:215], v0 offset:36864
	ds_read_b128 v[216:219], v148
	ds_read_b128 v[202:205], v0 offset:41472
	ds_read_b128 v[244:247], v148 offset:4608
	s_waitcnt lgkmcnt(2)
	v_mfma_f32_32x32x16_f16 v[50:65], v[212:215], v[216:219], v[50:65]
	global_load_dwordx4 v[170:173], v206, s[4:5] offset:1280
	s_waitcnt lgkmcnt(1)
	v_mfma_f32_32x32x16_f16 v[34:49], v[202:205], v[216:219], v[34:49]
	ds_read_b128 v[216:219], v148 offset:32
	s_waitcnt vmcnt(8)
	ds_write_b128 v150, v[152:155] offset:18432
	s_waitcnt lgkmcnt(2)
	v_mfma_f32_32x32x16_f16 v[18:33], v[212:215], v[244:247], v[18:33]
	ds_read_b128 v[212:215], v0 offset:36896
	global_load_dwordx4 v[174:177], v248, s[8:9] offset:1280
	v_mfma_f32_32x32x16_f16 v[2:17], v[202:205], v[244:247], v[2:17]
	ds_read_b128 v[202:205], v0 offset:41504
	ds_read_b128 v[244:247], v148 offset:4640
	s_waitcnt vmcnt(8)
	ds_write_b128 v150, v[228:231] offset:55296
	s_waitcnt lgkmcnt(3)
	v_mfma_f32_32x32x16_f16 v[50:65], v[212:215], v[216:219], v[50:65]
	global_load_dwordx4 v[178:181], v207, s[4:5] offset:1280
	s_waitcnt lgkmcnt(2)
	v_mfma_f32_32x32x16_f16 v[34:49], v[202:205], v[216:219], v[34:49]
	ds_read_b128 v[216:219], v148 offset:64
	s_waitcnt vmcnt(8)
	ds_write_b128 v150, v[156:159] offset:23040
	s_waitcnt lgkmcnt(3)
	v_mfma_f32_32x32x16_f16 v[18:33], v[212:215], v[244:247], v[18:33]
	ds_read_b128 v[212:215], v0 offset:36928
	global_load_dwordx4 v[182:185], v249, s[8:9] offset:1280
	v_mfma_f32_32x32x16_f16 v[2:17], v[202:205], v[244:247], v[2:17]
	ds_read_b128 v[202:205], v0 offset:41536
	ds_read_b128 v[244:247], v148 offset:4672
	s_waitcnt vmcnt(8)
	ds_write_b128 v150, v[232:235] offset:59904
	s_waitcnt lgkmcnt(3)
	v_mfma_f32_32x32x16_f16 v[50:65], v[212:215], v[216:219], v[50:65]
	global_load_dwordx4 v[186:189], v208, s[4:5] offset:1280
	s_waitcnt lgkmcnt(2)
	v_mfma_f32_32x32x16_f16 v[34:49], v[202:205], v[216:219], v[34:49]
	ds_read_b128 v[216:219], v148 offset:96
	s_waitcnt vmcnt(8)
	ds_write_b128 v150, v[160:163] offset:27648
	s_waitcnt lgkmcnt(3)
	v_mfma_f32_32x32x16_f16 v[18:33], v[212:215], v[244:247], v[18:33]
	ds_read_b128 v[212:215], v0 offset:36960
	global_load_dwordx4 v[190:193], v250, s[8:9] offset:1280
	v_mfma_f32_32x32x16_f16 v[2:17], v[202:205], v[244:247], v[2:17]
	ds_read_b128 v[202:205], v0 offset:41568
	ds_read_b128 v[244:247], v148 offset:4704
	s_waitcnt vmcnt(8)
	ds_write_b128 v150, v[236:239] offset:64512
	s_waitcnt lgkmcnt(3)
	v_mfma_f32_32x32x16_f16 v[50:65], v[212:215], v[216:219], v[50:65]
	global_load_dwordx4 v[194:197], v226, s[4:5] offset:1280
	s_waitcnt lgkmcnt(2)
	v_mfma_f32_32x32x16_f16 v[34:49], v[202:205], v[216:219], v[34:49]
	s_waitcnt vmcnt(8)
	ds_write_b128 v150, v[164:167] offset:32256
	s_waitcnt lgkmcnt(2)
	v_mfma_f32_32x32x16_f16 v[18:33], v[212:215], v[244:247], v[18:33]
	global_load_dwordx4 v[198:201], v169, s[8:9] offset:1280
	v_mfma_f32_32x32x16_f16 v[2:17], v[202:205], v[244:247], v[2:17]
	s_waitcnt vmcnt(8)
	ds_write_b128 v151, v[240:243] offset:64512
	s_setprio 0
	s_waitcnt lgkmcnt(0)
	s_barrier
	s_setprio 1
	ds_read_b128 v[212:215], v0 offset:55296
	ds_read_b128 v[216:219], v148 offset:18432
	ds_read_b128 v[202:205], v0 offset:59904
	ds_read_b128 v[244:247], v148 offset:23040
	s_waitcnt lgkmcnt(2)
	v_mfma_f32_32x32x16_f16 v[50:65], v[212:215], v[216:219], v[50:65]
	global_load_dwordx4 v[152:155], v206, s[4:5] offset:1408
	s_waitcnt lgkmcnt(1)
	v_mfma_f32_32x32x16_f16 v[34:49], v[202:205], v[216:219], v[34:49]
	ds_read_b128 v[216:219], v148 offset:18464
	s_waitcnt vmcnt(8)
	ds_write_b128 v150, v[170:173]
	s_waitcnt lgkmcnt(2)
	v_mfma_f32_32x32x16_f16 v[18:33], v[212:215], v[244:247], v[18:33]
	ds_read_b128 v[212:215], v0 offset:55328
	global_load_dwordx4 v[228:231], v248, s[8:9] offset:1408
	v_mfma_f32_32x32x16_f16 v[2:17], v[202:205], v[244:247], v[2:17]
	ds_read_b128 v[202:205], v0 offset:59936
	ds_read_b128 v[244:247], v148 offset:23072
	s_waitcnt vmcnt(8)
	ds_write_b128 v150, v[174:177] offset:36864
	s_waitcnt lgkmcnt(3)
	v_mfma_f32_32x32x16_f16 v[50:65], v[212:215], v[216:219], v[50:65]
	global_load_dwordx4 v[156:159], v207, s[4:5] offset:1408
	s_waitcnt lgkmcnt(2)
	v_mfma_f32_32x32x16_f16 v[34:49], v[202:205], v[216:219], v[34:49]
	ds_read_b128 v[216:219], v148 offset:18496
	s_waitcnt vmcnt(8)
	ds_write_b128 v150, v[178:181] offset:4608
	s_waitcnt lgkmcnt(3)
	v_mfma_f32_32x32x16_f16 v[18:33], v[212:215], v[244:247], v[18:33]
	ds_read_b128 v[212:215], v0 offset:55360
	global_load_dwordx4 v[232:235], v249, s[8:9] offset:1408
	v_mfma_f32_32x32x16_f16 v[2:17], v[202:205], v[244:247], v[2:17]
	ds_read_b128 v[202:205], v0 offset:59968
	ds_read_b128 v[244:247], v148 offset:23104
	s_waitcnt vmcnt(8)
	ds_write_b128 v150, v[182:185] offset:41472
	s_waitcnt lgkmcnt(3)
	v_mfma_f32_32x32x16_f16 v[50:65], v[212:215], v[216:219], v[50:65]
	global_load_dwordx4 v[160:163], v208, s[4:5] offset:1408
	s_waitcnt lgkmcnt(2)
	v_mfma_f32_32x32x16_f16 v[34:49], v[202:205], v[216:219], v[34:49]
	ds_read_b128 v[216:219], v148 offset:18528
	s_waitcnt vmcnt(8)
	ds_write_b128 v150, v[186:189] offset:9216
	s_waitcnt lgkmcnt(3)
	v_mfma_f32_32x32x16_f16 v[18:33], v[212:215], v[244:247], v[18:33]
	ds_read_b128 v[212:215], v0 offset:55392
	global_load_dwordx4 v[236:239], v250, s[8:9] offset:1408
	v_mfma_f32_32x32x16_f16 v[2:17], v[202:205], v[244:247], v[2:17]
	ds_read_b128 v[202:205], v0 offset:60000
	ds_read_b128 v[244:247], v148 offset:23136
	s_waitcnt vmcnt(8)
	ds_write_b128 v150, v[190:193] offset:46080
	s_waitcnt lgkmcnt(3)
	v_mfma_f32_32x32x16_f16 v[50:65], v[212:215], v[216:219], v[50:65]
	global_load_dwordx4 v[164:167], v226, s[4:5] offset:1408
	s_waitcnt lgkmcnt(2)
	v_mfma_f32_32x32x16_f16 v[34:49], v[202:205], v[216:219], v[34:49]
	s_waitcnt vmcnt(8)
	ds_write_b128 v150, v[194:197] offset:13824
	s_waitcnt lgkmcnt(2)
	v_mfma_f32_32x32x16_f16 v[18:33], v[212:215], v[244:247], v[18:33]
	global_load_dwordx4 v[240:243], v169, s[8:9] offset:1408
	v_mfma_f32_32x32x16_f16 v[2:17], v[202:205], v[244:247], v[2:17]
	s_waitcnt vmcnt(8)
	ds_write_b128 v150, v[198:201] offset:50688
	s_setprio 0
	s_waitcnt lgkmcnt(0)
	s_barrier
; #define GEMM_GLOAD(P, kt_) { GEMM_GL1(P, 0, kt_) GEMM_GL1(P, 1, kt_) GEMM_GL1(P, 2, kt_) GEMM_GL1(P, 3, kt_) }
; #define GEMM_LSTORE(P, buf_) { GEMM_LS1(P, 0, buf_) GEMM_LS1(P, 1, buf_) GEMM_LS1(P, 2, buf_) GEMM_LS1(P, 3, buf_) }
; template <bool DEEP>
; DI void gemm_mainloop_t(const u16* __restrict__ Ag, int lda, const u16* __restrict__ Bg, int ldb, int K, char* ldsraw,
;                         f32x16 (&acc)[2][2], int akstep) {
;     ...
;     for (int kt = 0; kt < nk; kt += 2) {
;       if (kt + 2 < nk) GEMM_GLOAD(x, kt + 2);
;       GEMM_COMPUTE(0);
;       GEMM_LSTORE(y, 1);
;       __syncthreads();
;       if (kt + 3 < nk) GEMM_GLOAD(y, kt + 3);
;       GEMM_COMPUTE(1);
;       if (kt + 2 < nk) GEMM_LSTORE(x, 0);
;       __syncthreads();
;     }
	s_setprio 1
	ds_read_b128 v[212:215], v0 offset:36864
	ds_read_b128 v[216:219], v148
	ds_read_b128 v[202:205], v0 offset:41472
	ds_read_b128 v[244:247], v148 offset:4608
	s_waitcnt lgkmcnt(2)
	v_mfma_f32_32x32x16_f16 v[50:65], v[212:215], v[216:219], v[50:65]
	global_load_dwordx4 v[170:173], v206, s[4:5] offset:1536
	s_waitcnt lgkmcnt(1)
	v_mfma_f32_32x32x16_f16 v[34:49], v[202:205], v[216:219], v[34:49]
	ds_read_b128 v[216:219], v148 offset:32
	s_waitcnt vmcnt(8)
	ds_write_b128 v150, v[152:155] offset:18432
	s_waitcnt lgkmcnt(2)
	v_mfma_f32_32x32x16_f16 v[18:33], v[212:215], v[244:247], v[18:33]
	ds_read_b128 v[212:215], v0 offset:36896
	global_load_dwordx4 v[174:177], v248, s[8:9] offset:1536
	v_mfma_f32_32x32x16_f16 v[2:17], v[202:205], v[244:247], v[2:17]
	ds_read_b128 v[202:205], v0 offset:41504
	ds_read_b128 v[244:247], v148 offset:4640
	s_waitcnt vmcnt(8)
	ds_write_b128 v150, v[228:231] offset:55296
	s_waitcnt lgkmcnt(3)
	v_mfma_f32_32x32x16_f16 v[50:65], v[212:215], v[216:219], v[50:65]
	global_load_dwordx4 v[178:181], v207, s[4:5] offset:1536
	s_waitcnt lgkmcnt(2)
	v_mfma_f32_32x32x16_f16 v[34:49], v[202:205], v[216:219], v[34:49]
	ds_read_b128 v[216:219], v148 offset:64
	s_waitcnt vmcnt(8)
	ds_write_b128 v150, v[156:159] offset:23040
	s_waitcnt lgkmcnt(3)
	v_mfma_f32_32x32x16_f16 v[18:33], v[212:215], v[244:247], v[18:33]
	ds_read_b128 v[212:215], v0 offset:36928
	global_load_dwordx4 v[182:185], v249, s[8:9] offset:1536
	v_mfma_f32_32x32x16_f16 v[2:17], v[202:205], v[244:247], v[2:17]
	ds_read_b128 v[202:205], v0 offset:41536
	ds_read_b128 v[244:247], v148 offset:4672
	s_waitcnt vmcnt(8)
	ds_write_b128 v150, v[232:235] offset:59904
	s_waitcnt lgkmcnt(3)
	v_mfma_f32_32x32x16_f16 v[50:65], v[212:215], v[216:219], v[50:65]
	global_load_dwordx4 v[186:189], v208, s[4:5] offset:1536
	s_waitcnt lgkmcnt(2)
	v_mfma_f32_32x32x16_f16 v[34:49], v[202:205], v[216:219], v[34:49]
	ds_read_b128 v[216:219], v148 offset:96
	s_waitcnt vmcnt(8)
	ds_write_b128 v150, v[160:163] offset:27648
	s_waitcnt lgkmcnt(3)
	v_mfma_f32_32x32x16_f16 v[18:33], v[212:215], v[244:247], v[18:33]
	ds_read_b128 v[212:215], v0 offset:36960
	global_load_dwordx4 v[190:193], v250, s[8:9] offset:1536
	v_mfma_f32_32x32x16_f16 v[2:17], v[202:205], v[244:247], v[2:17]
	ds_read_b128 v[202:205], v0 offset:41568
	ds_read_b128 v[244:247], v148 offset:4704
	s_waitcnt vmcnt(8)
	ds_write_b128 v150, v[236:239] offset:64512
	s_waitcnt lgkmcnt(3)
	v_mfma_f32_32x32x16_f16 v[50:65], v[212:215], v[216:219], v[50:65]
	global_load_dwordx4 v[194:197], v226, s[4:5] offset:1536
	s_waitcnt lgkmcnt(2)
	v_mfma_f32_32x32x16_f16 v[34:49], v[202:205], v[216:219], v[34:49]
	s_waitcnt vmcnt(8)
	ds_write_b128 v150, v[164:167] offset:32256
	s_waitcnt lgkmcnt(2)
	v_mfma_f32_32x32x16_f16 v[18:33], v[212:215], v[244:247], v[18:33]
	global_load_dwordx4 v[198:201], v169, s[8:9] offset:1536
	v_mfma_f32_32x32x16_f16 v[2:17], v[202:205], v[244:247], v[2:17]
	s_waitcnt vmcnt(8)
	ds_write_b128 v151, v[240:243] offset:64512
	s_setprio 0
	s_waitcnt lgkmcnt(0)
	s_barrier
	s_setprio 1
	ds_read_b128 v[212:215], v0 offset:55296
	ds_read_b128 v[216:219], v148 offset:18432
	ds_read_b128 v[202:205], v0 offset:59904
	ds_read_b128 v[244:247], v148 offset:23040
	s_waitcnt lgkmcnt(2)
	v_mfma_f32_32x32x16_f16 v[50:65], v[212:215], v[216:219], v[50:65]
	global_load_dwordx4 v[152:155], v206, s[4:5] offset:1664
	s_waitcnt lgkmcnt(1)
	v_mfma_f32_32x32x16_f16 v[34:49], v[202:205], v[216:219], v[34:49]
	ds_read_b128 v[216:219], v148 offset:18464
	s_waitcnt vmcnt(8)
	ds_write_b128 v150, v[170:173]
	s_waitcnt lgkmcnt(2)
	v_mfma_f32_32x32x16_f16 v[18:33], v[212:215], v[244:247], v[18:33]
	ds_read_b128 v[212:215], v0 offset:55328
	global_load_dwordx4 v[228:231], v248, s[8:9] offset:1664
	v_mfma_f32_32x32x16_f16 v[2:17], v[202:205], v[244:247], v[2:17]
	ds_read_b128 v[202:205], v0 offset:59936
	ds_read_b128 v[244:247], v148 offset:23072
	s_waitcnt vmcnt(8)
	ds_write_b128 v150, v[174:177] offset:36864
	s_waitcnt lgkmcnt(3)
	v_mfma_f32_32x32x16_f16 v[50:65], v[212:215], v[216:219], v[50:65]
	global_load_dwordx4 v[156:159], v207, s[4:5] offset:1664
	s_waitcnt lgkmcnt(2)
	v_mfma_f32_32x32x16_f16 v[34:49], v[202:205], v[216:219], v[34:49]
	ds_read_b128 v[216:219], v148 offset:18496
	s_waitcnt vmcnt(8)
	ds_write_b128 v150, v[178:181] offset:4608
	s_waitcnt lgkmcnt(3)
	v_mfma_f32_32x32x16_f16 v[18:33], v[212:215], v[244:247], v[18:33]
	ds_read_b128 v[212:215], v0 offset:55360
	global_load_dwordx4 v[232:235], v249, s[8:9] offset:1664
	v_mfma_f32_32x32x16_f16 v[2:17], v[202:205], v[244:247], v[2:17]
	ds_read_b128 v[202:205], v0 offset:59968
	ds_read_b128 v[244:247], v148 offset:23104
	s_waitcnt vmcnt(8)
	ds_write_b128 v150, v[182:185] offset:41472
	s_waitcnt lgkmcnt(3)
	v_mfma_f32_32x32x16_f16 v[50:65], v[212:215], v[216:219], v[50:65]
	global_load_dwordx4 v[160:163], v208, s[4:5] offset:1664
	s_waitcnt lgkmcnt(2)
	v_mfma_f32_32x32x16_f16 v[34:49], v[202:205], v[216:219], v[34:49]
	ds_read_b128 v[216:219], v148 offset:18528
	s_waitcnt vmcnt(8)
	ds_write_b128 v150, v[186:189] offset:9216
	s_waitcnt lgkmcnt(3)
	v_mfma_f32_32x32x16_f16 v[18:33], v[212:215], v[244:247], v[18:33]
	ds_read_b128 v[212:215], v0 offset:55392
	global_load_dwordx4 v[236:239], v250, s[8:9] offset:1664
	v_mfma_f32_32x32x16_f16 v[2:17], v[202:205], v[244:247], v[2:17]
	ds_read_b128 v[202:205], v0 offset:60000
	ds_read_b128 v[244:247], v148 offset:23136
	s_waitcnt vmcnt(8)
	ds_write_b128 v150, v[190:193] offset:46080
	s_waitcnt lgkmcnt(3)
	v_mfma_f32_32x32x16_f16 v[50:65], v[212:215], v[216:219], v[50:65]
	global_load_dwordx4 v[164:167], v226, s[4:5] offset:1664
	s_waitcnt lgkmcnt(2)
	v_mfma_f32_32x32x16_f16 v[34:49], v[202:205], v[216:219], v[34:49]
	s_waitcnt vmcnt(8)
	ds_write_b128 v150, v[194:197] offset:13824
	s_waitcnt lgkmcnt(2)
	v_mfma_f32_32x32x16_f16 v[18:33], v[212:215], v[244:247], v[18:33]
	global_load_dwordx4 v[240:243], v169, s[8:9] offset:1664
	v_mfma_f32_32x32x16_f16 v[2:17], v[202:205], v[244:247], v[2:17]
	s_waitcnt vmcnt(8)
	ds_write_b128 v150, v[198:201] offset:50688
	s_setprio 0
	s_waitcnt lgkmcnt(0)
	s_barrier
; #define GEMM_GLOAD(P, kt_) { GEMM_GL1(P, 0, kt_) GEMM_GL1(P, 1, kt_) GEMM_GL1(P, 2, kt_) GEMM_GL1(P, 3, kt_) }
; #define GEMM_LSTORE(P, buf_) { GEMM_LS1(P, 0, buf_) GEMM_LS1(P, 1, buf_) GEMM_LS1(P, 2, buf_) GEMM_LS1(P, 3, buf_) }
; template <bool DEEP>
; DI void gemm_mainloop_t(const u16* __restrict__ Ag, int lda, const u16* __restrict__ Bg, int ldb, int K, char* ldsraw,
;                         f32x16 (&acc)[2][2], int akstep) {
;     ...
;     for (int kt = 0; kt < nk; kt += 2) {
;       if (kt + 2 < nk) GEMM_GLOAD(x, kt + 2);
;       GEMM_COMPUTE(0);
;       GEMM_LSTORE(y, 1);
;       __syncthreads();
;       if (kt + 3 < nk) GEMM_GLOAD(y, kt + 3);
;       GEMM_COMPUTE(1);
;       if (kt + 2 < nk) GEMM_LSTORE(x, 0);
;       __syncthreads();
;     }
	s_setprio 1
	ds_read_b128 v[212:215], v0 offset:36864
	ds_read_b128 v[216:219], v148
	ds_read_b128 v[202:205], v0 offset:41472
	ds_read_b128 v[244:247], v148 offset:4608
	s_waitcnt lgkmcnt(2)
	v_mfma_f32_32x32x16_f16 v[50:65], v[212:215], v[216:219], v[50:65]
	global_load_dwordx4 v[170:173], v206, s[4:5] offset:1792
	s_waitcnt lgkmcnt(1)
	v_mfma_f32_32x32x16_f16 v[34:49], v[202:205], v[216:219], v[34:49]
	ds_read_b128 v[216:219], v148 offset:32
	s_waitcnt vmcnt(8)
	ds_write_b128 v150, v[152:155] offset:18432
	s_waitcnt lgkmcnt(2)
	v_mfma_f32_32x32x16_f16 v[18:33], v[212:215], v[244:247], v[18:33]
	ds_read_b128 v[212:215], v0 offset:36896
	global_load_dwordx4 v[174:177], v248, s[8:9] offset:1792
	v_mfma_f32_32x32x16_f16 v[2:17], v[202:205], v[244:247], v[2:17]
	ds_read_b128 v[202:205], v0 offset:41504
	ds_read_b128 v[244:247], v148 offset:4640
	s_waitcnt vmcnt(8)
	ds_write_b128 v150, v[228:231] offset:55296
	s_waitcnt lgkmcnt(3)
	v_mfma_f32_32x32x16_f16 v[50:65], v[212:215], v[216:219], v[50:65]
	global_load_dwordx4 v[178:181], v207, s[4:5] offset:1792
	s_waitcnt lgkmcnt(2)
	v_mfma_f32_32x32x16_f16 v[34:49], v[202:205], v[216:219], v[34:49]
	ds_read_b128 v[216:219], v148 offset:64
	s_waitcnt vmcnt(8)
	ds_write_b128 v150, v[156:159] offset:23040
	s_waitcnt lgkmcnt(3)
	v_mfma_f32_32x32x16_f16 v[18:33], v[212:215], v[244:247], v[18:33]
	ds_read_b128 v[212:215], v0 offset:36928
	global_load_dwordx4 v[182:185], v249, s[8:9] offset:1792
	v_mfma_f32_32x32x16_f16 v[2:17], v[202:205], v[244:247], v[2:17]
	ds_read_b128 v[202:205], v0 offset:41536
	ds_read_b128 v[244:247], v148 offset:4672
	s_waitcnt vmcnt(8)
	ds_write_b128 v150, v[232:235] offset:59904
	s_waitcnt lgkmcnt(3)
	v_mfma_f32_32x32x16_f16 v[50:65], v[212:215], v[216:219], v[50:65]
	global_load_dwordx4 v[186:189], v208, s[4:5] offset:1792
	s_waitcnt lgkmcnt(2)
	v_mfma_f32_32x32x16_f16 v[34:49], v[202:205], v[216:219], v[34:49]
	ds_read_b128 v[216:219], v148 offset:96
	s_waitcnt vmcnt(8)
	ds_write_b128 v150, v[160:163] offset:27648
	s_waitcnt lgkmcnt(3)
	v_mfma_f32_32x32x16_f16 v[18:33], v[212:215], v[244:247], v[18:33]
	ds_read_b128 v[212:215], v0 offset:36960
	global_load_dwordx4 v[190:193], v250, s[8:9] offset:1792
	v_mfma_f32_32x32x16_f16 v[2:17], v[202:205], v[244:247], v[2:17]
	ds_read_b128 v[202:205], v0 offset:41568
	ds_read_b128 v[244:247], v148 offset:4704
	s_waitcnt vmcnt(8)
	ds_write_b128 v150, v[236:239] offset:64512
	s_waitcnt lgkmcnt(3)
	v_mfma_f32_32x32x16_f16 v[50:65], v[212:215], v[216:219], v[50:65]
	global_load_dwordx4 v[194:197], v226, s[4:5] offset:1792
	s_waitcnt lgkmcnt(2)
	v_mfma_f32_32x32x16_f16 v[34:49], v[202:205], v[216:219], v[34:49]
	s_waitcnt vmcnt(8)
	ds_write_b128 v150, v[164:167] offset:32256
	s_waitcnt lgkmcnt(2)
	v_mfma_f32_32x32x16_f16 v[18:33], v[212:215], v[244:247], v[18:33]
	global_load_dwordx4 v[198:201], v169, s[8:9] offset:1792
	v_mfma_f32_32x32x16_f16 v[2:17], v[202:205], v[244:247], v[2:17]
	s_waitcnt vmcnt(8)
	ds_write_b128 v151, v[240:243] offset:64512
	s_setprio 0
	s_waitcnt lgkmcnt(0)
	s_barrier
	s_setprio 1
	ds_read_b128 v[212:215], v0 offset:55296
	ds_read_b128 v[216:219], v148 offset:18432
	ds_read_b128 v[202:205], v0 offset:59904
	ds_read_b128 v[244:247], v148 offset:23040
	s_waitcnt lgkmcnt(2)
	v_mfma_f32_32x32x16_f16 v[50:65], v[212:215], v[216:219], v[50:65]
	global_load_dwordx4 v[152:155], v206, s[4:5] offset:1920
	s_waitcnt lgkmcnt(1)
	v_mfma_f32_32x32x16_f16 v[34:49], v[202:205], v[216:219], v[34:49]
	ds_read_b128 v[216:219], v148 offset:18464
	s_waitcnt vmcnt(8)
	ds_write_b128 v150, v[170:173]
	s_waitcnt lgkmcnt(2)
	v_mfma_f32_32x32x16_f16 v[18:33], v[212:215], v[244:247], v[18:33]
	ds_read_b128 v[212:215], v0 offset:55328
	global_load_dwordx4 v[228:231], v248, s[8:9] offset:1920
	v_mfma_f32_32x32x16_f16 v[2:17], v[202:205], v[244:247], v[2:17]
	ds_read_b128 v[202:205], v0 offset:59936
	ds_read_b128 v[244:247], v148 offset:23072
	s_waitcnt vmcnt(8)
	ds_write_b128 v150, v[174:177] offset:36864
	s_waitcnt lgkmcnt(3)
	v_mfma_f32_32x32x16_f16 v[50:65], v[212:215], v[216:219], v[50:65]
	global_load_dwordx4 v[156:159], v207, s[4:5] offset:1920
	s_waitcnt lgkmcnt(2)
	v_mfma_f32_32x32x16_f16 v[34:49], v[202:205], v[216:219], v[34:49]
	ds_read_b128 v[216:219], v148 offset:18496
	s_waitcnt vmcnt(8)
	ds_write_b128 v150, v[178:181] offset:4608
	s_waitcnt lgkmcnt(3)
	v_mfma_f32_32x32x16_f16 v[18:33], v[212:215], v[244:247], v[18:33]
	ds_read_b128 v[212:215], v0 offset:55360
	global_load_dwordx4 v[232:235], v249, s[8:9] offset:1920
	v_mfma_f32_32x32x16_f16 v[2:17], v[202:205], v[244:247], v[2:17]
	ds_read_b128 v[202:205], v0 offset:59968
	ds_read_b128 v[244:247], v148 offset:23104
	s_waitcnt vmcnt(8)
	ds_write_b128 v150, v[182:185] offset:41472
	s_waitcnt lgkmcnt(3)
	v_mfma_f32_32x32x16_f16 v[50:65], v[212:215], v[216:219], v[50:65]
	global_load_dwordx4 v[160:163], v208, s[4:5] offset:1920
	s_waitcnt lgkmcnt(2)
	v_mfma_f32_32x32x16_f16 v[34:49], v[202:205], v[216:219], v[34:49]
	ds_read_b128 v[216:219], v148 offset:18528
	s_waitcnt vmcnt(8)
	ds_write_b128 v150, v[186:189] offset:9216
	s_waitcnt lgkmcnt(3)
	v_mfma_f32_32x32x16_f16 v[18:33], v[212:215], v[244:247], v[18:33]
	ds_read_b128 v[212:215], v0 offset:55392
	global_load_dwordx4 v[236:239], v250, s[8:9] offset:1920
	v_mfma_f32_32x32x16_f16 v[2:17], v[202:205], v[244:247], v[2:17]
	ds_read_b128 v[202:205], v0 offset:60000
	ds_read_b128 v[244:247], v148 offset:23136
	s_waitcnt vmcnt(8)
	ds_write_b128 v150, v[190:193] offset:46080
	s_waitcnt lgkmcnt(3)
	v_mfma_f32_32x32x16_f16 v[50:65], v[212:215], v[216:219], v[50:65]
	global_load_dwordx4 v[164:167], v226, s[4:5] offset:1920
	s_waitcnt lgkmcnt(2)
	v_mfma_f32_32x32x16_f16 v[34:49], v[202:205], v[216:219], v[34:49]
	s_waitcnt vmcnt(8)
	ds_write_b128 v150, v[194:197] offset:13824
	s_waitcnt lgkmcnt(2)
	v_mfma_f32_32x32x16_f16 v[18:33], v[212:215], v[244:247], v[18:33]
	global_load_dwordx4 v[240:243], v169, s[8:9] offset:1920
	v_mfma_f32_32x32x16_f16 v[2:17], v[202:205], v[244:247], v[2:17]
	s_waitcnt vmcnt(8)
	ds_write_b128 v150, v[198:201] offset:50688
	s_setprio 0
	s_waitcnt lgkmcnt(0)
	s_barrier
; DI unsigned pk2(float a, float b) { f2_t v = {a, b}; bf2_t r = __builtin_convertvector(v, bf2_t); return __builtin_bit_cast(unsigned, r); }
; DI float sigmoidf_(float x) { return 1.f / (1.f + __expf(-x)); }
; DI void phase4(const Params& p, int l, char* lds) {
;     ...
;           for (int i = 0; i < 2; ++i) {
;             uint4 o;
;             o.x = pk2(sigmoidf_(acc[a][b][8 * i]), sigmoidf_(acc[a][b][8 * i + 1]));
;             o.y = pk2(sigmoidf_(acc[a][b][8 * i + 2]), sigmoidf_(acc[a][b][8 * i + 3]));
;             o.z = pk2(sigmoidf_(acc[a][b][8 * i + 4]), sigmoidf_(acc[a][b][8 * i + 5]));
;             o.w = pk2(sigmoidf_(acc[a][b][8 * i + 6]), sigmoidf_(acc[a][b][8 * i + 7]));
;             scr[((a * 2 + b) * 2 + i) * 256] = o;
	s_setprio 1
	ds_read_b128 v[212:215], v0 offset:36864
	ds_read_b128 v[216:219], v148
	ds_read_b128 v[202:205], v0 offset:41472
	ds_read_b128 v[244:247], v148 offset:4608
	s_waitcnt lgkmcnt(2)
	v_mfma_f32_32x32x16_f16 v[50:65], v[212:215], v[216:219], v[50:65]
	s_waitcnt lgkmcnt(1)
	v_mfma_f32_32x32x16_f16 v[34:49], v[202:205], v[216:219], v[34:49]
	ds_read_b128 v[216:219], v148 offset:32
	s_waitcnt vmcnt(7)
	ds_write_b128 v150, v[152:155] offset:18432
	s_waitcnt lgkmcnt(2)
	v_mfma_f32_32x32x16_f16 v[18:33], v[212:215], v[244:247], v[18:33]
	ds_read_b128 v[212:215], v0 offset:36896
	v_mfma_f32_32x32x16_f16 v[2:17], v[202:205], v[244:247], v[2:17]
	ds_read_b128 v[202:205], v0 offset:41504
	ds_read_b128 v[244:247], v148 offset:4640
	s_waitcnt vmcnt(6)
	ds_write_b128 v150, v[228:231] offset:55296
	s_waitcnt lgkmcnt(3)
	v_mfma_f32_32x32x16_f16 v[50:65], v[212:215], v[216:219], v[50:65]
	s_waitcnt lgkmcnt(2)
	v_mfma_f32_32x32x16_f16 v[34:49], v[202:205], v[216:219], v[34:49]
	ds_read_b128 v[216:219], v148 offset:64
	s_waitcnt vmcnt(5)
	ds_write_b128 v150, v[156:159] offset:23040
	s_waitcnt lgkmcnt(3)
	v_mfma_f32_32x32x16_f16 v[18:33], v[212:215], v[244:247], v[18:33]
	ds_read_b128 v[212:215], v0 offset:36928
	v_mfma_f32_32x32x16_f16 v[2:17], v[202:205], v[244:247], v[2:17]
	ds_read_b128 v[202:205], v0 offset:41536
	ds_read_b128 v[244:247], v148 offset:4672
	s_waitcnt vmcnt(4)
	ds_write_b128 v150, v[232:235] offset:59904
	s_waitcnt lgkmcnt(3)
	v_mfma_f32_32x32x16_f16 v[50:65], v[212:215], v[216:219], v[50:65]
	s_waitcnt lgkmcnt(2)
	v_mfma_f32_32x32x16_f16 v[34:49], v[202:205], v[216:219], v[34:49]
	ds_read_b128 v[216:219], v148 offset:96
	s_waitcnt vmcnt(3)
	ds_write_b128 v150, v[160:163] offset:27648
	s_waitcnt lgkmcnt(3)
	v_mfma_f32_32x32x16_f16 v[18:33], v[212:215], v[244:247], v[18:33]
	ds_read_b128 v[212:215], v0 offset:36960
	v_mfma_f32_32x32x16_f16 v[2:17], v[202:205], v[244:247], v[2:17]
	ds_read_b128 v[202:205], v0 offset:41568
	ds_read_b128 v[244:247], v148 offset:4704
	s_waitcnt vmcnt(2)
	ds_write_b128 v150, v[236:239] offset:64512
	s_waitcnt lgkmcnt(3)
	v_mfma_f32_32x32x16_f16 v[50:65], v[212:215], v[216:219], v[50:65]
	s_waitcnt lgkmcnt(2)
	v_mfma_f32_32x32x16_f16 v[34:49], v[202:205], v[216:219], v[34:49]
	s_waitcnt vmcnt(1)
	ds_write_b128 v150, v[164:167] offset:32256
	s_waitcnt lgkmcnt(2)
	v_mfma_f32_32x32x16_f16 v[18:33], v[212:215], v[244:247], v[18:33]
	v_mfma_f32_32x32x16_f16 v[2:17], v[202:205], v[244:247], v[2:17]
	s_waitcnt vmcnt(0)
	ds_write_b128 v151, v[240:243] offset:64512
	s_setprio 0
	s_waitcnt lgkmcnt(0)
	s_barrier
	s_setprio 1
	ds_read_b128 v[212:215], v0 offset:55296
	ds_read_b128 v[216:219], v148 offset:18432
	ds_read_b128 v[202:205], v0 offset:59904
	ds_read_b128 v[244:247], v148 offset:23040
	s_waitcnt lgkmcnt(2)
	v_mfma_f32_32x32x16_f16 v[50:65], v[212:215], v[216:219], v[50:65]
	s_waitcnt lgkmcnt(1)
	v_mfma_f32_32x32x16_f16 v[34:49], v[202:205], v[216:219], v[34:49]
	ds_read_b128 v[216:219], v148 offset:18464
	s_waitcnt lgkmcnt(1)
	v_mfma_f32_32x32x16_f16 v[18:33], v[212:215], v[244:247], v[18:33]
	ds_read_b128 v[212:215], v0 offset:55328
	v_mfma_f32_32x32x16_f16 v[2:17], v[202:205], v[244:247], v[2:17]
	ds_read_b128 v[202:205], v0 offset:59936
	ds_read_b128 v[244:247], v148 offset:23072
	s_waitcnt lgkmcnt(2)
	v_mfma_f32_32x32x16_f16 v[50:65], v[212:215], v[216:219], v[50:65]
	s_waitcnt lgkmcnt(1)
	v_mfma_f32_32x32x16_f16 v[34:49], v[202:205], v[216:219], v[34:49]
	ds_read_b128 v[216:219], v148 offset:18496
	s_waitcnt lgkmcnt(1)
	v_mfma_f32_32x32x16_f16 v[18:33], v[212:215], v[244:247], v[18:33]
	ds_read_b128 v[212:215], v0 offset:55360
	v_mfma_f32_32x32x16_f16 v[2:17], v[202:205], v[244:247], v[2:17]
	ds_read_b128 v[202:205], v0 offset:59968
	ds_read_b128 v[244:247], v148 offset:23104
	s_waitcnt lgkmcnt(2)
	v_mfma_f32_32x32x16_f16 v[50:65], v[212:215], v[216:219], v[50:65]
	s_waitcnt lgkmcnt(1)
	v_mfma_f32_32x32x16_f16 v[34:49], v[202:205], v[216:219], v[34:49]
	ds_read_b128 v[216:219], v148 offset:18528
	s_waitcnt lgkmcnt(1)
	v_mfma_f32_32x32x16_f16 v[18:33], v[212:215], v[244:247], v[18:33]
	ds_read_b128 v[212:215], v0 offset:55392
	v_mfma_f32_32x32x16_f16 v[2:17], v[202:205], v[244:247], v[2:17]
	ds_read_b128 v[202:205], v0 offset:60000
	ds_read_b128 v[244:247], v148 offset:23136
	s_waitcnt lgkmcnt(2)
	v_mfma_f32_32x32x16_f16 v[50:65], v[212:215], v[216:219], v[50:65]
	s_waitcnt lgkmcnt(1)
	v_mfma_f32_32x32x16_f16 v[34:49], v[202:205], v[216:219], v[34:49]
	s_waitcnt lgkmcnt(0)
	v_mfma_f32_32x32x16_f16 v[18:33], v[212:215], v[244:247], v[18:33]
	v_mfma_f32_32x32x16_f16 v[2:17], v[202:205], v[244:247], v[2:17]
	s_setprio 0
	s_nop 1
	s_nop 4
	v_mul_f32_e32 v0, 0xbfb8aa3b, v50
	v_exp_f32_e32 v50, v0
	v_mul_f32_e32 v0, 0xbfb8aa3b, v51
	v_exp_f32_e32 v51, v0
	s_barrier
; DI unsigned pk2(float a, float b) { f2_t v = {a, b}; bf2_t r = __builtin_convertvector(v, bf2_t); return __builtin_bit_cast(unsigned, r); }
; DI float sigmoidf_(float x) { return 1.f / (1.f + __expf(-x)); }
; DI void phase4(const Params& p, int l, char* lds) {
;     ...
;           for (int i = 0; i < 2; ++i) {
;             uint4 o;
;             o.x = pk2(sigmoidf_(acc[a][b][8 * i]), sigmoidf_(acc[a][b][8 * i + 1]));
;             o.y = pk2(sigmoidf_(acc[a][b][8 * i + 2]), sigmoidf_(acc[a][b][8 * i + 3]));
;             o.z = pk2(sigmoidf_(acc[a][b][8 * i + 4]), sigmoidf_(acc[a][b][8 * i + 5]));
;             o.w = pk2(sigmoidf_(acc[a][b][8 * i + 6]), sigmoidf_(acc[a][b][8 * i + 7]));
;             scr[((a * 2 + b) * 2 + i) * 256] = o;
	v_pk_add_f32 v[50:51], v[50:51], 1.0 op_sel_hi:[1,0]
	s_cmp_lt_i32 s22, 1
	v_div_scale_f32 v0, s[8:9], v51, v51, 1.0
	v_rcp_f32_e32 v148, v0
	s_nop 0
	v_fma_f32 v149, -v0, v148, 1.0
	v_fmac_f32_e32 v148, v149, v148
	v_div_scale_f32 v149, vcc, 1.0, v51, 1.0
	v_mul_f32_e32 v150, v149, v148
	v_fma_f32 v151, -v0, v150, v149
	v_fmac_f32_e32 v150, v151, v148
	v_fma_f32 v0, -v0, v150, v149
	v_div_fmas_f32 v0, v0, v148, v150
	v_div_fixup_f32 v0, v0, v51, 1.0
	v_div_scale_f32 v51, s[8:9], v50, v50, 1.0
	v_rcp_f32_e32 v148, v51
	s_nop 0
	v_fma_f32 v149, -v51, v148, 1.0
	v_fmac_f32_e32 v148, v149, v148
	v_div_scale_f32 v149, vcc, 1.0, v50, 1.0
	v_mul_f32_e32 v150, v149, v148
	v_fma_f32 v151, -v51, v150, v149
	v_fmac_f32_e32 v150, v151, v148
	v_fma_f32 v51, -v51, v150, v149
	v_div_fmas_f32 v51, v51, v148, v150
	v_div_fixup_f32 v50, v51, v50, 1.0
	v_cvt_pk_f16_f32 v50, v50, v0
	v_mul_f32_e32 v0, 0xbfb8aa3b, v52
	v_exp_f32_e32 v52, v0
	v_mul_f32_e32 v0, 0xbfb8aa3b, v53
	v_exp_f32_e32 v53, v0
	s_nop 0
	v_pk_add_f32 v[52:53], v[52:53], 1.0 op_sel_hi:[1,0]
	s_nop 0
	v_div_scale_f32 v0, s[8:9], v53, v53, 1.0
	v_rcp_f32_e32 v51, v0
	s_nop 0
	v_fma_f32 v148, -v0, v51, 1.0
	v_fmac_f32_e32 v51, v148, v51
	v_div_scale_f32 v148, vcc, 1.0, v53, 1.0
	v_mul_f32_e32 v149, v148, v51
	v_fma_f32 v150, -v0, v149, v148
	v_fmac_f32_e32 v149, v150, v51
	v_fma_f32 v0, -v0, v149, v148
	v_div_fmas_f32 v0, v0, v51, v149
	v_div_scale_f32 v51, s[8:9], v52, v52, 1.0
	v_div_fixup_f32 v0, v0, v53, 1.0
	v_rcp_f32_e32 v53, v51
	s_nop 0
	v_fma_f32 v148, -v51, v53, 1.0
	v_fmac_f32_e32 v53, v148, v53
	v_div_scale_f32 v148, vcc, 1.0, v52, 1.0
	v_mul_f32_e32 v149, v148, v53
	v_fma_f32 v150, -v51, v149, v148
	v_fmac_f32_e32 v149, v150, v53
	v_fma_f32 v51, -v51, v149, v148
	v_div_fmas_f32 v51, v51, v53, v149
	v_div_fixup_f32 v51, v51, v52, 1.0
	v_cvt_pk_f16_f32 v51, v51, v0
	v_mul_f32_e32 v0, 0xbfb8aa3b, v54
	v_exp_f32_e32 v52, v0
	v_mul_f32_e32 v0, 0xbfb8aa3b, v55
	v_exp_f32_e32 v53, v0
	s_nop 0
	v_pk_add_f32 v[52:53], v[52:53], 1.0 op_sel_hi:[1,0]
	s_nop 0
	v_div_scale_f32 v0, s[8:9], v53, v53, 1.0
	v_rcp_f32_e32 v54, v0
	s_nop 0
	v_fma_f32 v55, -v0, v54, 1.0
	v_fmac_f32_e32 v54, v55, v54
	v_div_scale_f32 v55, vcc, 1.0, v53, 1.0
	v_mul_f32_e32 v148, v55, v54
	v_fma_f32 v149, -v0, v148, v55
	v_fmac_f32_e32 v148, v149, v54
	v_fma_f32 v0, -v0, v148, v55
	v_div_fmas_f32 v0, v0, v54, v148
	v_div_fixup_f32 v0, v0, v53, 1.0
	v_div_scale_f32 v53, s[8:9], v52, v52, 1.0
	v_rcp_f32_e32 v54, v53
	s_nop 0
	v_fma_f32 v55, -v53, v54, 1.0
	v_fmac_f32_e32 v54, v55, v54
	v_div_scale_f32 v55, vcc, 1.0, v52, 1.0
	v_mul_f32_e32 v148, v55, v54
	v_fma_f32 v149, -v53, v148, v55
	v_fmac_f32_e32 v148, v149, v54
	v_fma_f32 v53, -v53, v148, v55
	v_div_fmas_f32 v53, v53, v54, v148
	v_div_fixup_f32 v52, v53, v52, 1.0
	v_cvt_pk_f16_f32 v52, v52, v0
	v_mul_f32_e32 v0, 0xbfb8aa3b, v56
	v_exp_f32_e32 v54, v0
	v_mul_f32_e32 v0, 0xbfb8aa3b, v57
	v_exp_f32_e32 v55, v0
	s_nop 0
	v_pk_add_f32 v[54:55], v[54:55], 1.0 op_sel_hi:[1,0]
	s_nop 0
	v_div_scale_f32 v0, s[8:9], v55, v55, 1.0
	v_rcp_f32_e32 v53, v0
	s_nop 0
	v_fma_f32 v56, -v0, v53, 1.0
	v_fmac_f32_e32 v53, v56, v53
	v_div_scale_f32 v56, vcc, 1.0, v55, 1.0
	v_mul_f32_e32 v57, v56, v53
	v_fma_f32 v148, -v0, v57, v56
	v_fmac_f32_e32 v57, v148, v53
	v_fma_f32 v0, -v0, v57, v56
	v_div_fmas_f32 v0, v0, v53, v57
	v_div_scale_f32 v53, s[8:9], v54, v54, 1.0
	v_div_fixup_f32 v0, v0, v55, 1.0
	v_rcp_f32_e32 v55, v53
	s_nop 0
	v_fma_f32 v56, -v53, v55, 1.0
	v_fmac_f32_e32 v55, v56, v55
	v_div_scale_f32 v56, vcc, 1.0, v54, 1.0
	v_mul_f32_e32 v57, v56, v55
	v_fma_f32 v148, -v53, v57, v56
	v_fmac_f32_e32 v57, v148, v55
	v_fma_f32 v53, -v53, v57, v56
	v_div_fmas_f32 v53, v53, v55, v57
	v_div_fixup_f32 v53, v53, v54, 1.0
	v_cvt_pk_f16_f32 v53, v53, v0
	v_mul_f32_e32 v0, 0xbfb8aa3b, v58
	global_store_dwordx4 v[68:69], v[50:53], off
	s_nop 1
	v_exp_f32_e32 v50, v0
	v_mul_f32_e32 v0, 0xbfb8aa3b, v59
	v_exp_f32_e32 v51, v0
	s_nop 0
	v_pk_add_f32 v[50:51], v[50:51], 1.0 op_sel_hi:[1,0]
	s_nop 0
	v_div_scale_f32 v0, s[8:9], v51, v51, 1.0
	v_rcp_f32_e32 v52, v0
	s_nop 0
	v_fma_f32 v53, -v0, v52, 1.0
	v_fmac_f32_e32 v52, v53, v52
	v_div_scale_f32 v53, vcc, 1.0, v51, 1.0
	v_mul_f32_e32 v54, v53, v52
	v_fma_f32 v55, -v0, v54, v53
	v_fmac_f32_e32 v54, v55, v52
	v_fma_f32 v0, -v0, v54, v53
	v_div_fmas_f32 v0, v0, v52, v54
	v_div_fixup_f32 v0, v0, v51, 1.0
	v_div_scale_f32 v51, s[8:9], v50, v50, 1.0
	v_rcp_f32_e32 v52, v51
	s_nop 0
	v_fma_f32 v53, -v51, v52, 1.0
	v_fmac_f32_e32 v52, v53, v52
	v_div_scale_f32 v53, vcc, 1.0, v50, 1.0
	v_mul_f32_e32 v54, v53, v52
	v_fma_f32 v55, -v51, v54, v53
	v_fmac_f32_e32 v54, v55, v52
	v_fma_f32 v51, -v51, v54, v53
	v_div_fmas_f32 v51, v51, v52, v54
	v_div_fixup_f32 v50, v51, v50, 1.0
	v_cvt_pk_f16_f32 v50, v50, v0
	v_mul_f32_e32 v0, 0xbfb8aa3b, v60
	v_exp_f32_e32 v52, v0
	v_mul_f32_e32 v0, 0xbfb8aa3b, v61
	v_exp_f32_e32 v53, v0
	s_nop 0
	v_pk_add_f32 v[52:53], v[52:53], 1.0 op_sel_hi:[1,0]
	s_nop 0
	v_div_scale_f32 v0, s[8:9], v53, v53, 1.0
	v_rcp_f32_e32 v51, v0
	s_nop 0
	v_fma_f32 v54, -v0, v51, 1.0
	v_fmac_f32_e32 v51, v54, v51
	v_div_scale_f32 v54, vcc, 1.0, v53, 1.0
	v_mul_f32_e32 v55, v54, v51
	v_fma_f32 v56, -v0, v55, v54
	v_fmac_f32_e32 v55, v56, v51
	v_fma_f32 v0, -v0, v55, v54
	v_div_fmas_f32 v0, v0, v51, v55
	v_div_scale_f32 v51, s[8:9], v52, v52, 1.0
	v_div_fixup_f32 v0, v0, v53, 1.0
	v_rcp_f32_e32 v53, v51
	s_nop 0
	v_fma_f32 v54, -v51, v53, 1.0
	v_fmac_f32_e32 v53, v54, v53
	v_div_scale_f32 v54, vcc, 1.0, v52, 1.0
	v_mul_f32_e32 v55, v54, v53
	v_fma_f32 v56, -v51, v55, v54
	v_fmac_f32_e32 v55, v56, v53
	v_fma_f32 v51, -v51, v55, v54
; DI unsigned pk2(float a, float b) { f2_t v = {a, b}; bf2_t r = __builtin_convertvector(v, bf2_t); return __builtin_bit_cast(unsigned, r); }
; DI float sigmoidf_(float x) { return 1.f / (1.f + __expf(-x)); }
; DI void phase4(const Params& p, int l, char* lds) {
;     ...
;           for (int i = 0; i < 2; ++i) {
;             uint4 o;
;             o.x = pk2(sigmoidf_(acc[a][b][8 * i]), sigmoidf_(acc[a][b][8 * i + 1]));
;             o.y = pk2(sigmoidf_(acc[a][b][8 * i + 2]), sigmoidf_(acc[a][b][8 * i + 3]));
;             o.z = pk2(sigmoidf_(acc[a][b][8 * i + 4]), sigmoidf_(acc[a][b][8 * i + 5]));
;             o.w = pk2(sigmoidf_(acc[a][b][8 * i + 6]), sigmoidf_(acc[a][b][8 * i + 7]));
;             scr[((a * 2 + b) * 2 + i) * 256] = o;
	v_div_fmas_f32 v51, v51, v53, v55
	v_div_fixup_f32 v51, v51, v52, 1.0
	v_cvt_pk_f16_f32 v51, v51, v0
	v_mul_f32_e32 v0, 0xbfb8aa3b, v62
	v_exp_f32_e32 v52, v0
	v_mul_f32_e32 v0, 0xbfb8aa3b, v63
	v_exp_f32_e32 v53, v0
	s_nop 0
	v_pk_add_f32 v[52:53], v[52:53], 1.0 op_sel_hi:[1,0]
	s_nop 0
	v_div_scale_f32 v0, s[8:9], v53, v53, 1.0
	v_rcp_f32_e32 v54, v0
	s_nop 0
	v_fma_f32 v55, -v0, v54, 1.0
	v_fmac_f32_e32 v54, v55, v54
	v_div_scale_f32 v55, vcc, 1.0, v53, 1.0
	v_mul_f32_e32 v56, v55, v54
	v_fma_f32 v57, -v0, v56, v55
	v_fmac_f32_e32 v56, v57, v54
	v_fma_f32 v0, -v0, v56, v55
	v_div_fmas_f32 v0, v0, v54, v56
	v_div_fixup_f32 v0, v0, v53, 1.0
	v_div_scale_f32 v53, s[8:9], v52, v52, 1.0
	v_rcp_f32_e32 v54, v53
	s_nop 0
	v_fma_f32 v55, -v53, v54, 1.0
	v_fmac_f32_e32 v54, v55, v54
	v_div_scale_f32 v55, vcc, 1.0, v52, 1.0
	v_mul_f32_e32 v56, v55, v54
	v_fma_f32 v57, -v53, v56, v55
	v_fmac_f32_e32 v56, v57, v54
	v_fma_f32 v53, -v53, v56, v55
	v_div_fmas_f32 v53, v53, v54, v56
	v_div_fixup_f32 v52, v53, v52, 1.0
	v_cvt_pk_f16_f32 v52, v52, v0
	v_mul_f32_e32 v0, 0xbfb8aa3b, v64
	v_exp_f32_e32 v54, v0
	v_mul_f32_e32 v0, 0xbfb8aa3b, v65
	v_exp_f32_e32 v55, v0
	s_nop 0
	v_pk_add_f32 v[54:55], v[54:55], 1.0 op_sel_hi:[1,0]
	s_nop 0
	v_div_scale_f32 v0, s[8:9], v55, v55, 1.0
	v_rcp_f32_e32 v53, v0
	s_nop 0
	v_fma_f32 v56, -v0, v53, 1.0
	v_fmac_f32_e32 v53, v56, v53
	v_div_scale_f32 v56, vcc, 1.0, v55, 1.0
	v_mul_f32_e32 v57, v56, v53
	v_fma_f32 v58, -v0, v57, v56
	v_fmac_f32_e32 v57, v58, v53
	v_fma_f32 v0, -v0, v57, v56
	v_div_fmas_f32 v0, v0, v53, v57
	v_div_scale_f32 v53, s[8:9], v54, v54, 1.0
	v_div_fixup_f32 v0, v0, v55, 1.0
	v_rcp_f32_e32 v55, v53
	s_nop 0
	v_fma_f32 v56, -v53, v55, 1.0
	v_fmac_f32_e32 v55, v56, v55
	v_div_scale_f32 v56, vcc, 1.0, v54, 1.0
	v_mul_f32_e32 v57, v56, v55
	v_fma_f32 v58, -v53, v57, v56
	v_fmac_f32_e32 v57, v58, v55
	v_fma_f32 v53, -v53, v57, v56
	v_div_fmas_f32 v53, v53, v55, v57
	v_div_fixup_f32 v53, v53, v54, 1.0
	v_cvt_pk_f16_f32 v53, v53, v0
	v_mul_f32_e32 v0, 0xbfb8aa3b, v34
	v_exp_f32_e32 v34, v0
	v_mul_f32_e32 v0, 0xbfb8aa3b, v35
	v_exp_f32_e32 v35, v0
	global_store_dwordx4 v[70:71], v[50:53], off
	v_pk_add_f32 v[34:35], v[34:35], 1.0 op_sel_hi:[1,0]
	s_nop 0
	v_div_scale_f32 v0, s[8:9], v35, v35, 1.0
	v_rcp_f32_e32 v50, v0
	s_nop 0
	v_fma_f32 v51, -v0, v50, 1.0
	v_fmac_f32_e32 v50, v51, v50
	v_div_scale_f32 v51, vcc, 1.0, v35, 1.0
	v_mul_f32_e32 v52, v51, v50
	v_fma_f32 v53, -v0, v52, v51
	v_fmac_f32_e32 v52, v53, v50
	v_fma_f32 v0, -v0, v52, v51
	v_div_fmas_f32 v0, v0, v50, v52
	v_div_fixup_f32 v0, v0, v35, 1.0
	v_div_scale_f32 v35, s[8:9], v34, v34, 1.0
	v_rcp_f32_e32 v50, v35
	s_nop 0
	v_fma_f32 v51, -v35, v50, 1.0
	v_fmac_f32_e32 v50, v51, v50
	v_div_scale_f32 v51, vcc, 1.0, v34, 1.0
	v_mul_f32_e32 v52, v51, v50
	v_fma_f32 v53, -v35, v52, v51
	v_fmac_f32_e32 v52, v53, v50
	v_fma_f32 v35, -v35, v52, v51
	v_div_fmas_f32 v35, v35, v50, v52
	v_div_fixup_f32 v34, v35, v34, 1.0
	v_cvt_pk_f16_f32 v34, v34, v0
	v_mul_f32_e32 v0, 0xbfb8aa3b, v36
	v_exp_f32_e32 v36, v0
	v_mul_f32_e32 v0, 0xbfb8aa3b, v37
	v_exp_f32_e32 v37, v0
	s_nop 0
	v_pk_add_f32 v[36:37], v[36:37], 1.0 op_sel_hi:[1,0]
	s_nop 0
	v_div_scale_f32 v0, s[8:9], v37, v37, 1.0
	v_rcp_f32_e32 v35, v0
	s_nop 0
	v_fma_f32 v50, -v0, v35, 1.0
	v_fmac_f32_e32 v35, v50, v35
	v_div_scale_f32 v50, vcc, 1.0, v37, 1.0
	v_mul_f32_e32 v51, v50, v35
	v_fma_f32 v52, -v0, v51, v50
	v_fmac_f32_e32 v51, v52, v35
	v_fma_f32 v0, -v0, v51, v50
	v_div_fmas_f32 v0, v0, v35, v51
	v_div_scale_f32 v35, s[8:9], v36, v36, 1.0
	v_div_fixup_f32 v0, v0, v37, 1.0
	v_rcp_f32_e32 v37, v35
	s_nop 0
	v_fma_f32 v50, -v35, v37, 1.0
	v_fmac_f32_e32 v37, v50, v37
	v_div_scale_f32 v50, vcc, 1.0, v36, 1.0
	v_mul_f32_e32 v51, v50, v37
	v_fma_f32 v52, -v35, v51, v50
	v_fmac_f32_e32 v51, v52, v37
	v_fma_f32 v35, -v35, v51, v50
	v_div_fmas_f32 v35, v35, v37, v51
	v_div_fixup_f32 v35, v35, v36, 1.0
	v_cvt_pk_f16_f32 v35, v35, v0
	v_mul_f32_e32 v0, 0xbfb8aa3b, v38
	v_exp_f32_e32 v36, v0
	v_mul_f32_e32 v0, 0xbfb8aa3b, v39
	v_exp_f32_e32 v37, v0
	s_nop 0
	v_pk_add_f32 v[36:37], v[36:37], 1.0 op_sel_hi:[1,0]
	s_nop 0
	v_div_scale_f32 v0, s[8:9], v37, v37, 1.0
	v_rcp_f32_e32 v38, v0
	s_nop 0
	v_fma_f32 v39, -v0, v38, 1.0
	v_fmac_f32_e32 v38, v39, v38
	v_div_scale_f32 v39, vcc, 1.0, v37, 1.0
	v_mul_f32_e32 v50, v39, v38
	v_fma_f32 v51, -v0, v50, v39
	v_fmac_f32_e32 v50, v51, v38
	v_fma_f32 v0, -v0, v50, v39
	v_div_fmas_f32 v0, v0, v38, v50
	v_div_fixup_f32 v0, v0, v37, 1.0
	v_div_scale_f32 v37, s[8:9], v36, v36, 1.0
	v_rcp_f32_e32 v38, v37
	s_nop 0
	v_fma_f32 v39, -v37, v38, 1.0
	v_fmac_f32_e32 v38, v39, v38
	v_div_scale_f32 v39, vcc, 1.0, v36, 1.0
	v_mul_f32_e32 v50, v39, v38
	v_fma_f32 v51, -v37, v50, v39
	v_fmac_f32_e32 v50, v51, v38
	v_fma_f32 v37, -v37, v50, v39
	v_div_fmas_f32 v37, v37, v38, v50
	v_div_fixup_f32 v36, v37, v36, 1.0
	v_cvt_pk_f16_f32 v36, v36, v0
	v_mul_f32_e32 v0, 0xbfb8aa3b, v40
	v_exp_f32_e32 v38, v0
	v_mul_f32_e32 v0, 0xbfb8aa3b, v41
	v_exp_f32_e32 v39, v0
	s_nop 0
	v_pk_add_f32 v[38:39], v[38:39], 1.0 op_sel_hi:[1,0]
	s_nop 0
	v_div_scale_f32 v0, s[8:9], v39, v39, 1.0
	v_rcp_f32_e32 v37, v0
	s_nop 0
	v_fma_f32 v40, -v0, v37, 1.0
	v_fmac_f32_e32 v37, v40, v37
	v_div_scale_f32 v40, vcc, 1.0, v39, 1.0
	v_mul_f32_e32 v41, v40, v37
	v_fma_f32 v50, -v0, v41, v40
	v_fmac_f32_e32 v41, v50, v37
	v_fma_f32 v0, -v0, v41, v40
	v_div_fmas_f32 v0, v0, v37, v41
	v_div_scale_f32 v37, s[8:9], v38, v38, 1.0
	v_div_fixup_f32 v0, v0, v39, 1.0
	v_rcp_f32_e32 v39, v37
	s_nop 0
	v_fma_f32 v40, -v37, v39, 1.0
	v_fmac_f32_e32 v39, v40, v39
	v_div_scale_f32 v40, vcc, 1.0, v38, 1.0
	v_mul_f32_e32 v41, v40, v39
; DI unsigned pk2(float a, float b) { f2_t v = {a, b}; bf2_t r = __builtin_convertvector(v, bf2_t); return __builtin_bit_cast(unsigned, r); }
; DI float sigmoidf_(float x) { return 1.f / (1.f + __expf(-x)); }
; DI void phase4(const Params& p, int l, char* lds) {
;     ...
;           for (int i = 0; i < 2; ++i) {
;             uint4 o;
;             o.x = pk2(sigmoidf_(acc[a][b][8 * i]), sigmoidf_(acc[a][b][8 * i + 1]));
;             o.y = pk2(sigmoidf_(acc[a][b][8 * i + 2]), sigmoidf_(acc[a][b][8 * i + 3]));
;             o.z = pk2(sigmoidf_(acc[a][b][8 * i + 4]), sigmoidf_(acc[a][b][8 * i + 5]));
;             o.w = pk2(sigmoidf_(acc[a][b][8 * i + 6]), sigmoidf_(acc[a][b][8 * i + 7]));
;             scr[((a * 2 + b) * 2 + i) * 256] = o;
	v_fma_f32 v50, -v37, v41, v40
	v_fmac_f32_e32 v41, v50, v39
	v_fma_f32 v37, -v37, v41, v40
	v_div_fmas_f32 v37, v37, v39, v41
	v_div_fixup_f32 v37, v37, v38, 1.0
	v_cvt_pk_f16_f32 v37, v37, v0
	v_mul_f32_e32 v0, 0xbfb8aa3b, v42
	global_store_dwordx4 v[72:73], v[34:37], off
	s_nop 1
	v_exp_f32_e32 v34, v0
	v_mul_f32_e32 v0, 0xbfb8aa3b, v43
	v_exp_f32_e32 v35, v0
	s_nop 0
	v_pk_add_f32 v[34:35], v[34:35], 1.0 op_sel_hi:[1,0]
	s_nop 0
	v_div_scale_f32 v0, s[8:9], v35, v35, 1.0
	v_rcp_f32_e32 v36, v0
	s_nop 0
	v_fma_f32 v37, -v0, v36, 1.0
	v_fmac_f32_e32 v36, v37, v36
	v_div_scale_f32 v37, vcc, 1.0, v35, 1.0
	v_mul_f32_e32 v38, v37, v36
	v_fma_f32 v39, -v0, v38, v37
	v_fmac_f32_e32 v38, v39, v36
	v_fma_f32 v0, -v0, v38, v37
	v_div_fmas_f32 v0, v0, v36, v38
	v_div_fixup_f32 v0, v0, v35, 1.0
	v_div_scale_f32 v35, s[8:9], v34, v34, 1.0
	v_rcp_f32_e32 v36, v35
	s_nop 0
	v_fma_f32 v37, -v35, v36, 1.0
	v_fmac_f32_e32 v36, v37, v36
	v_div_scale_f32 v37, vcc, 1.0, v34, 1.0
	v_mul_f32_e32 v38, v37, v36
	v_fma_f32 v39, -v35, v38, v37
	v_fmac_f32_e32 v38, v39, v36
	v_fma_f32 v35, -v35, v38, v37
	v_div_fmas_f32 v35, v35, v36, v38
	v_div_fixup_f32 v34, v35, v34, 1.0
	v_cvt_pk_f16_f32 v34, v34, v0
	v_mul_f32_e32 v0, 0xbfb8aa3b, v44
	v_exp_f32_e32 v36, v0
	v_mul_f32_e32 v0, 0xbfb8aa3b, v45
	v_exp_f32_e32 v37, v0
	s_nop 0
	v_pk_add_f32 v[36:37], v[36:37], 1.0 op_sel_hi:[1,0]
	s_nop 0
	v_div_scale_f32 v0, s[8:9], v37, v37, 1.0
	v_rcp_f32_e32 v35, v0
	s_nop 0
	v_fma_f32 v38, -v0, v35, 1.0
	v_fmac_f32_e32 v35, v38, v35
	v_div_scale_f32 v38, vcc, 1.0, v37, 1.0
	v_mul_f32_e32 v39, v38, v35
	v_fma_f32 v40, -v0, v39, v38
	v_fmac_f32_e32 v39, v40, v35
	v_fma_f32 v0, -v0, v39, v38
	v_div_fmas_f32 v0, v0, v35, v39
	v_div_scale_f32 v35, s[8:9], v36, v36, 1.0
	v_div_fixup_f32 v0, v0, v37, 1.0
	v_rcp_f32_e32 v37, v35
	s_nop 0
	v_fma_f32 v38, -v35, v37, 1.0
	v_fmac_f32_e32 v37, v38, v37
	v_div_scale_f32 v38, vcc, 1.0, v36, 1.0
	v_mul_f32_e32 v39, v38, v37
	v_fma_f32 v40, -v35, v39, v38
	v_fmac_f32_e32 v39, v40, v37
	v_fma_f32 v35, -v35, v39, v38
	v_div_fmas_f32 v35, v35, v37, v39
	v_div_fixup_f32 v35, v35, v36, 1.0
	v_cvt_pk_f16_f32 v35, v35, v0
	v_mul_f32_e32 v0, 0xbfb8aa3b, v46
	v_exp_f32_e32 v36, v0
	v_mul_f32_e32 v0, 0xbfb8aa3b, v47
	v_exp_f32_e32 v37, v0
	s_nop 0
	v_pk_add_f32 v[36:37], v[36:37], 1.0 op_sel_hi:[1,0]
	s_nop 0
	v_div_scale_f32 v0, s[8:9], v37, v37, 1.0
	v_rcp_f32_e32 v38, v0
	s_nop 0
	v_fma_f32 v39, -v0, v38, 1.0
	v_fmac_f32_e32 v38, v39, v38
	v_div_scale_f32 v39, vcc, 1.0, v37, 1.0
	v_mul_f32_e32 v40, v39, v38
	v_fma_f32 v41, -v0, v40, v39
	v_fmac_f32_e32 v40, v41, v38
	v_fma_f32 v0, -v0, v40, v39
	v_div_fmas_f32 v0, v0, v38, v40
	v_div_fixup_f32 v0, v0, v37, 1.0
	v_div_scale_f32 v37, s[8:9], v36, v36, 1.0
	v_rcp_f32_e32 v38, v37
	s_nop 0
	v_fma_f32 v39, -v37, v38, 1.0
	v_fmac_f32_e32 v38, v39, v38
	v_div_scale_f32 v39, vcc, 1.0, v36, 1.0
	v_mul_f32_e32 v40, v39, v38
	v_fma_f32 v41, -v37, v40, v39
	v_fmac_f32_e32 v40, v41, v38
	v_fma_f32 v37, -v37, v40, v39
	v_div_fmas_f32 v37, v37, v38, v40
	v_div_fixup_f32 v36, v37, v36, 1.0
	v_cvt_pk_f16_f32 v36, v36, v0
	v_mul_f32_e32 v0, 0xbfb8aa3b, v48
	v_exp_f32_e32 v38, v0
	v_mul_f32_e32 v0, 0xbfb8aa3b, v49
	v_exp_f32_e32 v39, v0
	s_nop 0
	v_pk_add_f32 v[38:39], v[38:39], 1.0 op_sel_hi:[1,0]
	s_nop 0
	v_div_scale_f32 v0, s[8:9], v39, v39, 1.0
	v_rcp_f32_e32 v37, v0
	s_nop 0
	v_fma_f32 v40, -v0, v37, 1.0
	v_fmac_f32_e32 v37, v40, v37
	v_div_scale_f32 v40, vcc, 1.0, v39, 1.0
	v_mul_f32_e32 v41, v40, v37
	v_fma_f32 v42, -v0, v41, v40
	v_fmac_f32_e32 v41, v42, v37
	v_fma_f32 v0, -v0, v41, v40
	v_div_fmas_f32 v0, v0, v37, v41
	v_div_scale_f32 v37, s[8:9], v38, v38, 1.0
	v_div_fixup_f32 v0, v0, v39, 1.0
	v_rcp_f32_e32 v39, v37
	s_nop 0
	v_fma_f32 v40, -v37, v39, 1.0
	v_fmac_f32_e32 v39, v40, v39
	v_div_scale_f32 v40, vcc, 1.0, v38, 1.0
	v_mul_f32_e32 v41, v40, v39
	v_fma_f32 v42, -v37, v41, v40
	v_fmac_f32_e32 v41, v42, v39
	v_fma_f32 v37, -v37, v41, v40
	v_div_fmas_f32 v37, v37, v39, v41
	v_div_fixup_f32 v37, v37, v38, 1.0
	v_cvt_pk_f16_f32 v37, v37, v0
	v_mul_f32_e32 v0, 0xbfb8aa3b, v18
	v_exp_f32_e32 v18, v0
	v_mul_f32_e32 v0, 0xbfb8aa3b, v19
	v_exp_f32_e32 v19, v0
	global_store_dwordx4 v[74:75], v[34:37], off
	v_pk_add_f32 v[18:19], v[18:19], 1.0 op_sel_hi:[1,0]
	s_nop 0
	v_div_scale_f32 v0, s[8:9], v19, v19, 1.0
	v_rcp_f32_e32 v34, v0
	s_nop 0
	v_fma_f32 v35, -v0, v34, 1.0
	v_fmac_f32_e32 v34, v35, v34
	v_div_scale_f32 v35, vcc, 1.0, v19, 1.0
	v_mul_f32_e32 v36, v35, v34
	v_fma_f32 v37, -v0, v36, v35
	v_fmac_f32_e32 v36, v37, v34
	v_fma_f32 v0, -v0, v36, v35
	v_div_fmas_f32 v0, v0, v34, v36
	v_div_fixup_f32 v0, v0, v19, 1.0
	v_div_scale_f32 v19, s[8:9], v18, v18, 1.0
	v_rcp_f32_e32 v34, v19
	s_nop 0
	v_fma_f32 v35, -v19, v34, 1.0
	v_fmac_f32_e32 v34, v35, v34
	v_div_scale_f32 v35, vcc, 1.0, v18, 1.0
	v_mul_f32_e32 v36, v35, v34
	v_fma_f32 v37, -v19, v36, v35
	v_fmac_f32_e32 v36, v37, v34
	v_fma_f32 v19, -v19, v36, v35
	v_div_fmas_f32 v19, v19, v34, v36
	v_div_fixup_f32 v18, v19, v18, 1.0
	v_cvt_pk_f16_f32 v18, v18, v0
	v_mul_f32_e32 v0, 0xbfb8aa3b, v20
	v_exp_f32_e32 v20, v0
	v_mul_f32_e32 v0, 0xbfb8aa3b, v21
	v_exp_f32_e32 v21, v0
	s_nop 0
	v_pk_add_f32 v[20:21], v[20:21], 1.0 op_sel_hi:[1,0]
	s_nop 0
	v_div_scale_f32 v0, s[8:9], v21, v21, 1.0
	v_rcp_f32_e32 v19, v0
	s_nop 0
	v_fma_f32 v34, -v0, v19, 1.0
	v_fmac_f32_e32 v19, v34, v19
	v_div_scale_f32 v34, vcc, 1.0, v21, 1.0
	v_mul_f32_e32 v35, v34, v19
	v_fma_f32 v36, -v0, v35, v34
	v_fmac_f32_e32 v35, v36, v19
	v_fma_f32 v0, -v0, v35, v34
	v_div_fmas_f32 v0, v0, v19, v35
	v_div_scale_f32 v19, s[8:9], v20, v20, 1.0
	v_div_fixup_f32 v0, v0, v21, 1.0
; DI unsigned pk2(float a, float b) { f2_t v = {a, b}; bf2_t r = __builtin_convertvector(v, bf2_t); return __builtin_bit_cast(unsigned, r); }
; DI float sigmoidf_(float x) { return 1.f / (1.f + __expf(-x)); }
; DI void phase4(const Params& p, int l, char* lds) {
;     ...
;           for (int i = 0; i < 2; ++i) {
;             uint4 o;
;             o.x = pk2(sigmoidf_(acc[a][b][8 * i]), sigmoidf_(acc[a][b][8 * i + 1]));
;             o.y = pk2(sigmoidf_(acc[a][b][8 * i + 2]), sigmoidf_(acc[a][b][8 * i + 3]));
;             o.z = pk2(sigmoidf_(acc[a][b][8 * i + 4]), sigmoidf_(acc[a][b][8 * i + 5]));
;             o.w = pk2(sigmoidf_(acc[a][b][8 * i + 6]), sigmoidf_(acc[a][b][8 * i + 7]));
;             scr[((a * 2 + b) * 2 + i) * 256] = o;
	v_rcp_f32_e32 v21, v19
	s_nop 0
	v_fma_f32 v34, -v19, v21, 1.0
	v_fmac_f32_e32 v21, v34, v21
	v_div_scale_f32 v34, vcc, 1.0, v20, 1.0
	v_mul_f32_e32 v35, v34, v21
	v_fma_f32 v36, -v19, v35, v34
	v_fmac_f32_e32 v35, v36, v21
	v_fma_f32 v19, -v19, v35, v34
	v_div_fmas_f32 v19, v19, v21, v35
	v_div_fixup_f32 v19, v19, v20, 1.0
	v_cvt_pk_f16_f32 v19, v19, v0
	v_mul_f32_e32 v0, 0xbfb8aa3b, v22
	v_exp_f32_e32 v20, v0
	v_mul_f32_e32 v0, 0xbfb8aa3b, v23
	v_exp_f32_e32 v21, v0
	s_nop 0
	v_pk_add_f32 v[20:21], v[20:21], 1.0 op_sel_hi:[1,0]
	s_nop 0
	v_div_scale_f32 v0, s[8:9], v21, v21, 1.0
	v_rcp_f32_e32 v22, v0
	s_nop 0
	v_fma_f32 v23, -v0, v22, 1.0
	v_fmac_f32_e32 v22, v23, v22
	v_div_scale_f32 v23, vcc, 1.0, v21, 1.0
	v_mul_f32_e32 v34, v23, v22
	v_fma_f32 v35, -v0, v34, v23
	v_fmac_f32_e32 v34, v35, v22
	v_fma_f32 v0, -v0, v34, v23
	v_div_fmas_f32 v0, v0, v22, v34
	v_div_fixup_f32 v0, v0, v21, 1.0
	v_div_scale_f32 v21, s[8:9], v20, v20, 1.0
	v_rcp_f32_e32 v22, v21
	s_nop 0
	v_fma_f32 v23, -v21, v22, 1.0
	v_fmac_f32_e32 v22, v23, v22
	v_div_scale_f32 v23, vcc, 1.0, v20, 1.0
	v_mul_f32_e32 v34, v23, v22
	v_fma_f32 v35, -v21, v34, v23
	v_fmac_f32_e32 v34, v35, v22
	v_fma_f32 v21, -v21, v34, v23
	v_div_fmas_f32 v21, v21, v22, v34
	v_div_fixup_f32 v20, v21, v20, 1.0
	v_cvt_pk_f16_f32 v20, v20, v0
	v_mul_f32_e32 v0, 0xbfb8aa3b, v24
	v_exp_f32_e32 v22, v0
	v_mul_f32_e32 v0, 0xbfb8aa3b, v25
	v_exp_f32_e32 v23, v0
	s_nop 0
	v_pk_add_f32 v[22:23], v[22:23], 1.0 op_sel_hi:[1,0]
	s_nop 0
	v_div_scale_f32 v0, s[8:9], v23, v23, 1.0
	v_rcp_f32_e32 v21, v0
	s_nop 0
	v_fma_f32 v24, -v0, v21, 1.0
	v_fmac_f32_e32 v21, v24, v21
	v_div_scale_f32 v24, vcc, 1.0, v23, 1.0
	v_mul_f32_e32 v25, v24, v21
	v_fma_f32 v34, -v0, v25, v24
	v_fmac_f32_e32 v25, v34, v21
	v_fma_f32 v0, -v0, v25, v24
	v_div_fmas_f32 v0, v0, v21, v25
	v_div_scale_f32 v21, s[8:9], v22, v22, 1.0
	v_div_fixup_f32 v0, v0, v23, 1.0
	v_rcp_f32_e32 v23, v21
	s_nop 0
	v_fma_f32 v24, -v21, v23, 1.0
	v_fmac_f32_e32 v23, v24, v23
	v_div_scale_f32 v24, vcc, 1.0, v22, 1.0
	v_mul_f32_e32 v25, v24, v23
	v_fma_f32 v34, -v21, v25, v24
	v_fmac_f32_e32 v25, v34, v23
	v_fma_f32 v21, -v21, v25, v24
	v_div_fmas_f32 v21, v21, v23, v25
	v_div_fixup_f32 v21, v21, v22, 1.0
	v_cvt_pk_f16_f32 v21, v21, v0
	v_mul_f32_e32 v0, 0xbfb8aa3b, v26
	global_store_dwordx4 v[76:77], v[18:21], off
	s_nop 1
	v_exp_f32_e32 v18, v0
	v_mul_f32_e32 v0, 0xbfb8aa3b, v27
	v_exp_f32_e32 v19, v0
	s_nop 0
	v_pk_add_f32 v[18:19], v[18:19], 1.0 op_sel_hi:[1,0]
	s_nop 0
	v_div_scale_f32 v0, s[8:9], v19, v19, 1.0
	v_rcp_f32_e32 v20, v0
	s_nop 0
	v_fma_f32 v21, -v0, v20, 1.0
	v_fmac_f32_e32 v20, v21, v20
	v_div_scale_f32 v21, vcc, 1.0, v19, 1.0
	v_mul_f32_e32 v22, v21, v20
	v_fma_f32 v23, -v0, v22, v21
	v_fmac_f32_e32 v22, v23, v20
	v_fma_f32 v0, -v0, v22, v21
	v_div_fmas_f32 v0, v0, v20, v22
	v_div_fixup_f32 v0, v0, v19, 1.0
	v_div_scale_f32 v19, s[8:9], v18, v18, 1.0
	v_rcp_f32_e32 v20, v19
	s_nop 0
	v_fma_f32 v21, -v19, v20, 1.0
	v_fmac_f32_e32 v20, v21, v20
	v_div_scale_f32 v21, vcc, 1.0, v18, 1.0
	v_mul_f32_e32 v22, v21, v20
	v_fma_f32 v23, -v19, v22, v21
	v_fmac_f32_e32 v22, v23, v20
	v_fma_f32 v19, -v19, v22, v21
	v_div_fmas_f32 v19, v19, v20, v22
	v_div_fixup_f32 v18, v19, v18, 1.0
	v_cvt_pk_f16_f32 v18, v18, v0
	v_mul_f32_e32 v0, 0xbfb8aa3b, v28
	v_exp_f32_e32 v20, v0
	v_mul_f32_e32 v0, 0xbfb8aa3b, v29
	v_exp_f32_e32 v21, v0
	s_nop 0
	v_pk_add_f32 v[20:21], v[20:21], 1.0 op_sel_hi:[1,0]
	s_nop 0
	v_div_scale_f32 v0, s[8:9], v21, v21, 1.0
	v_rcp_f32_e32 v19, v0
	s_nop 0
	v_fma_f32 v22, -v0, v19, 1.0
	v_fmac_f32_e32 v19, v22, v19
	v_div_scale_f32 v22, vcc, 1.0, v21, 1.0
	v_mul_f32_e32 v23, v22, v19
	v_fma_f32 v24, -v0, v23, v22
	v_fmac_f32_e32 v23, v24, v19
	v_fma_f32 v0, -v0, v23, v22
	v_div_fmas_f32 v0, v0, v19, v23
	v_div_scale_f32 v19, s[8:9], v20, v20, 1.0
	v_div_fixup_f32 v0, v0, v21, 1.0
	v_rcp_f32_e32 v21, v19
	s_nop 0
	v_fma_f32 v22, -v19, v21, 1.0
	v_fmac_f32_e32 v21, v22, v21
	v_div_scale_f32 v22, vcc, 1.0, v20, 1.0
	v_mul_f32_e32 v23, v22, v21
	v_fma_f32 v24, -v19, v23, v22
	v_fmac_f32_e32 v23, v24, v21
	v_fma_f32 v19, -v19, v23, v22
	v_div_fmas_f32 v19, v19, v21, v23
	v_div_fixup_f32 v19, v19, v20, 1.0
	v_cvt_pk_f16_f32 v19, v19, v0
	v_mul_f32_e32 v0, 0xbfb8aa3b, v30
	v_exp_f32_e32 v20, v0
	v_mul_f32_e32 v0, 0xbfb8aa3b, v31
	v_exp_f32_e32 v21, v0
	s_nop 0
	v_pk_add_f32 v[20:21], v[20:21], 1.0 op_sel_hi:[1,0]
	s_nop 0
	v_div_scale_f32 v0, s[8:9], v21, v21, 1.0
	v_rcp_f32_e32 v22, v0
	s_nop 0
	v_fma_f32 v23, -v0, v22, 1.0
	v_fmac_f32_e32 v22, v23, v22
	v_div_scale_f32 v23, vcc, 1.0, v21, 1.0
	v_mul_f32_e32 v24, v23, v22
	v_fma_f32 v25, -v0, v24, v23
	v_fmac_f32_e32 v24, v25, v22
	v_fma_f32 v0, -v0, v24, v23
	v_div_fmas_f32 v0, v0, v22, v24
	v_div_fixup_f32 v0, v0, v21, 1.0
	v_div_scale_f32 v21, s[8:9], v20, v20, 1.0
	v_rcp_f32_e32 v22, v21
	s_nop 0
	v_fma_f32 v23, -v21, v22, 1.0
	v_fmac_f32_e32 v22, v23, v22
	v_div_scale_f32 v23, vcc, 1.0, v20, 1.0
	v_mul_f32_e32 v24, v23, v22
	v_fma_f32 v25, -v21, v24, v23
	v_fmac_f32_e32 v24, v25, v22
	v_fma_f32 v21, -v21, v24, v23
	v_div_fmas_f32 v21, v21, v22, v24
	v_div_fixup_f32 v20, v21, v20, 1.0
	v_cvt_pk_f16_f32 v20, v20, v0
	v_mul_f32_e32 v0, 0xbfb8aa3b, v32
	v_exp_f32_e32 v22, v0
	v_mul_f32_e32 v0, 0xbfb8aa3b, v33
	v_exp_f32_e32 v23, v0
	s_nop 0
	v_pk_add_f32 v[22:23], v[22:23], 1.0 op_sel_hi:[1,0]
	s_nop 0
	v_div_scale_f32 v0, s[8:9], v23, v23, 1.0
	v_rcp_f32_e32 v21, v0
	s_nop 0
	v_fma_f32 v24, -v0, v21, 1.0
	v_fmac_f32_e32 v21, v24, v21
	v_div_scale_f32 v24, vcc, 1.0, v23, 1.0
	v_mul_f32_e32 v25, v24, v21
	v_fma_f32 v26, -v0, v25, v24
	v_fmac_f32_e32 v25, v26, v21
	v_fma_f32 v0, -v0, v25, v24
; DI unsigned pk2(float a, float b) { f2_t v = {a, b}; bf2_t r = __builtin_convertvector(v, bf2_t); return __builtin_bit_cast(unsigned, r); }
; DI float sigmoidf_(float x) { return 1.f / (1.f + __expf(-x)); }
; DI void phase4(const Params& p, int l, char* lds) {
;     ...
;           for (int i = 0; i < 2; ++i) {
;             uint4 o;
;             o.x = pk2(sigmoidf_(acc[a][b][8 * i]), sigmoidf_(acc[a][b][8 * i + 1]));
;             o.y = pk2(sigmoidf_(acc[a][b][8 * i + 2]), sigmoidf_(acc[a][b][8 * i + 3]));
;             o.z = pk2(sigmoidf_(acc[a][b][8 * i + 4]), sigmoidf_(acc[a][b][8 * i + 5]));
;             o.w = pk2(sigmoidf_(acc[a][b][8 * i + 6]), sigmoidf_(acc[a][b][8 * i + 7]));
;             scr[((a * 2 + b) * 2 + i) * 256] = o;
	v_div_fmas_f32 v0, v0, v21, v25
	v_div_scale_f32 v21, s[8:9], v22, v22, 1.0
	v_div_fixup_f32 v0, v0, v23, 1.0
	v_rcp_f32_e32 v23, v21
	s_nop 0
	v_fma_f32 v24, -v21, v23, 1.0
	v_fmac_f32_e32 v23, v24, v23
	v_div_scale_f32 v24, vcc, 1.0, v22, 1.0
	v_mul_f32_e32 v25, v24, v23
	v_fma_f32 v26, -v21, v25, v24
	v_fmac_f32_e32 v25, v26, v23
	v_fma_f32 v21, -v21, v25, v24
	v_div_fmas_f32 v21, v21, v23, v25
	v_div_fixup_f32 v21, v21, v22, 1.0
	v_cvt_pk_f16_f32 v21, v21, v0
	v_mul_f32_e32 v0, 0xbfb8aa3b, v2
	v_exp_f32_e32 v2, v0
	v_mul_f32_e32 v0, 0xbfb8aa3b, v3
	v_exp_f32_e32 v3, v0
	global_store_dwordx4 v[78:79], v[18:21], off
	v_pk_add_f32 v[2:3], v[2:3], 1.0 op_sel_hi:[1,0]
	s_nop 0
	v_div_scale_f32 v0, s[8:9], v3, v3, 1.0
	v_rcp_f32_e32 v18, v0
	s_nop 0
	v_fma_f32 v19, -v0, v18, 1.0
	v_fmac_f32_e32 v18, v19, v18
	v_div_scale_f32 v19, vcc, 1.0, v3, 1.0
	v_mul_f32_e32 v20, v19, v18
	v_fma_f32 v21, -v0, v20, v19
	v_fmac_f32_e32 v20, v21, v18
	v_fma_f32 v0, -v0, v20, v19
	v_div_fmas_f32 v0, v0, v18, v20
	v_div_fixup_f32 v0, v0, v3, 1.0
	v_div_scale_f32 v3, s[8:9], v2, v2, 1.0
	v_rcp_f32_e32 v18, v3
	s_nop 0
	v_fma_f32 v19, -v3, v18, 1.0
	v_fmac_f32_e32 v18, v19, v18
	v_div_scale_f32 v19, vcc, 1.0, v2, 1.0
	v_mul_f32_e32 v20, v19, v18
	v_fma_f32 v21, -v3, v20, v19
	v_fmac_f32_e32 v20, v21, v18
	v_fma_f32 v3, -v3, v20, v19
	v_div_fmas_f32 v3, v3, v18, v20
	v_div_fixup_f32 v2, v3, v2, 1.0
	v_cvt_pk_f16_f32 v2, v2, v0
	v_mul_f32_e32 v0, 0xbfb8aa3b, v4
	v_exp_f32_e32 v4, v0
	v_mul_f32_e32 v0, 0xbfb8aa3b, v5
	v_exp_f32_e32 v5, v0
	s_nop 0
	v_pk_add_f32 v[4:5], v[4:5], 1.0 op_sel_hi:[1,0]
	s_nop 0
	v_div_scale_f32 v0, s[8:9], v5, v5, 1.0
	v_rcp_f32_e32 v3, v0
	s_nop 0
	v_fma_f32 v18, -v0, v3, 1.0
	v_fmac_f32_e32 v3, v18, v3
	v_div_scale_f32 v18, vcc, 1.0, v5, 1.0
	v_mul_f32_e32 v19, v18, v3
	v_fma_f32 v20, -v0, v19, v18
	v_fmac_f32_e32 v19, v20, v3
	v_fma_f32 v0, -v0, v19, v18
	v_div_fmas_f32 v0, v0, v3, v19
	v_div_scale_f32 v3, s[8:9], v4, v4, 1.0
	v_div_fixup_f32 v0, v0, v5, 1.0
	v_rcp_f32_e32 v5, v3
	s_nop 0
	v_fma_f32 v18, -v3, v5, 1.0
	v_fmac_f32_e32 v5, v18, v5
	v_div_scale_f32 v18, vcc, 1.0, v4, 1.0
	v_mul_f32_e32 v19, v18, v5
	v_fma_f32 v20, -v3, v19, v18
	v_fmac_f32_e32 v19, v20, v5
	v_fma_f32 v3, -v3, v19, v18
	v_div_fmas_f32 v3, v3, v5, v19
	v_div_fixup_f32 v3, v3, v4, 1.0
	v_cvt_pk_f16_f32 v3, v3, v0
	v_mul_f32_e32 v0, 0xbfb8aa3b, v6
	v_exp_f32_e32 v4, v0
	v_mul_f32_e32 v0, 0xbfb8aa3b, v7
	v_exp_f32_e32 v5, v0
	s_nop 0
	v_pk_add_f32 v[4:5], v[4:5], 1.0 op_sel_hi:[1,0]
	s_nop 0
	v_div_scale_f32 v0, s[8:9], v5, v5, 1.0
	v_rcp_f32_e32 v6, v0
	s_nop 0
	v_fma_f32 v7, -v0, v6, 1.0
	v_fmac_f32_e32 v6, v7, v6
	v_div_scale_f32 v7, vcc, 1.0, v5, 1.0
	v_mul_f32_e32 v18, v7, v6
	v_fma_f32 v19, -v0, v18, v7
	v_fmac_f32_e32 v18, v19, v6
	v_fma_f32 v0, -v0, v18, v7
	v_div_fmas_f32 v0, v0, v6, v18
	v_div_fixup_f32 v0, v0, v5, 1.0
	v_div_scale_f32 v5, s[8:9], v4, v4, 1.0
	v_rcp_f32_e32 v6, v5
	s_nop 0
	v_fma_f32 v7, -v5, v6, 1.0
	v_fmac_f32_e32 v6, v7, v6
	v_div_scale_f32 v7, vcc, 1.0, v4, 1.0
	v_mul_f32_e32 v18, v7, v6
	v_fma_f32 v19, -v5, v18, v7
	v_fmac_f32_e32 v18, v19, v6
	v_fma_f32 v5, -v5, v18, v7
	v_div_fmas_f32 v5, v5, v6, v18
	v_div_fixup_f32 v4, v5, v4, 1.0
	v_cvt_pk_f16_f32 v4, v4, v0
	v_mul_f32_e32 v0, 0xbfb8aa3b, v8
	v_exp_f32_e32 v6, v0
	v_mul_f32_e32 v0, 0xbfb8aa3b, v9
	v_exp_f32_e32 v7, v0
	s_nop 0
	v_pk_add_f32 v[6:7], v[6:7], 1.0 op_sel_hi:[1,0]
	s_nop 0
	v_div_scale_f32 v0, s[8:9], v7, v7, 1.0
	v_rcp_f32_e32 v5, v0
	s_nop 0
	v_fma_f32 v8, -v0, v5, 1.0
	v_fmac_f32_e32 v5, v8, v5
	v_div_scale_f32 v8, vcc, 1.0, v7, 1.0
	v_mul_f32_e32 v9, v8, v5
	v_fma_f32 v18, -v0, v9, v8
	v_fmac_f32_e32 v9, v18, v5
	v_fma_f32 v0, -v0, v9, v8
	v_div_fmas_f32 v0, v0, v5, v9
	v_div_scale_f32 v5, s[8:9], v6, v6, 1.0
	v_div_fixup_f32 v0, v0, v7, 1.0
	v_rcp_f32_e32 v7, v5
	s_nop 0
	v_fma_f32 v8, -v5, v7, 1.0
	v_fmac_f32_e32 v7, v8, v7
	v_div_scale_f32 v8, vcc, 1.0, v6, 1.0
	v_mul_f32_e32 v9, v8, v7
	v_fma_f32 v18, -v5, v9, v8
	v_fmac_f32_e32 v9, v18, v7
; DI unsigned pk2(float a, float b) { f2_t v = {a, b}; bf2_t r = __builtin_convertvector(v, bf2_t); return __builtin_bit_cast(unsigned, r); }
; DI float sigmoidf_(float x) { return 1.f / (1.f + __expf(-x)); }
; DI void phase4(const Params& p, int l, char* lds) {
;     ...
;           for (int i = 0; i < 2; ++i) {
;             uint4 o;
;             o.x = pk2(sigmoidf_(acc[a][b][8 * i]), sigmoidf_(acc[a][b][8 * i + 1]));
;             o.y = pk2(sigmoidf_(acc[a][b][8 * i + 2]), sigmoidf_(acc[a][b][8 * i + 3]));
;             o.z = pk2(sigmoidf_(acc[a][b][8 * i + 4]), sigmoidf_(acc[a][b][8 * i + 5]));
;             o.w = pk2(sigmoidf_(acc[a][b][8 * i + 6]), sigmoidf_(acc[a][b][8 * i + 7]));
;             scr[((a * 2 + b) * 2 + i) * 256] = o;
;           }
;       zero_acc(acc);
;       const int yoff = (n == 0) ? GA : ((n == 1) ? GB : ((n == 2) ? GC : GD));
	v_fma_f32 v5, -v5, v9, v8
	v_div_fmas_f32 v5, v5, v7, v9
	v_div_fixup_f32 v5, v5, v6, 1.0
	v_cvt_pk_f16_f32 v5, v5, v0
	v_mul_f32_e32 v0, 0xbfb8aa3b, v10
	global_store_dwordx4 v[80:81], v[2:5], off
	s_nop 1
	v_exp_f32_e32 v2, v0
	v_mul_f32_e32 v0, 0xbfb8aa3b, v11
	v_exp_f32_e32 v3, v0
	s_nop 0
	v_pk_add_f32 v[2:3], v[2:3], 1.0 op_sel_hi:[1,0]
	s_nop 0
	v_div_scale_f32 v0, s[8:9], v3, v3, 1.0
	v_rcp_f32_e32 v4, v0
	s_nop 0
	v_fma_f32 v5, -v0, v4, 1.0
	v_fmac_f32_e32 v4, v5, v4
	v_div_scale_f32 v5, vcc, 1.0, v3, 1.0
	v_mul_f32_e32 v6, v5, v4
	v_fma_f32 v7, -v0, v6, v5
	v_fmac_f32_e32 v6, v7, v4
	v_fma_f32 v0, -v0, v6, v5
	v_div_fmas_f32 v0, v0, v4, v6
	v_div_fixup_f32 v0, v0, v3, 1.0
	v_div_scale_f32 v3, s[8:9], v2, v2, 1.0
	v_rcp_f32_e32 v4, v3
	s_nop 0
	v_fma_f32 v5, -v3, v4, 1.0
	v_fmac_f32_e32 v4, v5, v4
	v_div_scale_f32 v5, vcc, 1.0, v2, 1.0
	v_mul_f32_e32 v6, v5, v4
	v_fma_f32 v7, -v3, v6, v5
	v_fmac_f32_e32 v6, v7, v4
	v_fma_f32 v3, -v3, v6, v5
	v_div_fmas_f32 v3, v3, v4, v6
	v_div_fixup_f32 v2, v3, v2, 1.0
	v_cvt_pk_f16_f32 v2, v2, v0
	v_mul_f32_e32 v0, 0xbfb8aa3b, v12
	v_exp_f32_e32 v4, v0
	v_mul_f32_e32 v0, 0xbfb8aa3b, v13
	v_exp_f32_e32 v5, v0
	s_nop 0
	v_pk_add_f32 v[4:5], v[4:5], 1.0 op_sel_hi:[1,0]
	s_nop 0
	v_div_scale_f32 v0, s[8:9], v5, v5, 1.0
	v_rcp_f32_e32 v3, v0
	s_nop 0
	v_fma_f32 v6, -v0, v3, 1.0
	v_fmac_f32_e32 v3, v6, v3
	v_div_scale_f32 v6, vcc, 1.0, v5, 1.0
	v_mul_f32_e32 v7, v6, v3
	v_fma_f32 v8, -v0, v7, v6
	v_fmac_f32_e32 v7, v8, v3
	v_fma_f32 v0, -v0, v7, v6
	v_div_fmas_f32 v0, v0, v3, v7
	v_div_scale_f32 v3, s[8:9], v4, v4, 1.0
	v_div_fixup_f32 v0, v0, v5, 1.0
	v_rcp_f32_e32 v5, v3
	s_nop 0
	v_fma_f32 v6, -v3, v5, 1.0
	v_fmac_f32_e32 v5, v6, v5
	v_div_scale_f32 v6, vcc, 1.0, v4, 1.0
	v_mul_f32_e32 v7, v6, v5
	v_fma_f32 v8, -v3, v7, v6
	v_fmac_f32_e32 v7, v8, v5
	v_fma_f32 v3, -v3, v7, v6
	v_div_fmas_f32 v3, v3, v5, v7
	v_div_fixup_f32 v3, v3, v4, 1.0
	v_cvt_pk_f16_f32 v3, v3, v0
	v_mul_f32_e32 v0, 0xbfb8aa3b, v14
	v_exp_f32_e32 v4, v0
	v_mul_f32_e32 v0, 0xbfb8aa3b, v15
	v_exp_f32_e32 v5, v0
	s_nop 0
	v_pk_add_f32 v[4:5], v[4:5], 1.0 op_sel_hi:[1,0]
	s_nop 0
	v_div_scale_f32 v0, s[8:9], v5, v5, 1.0
	v_rcp_f32_e32 v6, v0
	s_nop 0
	v_fma_f32 v7, -v0, v6, 1.0
	v_fmac_f32_e32 v6, v7, v6
	v_div_scale_f32 v7, vcc, 1.0, v5, 1.0
	v_mul_f32_e32 v8, v7, v6
	v_fma_f32 v9, -v0, v8, v7
	v_fmac_f32_e32 v8, v9, v6
	v_fma_f32 v0, -v0, v8, v7
	v_div_fmas_f32 v0, v0, v6, v8
	v_div_fixup_f32 v0, v0, v5, 1.0
	v_div_scale_f32 v5, s[8:9], v4, v4, 1.0
	v_rcp_f32_e32 v6, v5
	s_nop 0
	v_fma_f32 v7, -v5, v6, 1.0
	v_fmac_f32_e32 v6, v7, v6
	v_div_scale_f32 v7, vcc, 1.0, v4, 1.0
	v_mul_f32_e32 v8, v7, v6
	v_fma_f32 v9, -v5, v8, v7
	v_fmac_f32_e32 v8, v9, v6
	v_fma_f32 v5, -v5, v8, v7
	v_div_fmas_f32 v5, v5, v6, v8
	v_div_fixup_f32 v4, v5, v4, 1.0
	v_cvt_pk_f16_f32 v4, v4, v0
	v_mul_f32_e32 v0, 0xbfb8aa3b, v16
	v_exp_f32_e32 v6, v0
	v_mul_f32_e32 v0, 0xbfb8aa3b, v17
	v_exp_f32_e32 v7, v0
	s_nop 0
	v_pk_add_f32 v[6:7], v[6:7], 1.0 op_sel_hi:[1,0]
	s_nop 0
	v_div_scale_f32 v0, s[8:9], v7, v7, 1.0
	v_rcp_f32_e32 v5, v0
	s_nop 0
	v_fma_f32 v8, -v0, v5, 1.0
	v_fmac_f32_e32 v5, v8, v5
	v_div_scale_f32 v8, vcc, 1.0, v7, 1.0
	v_mul_f32_e32 v9, v8, v5
	v_fma_f32 v10, -v0, v9, v8
	v_fmac_f32_e32 v9, v10, v5
	v_fma_f32 v0, -v0, v9, v8
	v_div_fmas_f32 v0, v0, v5, v9
	v_div_scale_f32 v5, s[8:9], v6, v6, 1.0
	v_div_fixup_f32 v0, v0, v7, 1.0
	v_rcp_f32_e32 v7, v5
	s_mov_b64 s[8:9], 0x600
	v_fma_f32 v8, -v5, v7, 1.0
	v_fmac_f32_e32 v7, v8, v7
	v_div_scale_f32 v8, vcc, 1.0, v6, 1.0
	v_mul_f32_e32 v9, v8, v7
	v_fma_f32 v10, -v5, v9, v8
	v_fmac_f32_e32 v9, v10, v7
	v_fma_f32 v5, -v5, v9, v8
	v_div_fmas_f32 v5, v5, v7, v9
	v_div_fixup_f32 v5, v5, v6, 1.0
	v_cvt_pk_f16_f32 v5, v5, v0
	global_store_dwordx4 v[82:83], v[2:5], off
	s_cbranch_scc1 .LBB0_1054
	s_cmp_eq_u32 s22, 1
	s_mov_b64 s[10:11], -1
	s_cbranch_scc1 .LBB0_1058
	s_cmp_eq_u32 s6, 0x400000
	s_movk_i32 s8, 0x1100
	s_mov_b32 s9, s23
	s_cselect_b32 s8, s8, 0x1700
	s_mov_b64 s[10:11], 0
